# on top of v12: EpiRes issues all 16 residual loads before its first wait (G2, G4); row-sum lane^16 exchange via v_permlane16_swap instead of ds_swizzle + LDS wait (24 sites)
# baseline (speedup 1.0000x reference)
; #define PG8_LAS __attribute__((address_space(3)))
; __device__ __forceinline__ unsigned cvt_pk_bf16(float lo, float hi) { return __builtin_bit_cast(unsigned, __builtin_convertvector((f32x2_t){lo, hi}, bf16x2_t)); }
; __device__ __forceinline__ float bf_lo(unsigned w) { return __uint_as_float(w << 16); }
; __device__ __forceinline__ float bf_hi(unsigned w) { return __uint_as_float(w & 0xffff0000u); }
; __device__ __forceinline__ float sum_xor16(float v) { return v + swz_f<0x401F>(v); }
; __device__ __forceinline__ float sum_xor32(float v) { const auto r = __builtin_amdgcn_permlane32_swap(__float_as_uint(v), __float_as_uint(v), false, false); return __uint_as_float(r[0]) + __uint_as_float(r[1]); }
;     __device__ __forceinline__ void operator()(const f32x4 (&acc)[2][2][4][2], const Unit& u, int wr, int wc, int fr, int fq, PG8_LAS unsigned char*, int) const {
;         const int row0 = u.pm * BM + wr * 64 + fr, col0 = u.pn * BM + wc * 32 + 8 * fq;
;         bf16_t* const base = HB + (size_t)row0 * 2048 + col0;
;         u32x4 old[2][4][2];
; #pragma unroll
;         for (int ai = 0; ai < 2; ++ai)
; #pragma unroll
;             for (int m = 0; m < 4; ++m)
; #pragma unroll
;                 for (int bj = 0; bj < 2; ++bj) old[ai][m][bj] = *(const u32x4*)(base + (size_t)(ai * HALF + m * 16) * 2048 + bj * HALF);
; #pragma unroll
;         for (int ai = 0; ai < 2; ++ai)
; #pragma unroll
;             for (int m = 0; m < 4; ++m) { const int row = row0 + ai * HALF + m * 16; float q = 0.f;
; #pragma unroll
;                 for (int bj = 0; bj < 2; ++bj) { const u32x4 o = old[ai][m][bj]; const f32x4 a0 = acc[ai][bj][m][0], a1 = acc[ai][bj][m][1];
;                     const float h0 = bf_lo(o.x) + a0[0], h1 = bf_hi(o.x) + a0[1], h2 = bf_lo(o.y) + a0[2], h3 = bf_hi(o.y) + a0[3], h4 = bf_lo(o.z) + a1[0], h5 = bf_hi(o.z) + a1[1], h6 = bf_lo(o.w) + a1[2], h7 = bf_hi(o.w) + a1[3];
;                     u32x4 w; w.x = cvt_pk_bf16(h0, h1); w.y = cvt_pk_bf16(h2, h3); w.z = cvt_pk_bf16(h4, h5); w.w = cvt_pk_bf16(h6, h7);
;                     *(u32x4*)(base + (size_t)(ai * HALF + m * 16) * 2048 + bj * HALF) = w;
;                     q += (h0 * h0 + h1 * h1) + (h2 * h2 + h3 * h3) + (h4 * h4 + h5 * h5) + (h6 * h6 + h7 * h7); }
;                 q = sum_xor32(sum_xor16(q));
;                 if (fq == 0) SSo[(size_t)row * 32 + u.pn * 4 + wc] = q; }
.LBB0_527:
	v_lshl_add_u32 v216, s20, 8, v1
	v_ashrrev_i32_e32 v217, 31, v216
	v_lshl_add_u32 v118, s26, 8, v220
	v_lshlrev_b64 v[120:121], 12, v[216:217]
	v_lshl_add_u64 v[120:121], s[4:5], 0, v[120:121]
	v_ashrrev_i32_e32 v119, 31, v118
	v_lshl_add_u64 v[214:215], v[118:119], 1, v[120:121]
	global_load_dwordx4 v[226:229], v[214:215], off
	global_load_dwordx4 v[186:189], v[214:215], off offset:256
	v_add_co_u32_e32 v118, vcc, s23, v214
	s_mov_b32 s13, 0x80000
	s_nop 0
	v_addc_co_u32_e32 v119, vcc, 0, v215, vcc
	global_load_dwordx4 v[182:185], v[118:119], off
	global_load_dwordx4 v[178:181], v[118:119], off offset:256
	v_add_co_u32_e32 v118, vcc, s0, v214
	s_lshl_b32 s20, s26, 2
	s_nop 0
	v_addc_co_u32_e32 v119, vcc, 0, v215, vcc
	global_load_dwordx4 v[174:177], v[118:119], off
	global_load_dwordx4 v[170:173], v[118:119], off offset:256
	v_add_co_u32_e32 v118, vcc, s1, v214
	s_ashr_i32 s21, s20, 31
	s_nop 0
	v_addc_co_u32_e32 v119, vcc, 0, v215, vcc
	global_load_dwordx4 v[166:169], v[118:119], off
	global_load_dwordx4 v[162:165], v[118:119], off offset:256
	v_add_co_u32_e32 v118, vcc, s13, v214
	s_nop 1
	v_addc_co_u32_e32 v119, vcc, 0, v215, vcc
	global_load_dwordx4 v[158:161], v[118:119], off
	global_load_dwordx4 v[154:157], v[118:119], off offset:256
	v_add_co_u32_e32 v118, vcc, s50, v214
	s_nop 0
	s_nop 0
	v_addc_co_u32_e32 v119, vcc, 0, v215, vcc
	global_load_dwordx4 v[150:153], v[118:119], off
	global_load_dwordx4 v[146:149], v[118:119], off offset:256
	v_add_co_u32_e32 v118, vcc, s51, v214
	s_nop 0
	s_nop 0
	v_addc_co_u32_e32 v119, vcc, 0, v215, vcc
	global_load_dwordx4 v[134:137], v[118:119], off
	global_load_dwordx4 v[130:133], v[118:119], off offset:256
	v_add_co_u32_e32 v118, vcc, s82, v214
	s_nop 0
	s_nop 0
	v_addc_co_u32_e32 v119, vcc, 0, v215, vcc
	global_load_dwordx4 v[122:125], v[118:119], off
	s_nop 0
	global_load_dwordx4 v[118:121], v[118:119], off offset:256
	s_waitcnt vmcnt(0)
	v_lshlrev_b32_e32 v230, 16, v226
	v_and_b32_e32 v231, 0xffff0000, v226
	v_lshlrev_b32_e32 v226, 16, v227
	v_and_b32_e32 v227, 0xffff0000, v227
	v_pk_add_f32 v[144:145], v[144:145], v[226:227]
	v_lshlrev_b32_e32 v226, 16, v228
	v_and_b32_e32 v227, 0xffff0000, v228
	v_pk_add_f32 v[226:227], v[138:139], v[226:227]
	v_lshlrev_b32_e32 v138, 16, v229
	v_and_b32_e32 v139, 0xffff0000, v229
	v_pk_add_f32 v[142:143], v[142:143], v[230:231]
	v_pk_add_f32 v[228:229], v[140:141], v[138:139]
	v_cvt_pk_bf16_f32 v138, v142, v143
	v_cvt_pk_bf16_f32 v139, v144, v145
	v_cvt_pk_bf16_f32 v140, v226, v227
	v_cvt_pk_bf16_f32 v141, v228, v229
	global_store_dwordx4 v[214:215], v[138:141], off
	s_nop 1
	v_pk_mul_f32 v[138:139], v[142:143], v[142:143]
	v_pk_mul_f32 v[142:143], v[226:227], v[226:227]
	v_lshlrev_b32_e32 v226, 16, v186
	v_and_b32_e32 v227, 0xffff0000, v186
	v_lshlrev_b32_e32 v186, 16, v187
	v_and_b32_e32 v187, 0xffff0000, v187
	v_pk_add_f32 v[128:129], v[128:129], v[186:187]
	v_lshlrev_b32_e32 v186, 16, v188
	v_and_b32_e32 v187, 0xffff0000, v188
	v_pk_add_f32 v[186:187], v[114:115], v[186:187]
	v_lshlrev_b32_e32 v114, 16, v189
	v_and_b32_e32 v115, 0xffff0000, v189
	v_pk_add_f32 v[126:127], v[126:127], v[226:227]
	v_pk_add_f32 v[188:189], v[116:117], v[114:115]
	v_cvt_pk_bf16_f32 v114, v126, v127
	v_cvt_pk_bf16_f32 v115, v128, v129
	v_cvt_pk_bf16_f32 v116, v186, v187
	v_cvt_pk_bf16_f32 v117, v188, v189
	global_store_dwordx4 v[214:215], v[114:117], off offset:256
	v_pk_mul_f32 v[140:141], v[144:145], v[144:145]
	v_pk_mul_f32 v[144:145], v[228:229], v[228:229]
	v_pk_mul_f32 v[114:115], v[126:127], v[126:127]
	v_pk_mul_f32 v[116:117], v[128:129], v[128:129]
	v_add_f32_e32 v114, v114, v115
	v_add_f32_e32 v116, v116, v117
	v_pk_mul_f32 v[126:127], v[186:187], v[186:187]
	v_add_f32_e32 v114, v114, v116
	v_add_f32_e32 v116, v140, v141
	v_add_f32_e32 v117, v138, v139
	v_pk_mul_f32 v[128:129], v[188:189], v[188:189]
	v_add_f32_e32 v115, v126, v127
	v_add_f32_e32 v116, v117, v116
	v_add_f32_e32 v117, v142, v143
	v_add_f32_e32 v128, v128, v129
	v_add_f32_e32 v114, v115, v114
	v_add_f32_e32 v115, v144, v145
	v_add_f32_e32 v116, v117, v116
	v_add_f32_e32 v114, v128, v114
	v_add_f32_e32 v115, v115, v116
	v_add_f32_e32 v114, v115, v114
	v_mov_b32_e32 v115, v114
	s_nop 1
	v_permlane16_swap_b32_e32 v115, v114
	s_waitcnt lgkmcnt(0)
	v_add_f32_e32 v116, v114, v115
	v_mov_b32_e32 v117, v116
	v_lshlrev_b64 v[114:115], 7, v[216:217]
	s_nop 0
	v_permlane32_swap_b32_e32 v116, v117
	v_lshl_add_u64 v[114:115], s[8:9], 0, v[114:115]
	s_and_saveexec_b64 s[40:41], s[36:37]
	s_cbranch_execz .LBB0_529
	v_add_f32_e32 v126, v116, v117
	v_lshl_add_u64 v[116:117], s[20:21], 2, v[114:115]
	s_lshl_b32 s26, s69, 2
	v_lshl_add_u64 v[116:117], v[116:117], 0, s[26:27]
	global_store_dword v[116:117], v126, off
; __device__ __forceinline__ unsigned cvt_pk_bf16(float lo, float hi) { return __builtin_bit_cast(unsigned, __builtin_convertvector((f32x2_t){lo, hi}, bf16x2_t)); }
; __device__ __forceinline__ float bf_lo(unsigned w) { return __uint_as_float(w << 16); }
; __device__ __forceinline__ float bf_hi(unsigned w) { return __uint_as_float(w & 0xffff0000u); }
; __device__ __forceinline__ float sum_xor16(float v) { return v + swz_f<0x401F>(v); }
; __device__ __forceinline__ float sum_xor32(float v) { const auto r = __builtin_amdgcn_permlane32_swap(__float_as_uint(v), __float_as_uint(v), false, false); return __uint_as_float(r[0]) + __uint_as_float(r[1]); }
;     __device__ __forceinline__ void operator()(const f32x4 (&acc)[2][2][4][2], const Unit& u, int wr, int wc, int fr, int fq, PG8_LAS unsigned char*, int) const {
;     ...
;         for (int ai = 0; ai < 2; ++ai)
; #pragma unroll
;             for (int m = 0; m < 4; ++m) { const int row = row0 + ai * HALF + m * 16; float q = 0.f;
; #pragma unroll
;                 for (int bj = 0; bj < 2; ++bj) { const u32x4 o = old[ai][m][bj]; const f32x4 a0 = acc[ai][bj][m][0], a1 = acc[ai][bj][m][1];
;                     const float h0 = bf_lo(o.x) + a0[0], h1 = bf_hi(o.x) + a0[1], h2 = bf_lo(o.y) + a0[2], h3 = bf_hi(o.y) + a0[3], h4 = bf_lo(o.z) + a1[0], h5 = bf_hi(o.z) + a1[1], h6 = bf_lo(o.w) + a1[2], h7 = bf_hi(o.w) + a1[3];
;                     u32x4 w; w.x = cvt_pk_bf16(h0, h1); w.y = cvt_pk_bf16(h2, h3); w.z = cvt_pk_bf16(h4, h5); w.w = cvt_pk_bf16(h6, h7);
;                     *(u32x4*)(base + (size_t)(ai * HALF + m * 16) * 2048 + bj * HALF) = w;
;                     q += (h0 * h0 + h1 * h1) + (h2 * h2 + h3 * h3) + (h4 * h4 + h5 * h5) + (h6 * h6 + h7 * h7); }
;                 q = sum_xor32(sum_xor16(q));
;                 if (fq == 0) SSo[(size_t)row * 32 + u.pn * 4 + wc] = q; }
.LBB0_529:
	s_or_b64 exec, exec, s[40:41]
	v_lshlrev_b32_e32 v128, 16, v182
	v_and_b32_e32 v129, 0xffff0000, v182
	v_pk_add_f32 v[110:111], v[110:111], v[128:129]
	v_lshlrev_b32_e32 v128, 16, v183
	v_and_b32_e32 v129, 0xffff0000, v183
	v_pk_add_f32 v[112:113], v[112:113], v[128:129]
	v_lshlrev_b32_e32 v128, 16, v184
	v_and_b32_e32 v129, 0xffff0000, v184
	v_pk_add_f32 v[128:129], v[106:107], v[128:129]
	v_lshlrev_b32_e32 v106, 16, v185
	v_and_b32_e32 v107, 0xffff0000, v185
	s_mov_b64 s[40:41], 0x10000
	v_pk_add_f32 v[138:139], v[108:109], v[106:107]
	v_lshl_add_u64 v[116:117], v[214:215], 0, s[40:41]
	v_cvt_pk_bf16_f32 v106, v110, v111
	v_cvt_pk_bf16_f32 v107, v112, v113
	v_cvt_pk_bf16_f32 v108, v128, v129
	v_cvt_pk_bf16_f32 v109, v138, v139
	global_store_dwordx4 v[116:117], v[106:109], off
	v_lshlrev_b32_e32 v116, 16, v178
	v_and_b32_e32 v117, 0xffff0000, v178
	v_pk_add_f32 v[102:103], v[102:103], v[116:117]
	v_lshlrev_b32_e32 v116, 16, v179
	v_and_b32_e32 v117, 0xffff0000, v179
	v_pk_add_f32 v[104:105], v[104:105], v[116:117]
	v_lshlrev_b32_e32 v116, 16, v180
	v_and_b32_e32 v117, 0xffff0000, v180
	v_pk_add_f32 v[116:117], v[98:99], v[116:117]
	v_lshlrev_b32_e32 v98, 16, v181
	v_and_b32_e32 v99, 0xffff0000, v181
	v_pk_mul_f32 v[106:107], v[110:111], v[110:111]
	v_pk_mul_f32 v[110:111], v[128:129], v[128:129]
	v_pk_add_f32 v[128:129], v[100:101], v[98:99]
	v_cvt_pk_bf16_f32 v98, v102, v103
	v_pk_mul_f32 v[100:101], v[102:103], v[102:103]
	v_pk_mul_f32 v[102:103], v[104:105], v[104:105]
	v_pk_mul_f32 v[108:109], v[112:113], v[112:113]
	v_pk_mul_f32 v[112:113], v[138:139], v[138:139]
	v_pk_mul_f32 v[138:139], v[116:117], v[116:117]
	v_add_f32_e32 v102, v102, v103
	v_add_f32_e32 v100, v100, v101
	v_add_f32_e32 v100, v100, v102
	v_add_f32_e32 v101, v138, v139
	v_pk_mul_f32 v[140:141], v[128:129], v[128:129]
	v_add_f32_e32 v100, v101, v100
	v_add_f32_e32 v101, v108, v109
	v_add_f32_e32 v102, v106, v107
	v_add_f32_e32 v99, v140, v141
	v_add_f32_e32 v101, v102, v101
	v_add_f32_e32 v102, v110, v111
	v_add_f32_e32 v99, v99, v100
	v_add_f32_e32 v100, v112, v113
	v_add_f32_e32 v101, v102, v101
	v_add_f32_e32 v100, v100, v101
	v_add_f32_e32 v102, v100, v99
	v_mov_b32_e32 v103, v102
	s_nop 1
	v_permlane16_swap_b32_e32 v103, v102
	s_mov_b64 s[40:41], 0x10100
	v_lshl_add_u64 v[126:127], v[214:215], 0, s[40:41]
	v_cvt_pk_bf16_f32 v99, v104, v105
	v_cvt_pk_bf16_f32 v100, v116, v117
	v_cvt_pk_bf16_f32 v101, v128, v129
	global_store_dwordx4 v[126:127], v[98:101], off
	s_waitcnt lgkmcnt(0)
	s_nop 0
	v_add_f32_e32 v98, v102, v103
	v_mov_b32_e32 v99, v98
	s_nop 1
	v_permlane32_swap_b32_e32 v98, v99
	s_and_saveexec_b64 s[40:41], s[36:37]
	s_cbranch_execz .LBB0_531
	v_or_b32_e32 v100, 16, v216
	v_ashrrev_i32_e32 v101, 31, v100
	v_add_f32_e32 v102, v98, v99
	v_lshlrev_b64 v[98:99], 7, v[100:101]
	v_lshl_add_u64 v[98:99], s[8:9], 0, v[98:99]
	v_lshl_add_u64 v[98:99], s[20:21], 2, v[98:99]
	s_lshl_b32 s26, s69, 2
	v_lshl_add_u64 v[98:99], v[98:99], 0, s[26:27]
	global_store_dword v[98:99], v102, off
.LBB0_531:
	s_or_b64 exec, exec, s[40:41]
	v_lshlrev_b32_e32 v102, 16, v174
	v_and_b32_e32 v103, 0xffff0000, v174
	v_pk_add_f32 v[94:95], v[94:95], v[102:103]
	v_lshlrev_b32_e32 v102, 16, v175
	v_and_b32_e32 v103, 0xffff0000, v175
	v_pk_add_f32 v[96:97], v[96:97], v[102:103]
	v_lshlrev_b32_e32 v102, 16, v176
	v_and_b32_e32 v103, 0xffff0000, v176
	v_pk_add_f32 v[102:103], v[90:91], v[102:103]
	v_lshlrev_b32_e32 v90, 16, v177
	v_and_b32_e32 v91, 0xffff0000, v177
	s_mov_b64 s[40:41], 0x20000
	v_pk_add_f32 v[104:105], v[92:93], v[90:91]
	v_lshl_add_u64 v[98:99], v[214:215], 0, s[40:41]
	v_cvt_pk_bf16_f32 v90, v94, v95
	v_cvt_pk_bf16_f32 v91, v96, v97
	v_cvt_pk_bf16_f32 v92, v102, v103
	v_cvt_pk_bf16_f32 v93, v104, v105
	global_store_dwordx4 v[98:99], v[90:93], off
	v_lshlrev_b32_e32 v98, 16, v170
	v_and_b32_e32 v99, 0xffff0000, v170
	v_pk_add_f32 v[86:87], v[86:87], v[98:99]
	v_lshlrev_b32_e32 v98, 16, v171
	v_and_b32_e32 v99, 0xffff0000, v171
	v_pk_add_f32 v[88:89], v[88:89], v[98:99]
	v_lshlrev_b32_e32 v98, 16, v172
	v_and_b32_e32 v99, 0xffff0000, v172
	v_pk_add_f32 v[98:99], v[82:83], v[98:99]
	v_lshlrev_b32_e32 v82, 16, v173
	v_and_b32_e32 v83, 0xffff0000, v173
	v_pk_mul_f32 v[90:91], v[94:95], v[94:95]
	v_pk_mul_f32 v[94:95], v[102:103], v[102:103]
	v_pk_add_f32 v[102:103], v[84:85], v[82:83]
	v_cvt_pk_bf16_f32 v82, v86, v87
	v_pk_mul_f32 v[84:85], v[86:87], v[86:87]
	v_pk_mul_f32 v[86:87], v[88:89], v[88:89]
	v_pk_mul_f32 v[92:93], v[96:97], v[96:97]
	v_pk_mul_f32 v[96:97], v[104:105], v[104:105]
	v_pk_mul_f32 v[104:105], v[98:99], v[98:99]
	v_add_f32_e32 v86, v86, v87
	v_add_f32_e32 v84, v84, v85
	v_add_f32_e32 v84, v84, v86
	v_add_f32_e32 v85, v104, v105
	v_pk_mul_f32 v[106:107], v[102:103], v[102:103]
	v_add_f32_e32 v84, v85, v84
	v_add_f32_e32 v85, v92, v93
	v_add_f32_e32 v86, v90, v91
	v_add_f32_e32 v83, v106, v107
	v_add_f32_e32 v85, v86, v85
	v_add_f32_e32 v86, v94, v95
	v_add_f32_e32 v83, v83, v84
	v_add_f32_e32 v84, v96, v97
	v_add_f32_e32 v85, v86, v85
	v_add_f32_e32 v84, v84, v85
	v_add_f32_e32 v86, v84, v83
	v_mov_b32_e32 v87, v86
	s_nop 1
	v_permlane16_swap_b32_e32 v87, v86
	s_mov_b64 s[40:41], 0x20100
	v_lshl_add_u64 v[100:101], v[214:215], 0, s[40:41]
	v_cvt_pk_bf16_f32 v83, v88, v89
	v_cvt_pk_bf16_f32 v84, v98, v99
	v_cvt_pk_bf16_f32 v85, v102, v103
	global_store_dwordx4 v[100:101], v[82:85], off
	s_waitcnt lgkmcnt(0)
	s_nop 0
	v_add_f32_e32 v82, v86, v87
	v_mov_b32_e32 v83, v82
	s_nop 1
	v_permlane32_swap_b32_e32 v82, v83
	s_and_saveexec_b64 s[40:41], s[36:37]
	s_cbranch_execz .LBB0_533
	v_or_b32_e32 v84, 32, v216
	v_ashrrev_i32_e32 v85, 31, v84
	v_add_f32_e32 v86, v82, v83
	v_lshlrev_b64 v[82:83], 7, v[84:85]
	v_lshl_add_u64 v[82:83], s[8:9], 0, v[82:83]
	v_lshl_add_u64 v[82:83], s[20:21], 2, v[82:83]
	s_lshl_b32 s26, s69, 2
	v_lshl_add_u64 v[82:83], v[82:83], 0, s[26:27]
	global_store_dword v[82:83], v86, off
; __device__ __forceinline__ unsigned cvt_pk_bf16(float lo, float hi) { return __builtin_bit_cast(unsigned, __builtin_convertvector((f32x2_t){lo, hi}, bf16x2_t)); }
; __device__ __forceinline__ float bf_lo(unsigned w) { return __uint_as_float(w << 16); }
; __device__ __forceinline__ float bf_hi(unsigned w) { return __uint_as_float(w & 0xffff0000u); }
; __device__ __forceinline__ float sum_xor16(float v) { return v + swz_f<0x401F>(v); }
; __device__ __forceinline__ float sum_xor32(float v) { const auto r = __builtin_amdgcn_permlane32_swap(__float_as_uint(v), __float_as_uint(v), false, false); return __uint_as_float(r[0]) + __uint_as_float(r[1]); }
;     __device__ __forceinline__ void operator()(const f32x4 (&acc)[2][2][4][2], const Unit& u, int wr, int wc, int fr, int fq, PG8_LAS unsigned char*, int) const {
;     ...
;         for (int ai = 0; ai < 2; ++ai)
; #pragma unroll
;             for (int m = 0; m < 4; ++m) { const int row = row0 + ai * HALF + m * 16; float q = 0.f;
; #pragma unroll
;                 for (int bj = 0; bj < 2; ++bj) { const u32x4 o = old[ai][m][bj]; const f32x4 a0 = acc[ai][bj][m][0], a1 = acc[ai][bj][m][1];
;                     const float h0 = bf_lo(o.x) + a0[0], h1 = bf_hi(o.x) + a0[1], h2 = bf_lo(o.y) + a0[2], h3 = bf_hi(o.y) + a0[3], h4 = bf_lo(o.z) + a1[0], h5 = bf_hi(o.z) + a1[1], h6 = bf_lo(o.w) + a1[2], h7 = bf_hi(o.w) + a1[3];
;                     u32x4 w; w.x = cvt_pk_bf16(h0, h1); w.y = cvt_pk_bf16(h2, h3); w.z = cvt_pk_bf16(h4, h5); w.w = cvt_pk_bf16(h6, h7);
;                     *(u32x4*)(base + (size_t)(ai * HALF + m * 16) * 2048 + bj * HALF) = w;
;                     q += (h0 * h0 + h1 * h1) + (h2 * h2 + h3 * h3) + (h4 * h4 + h5 * h5) + (h6 * h6 + h7 * h7); }
;                 q = sum_xor32(sum_xor16(q));
;                 if (fq == 0) SSo[(size_t)row * 32 + u.pn * 4 + wc] = q; }
.LBB0_533:
	s_or_b64 exec, exec, s[40:41]
	v_lshlrev_b32_e32 v86, 16, v166
	v_and_b32_e32 v87, 0xffff0000, v166
	v_pk_add_f32 v[78:79], v[78:79], v[86:87]
	v_lshlrev_b32_e32 v86, 16, v167
	v_and_b32_e32 v87, 0xffff0000, v167
	v_pk_add_f32 v[80:81], v[80:81], v[86:87]
	v_lshlrev_b32_e32 v86, 16, v168
	v_and_b32_e32 v87, 0xffff0000, v168
	v_pk_add_f32 v[86:87], v[74:75], v[86:87]
	v_lshlrev_b32_e32 v74, 16, v169
	v_and_b32_e32 v75, 0xffff0000, v169
	v_pk_add_f32 v[88:89], v[76:77], v[74:75]
	v_lshl_add_u64 v[82:83], v[214:215], 0, s[94:95]
	v_cvt_pk_bf16_f32 v74, v78, v79
	v_cvt_pk_bf16_f32 v75, v80, v81
	v_cvt_pk_bf16_f32 v76, v86, v87
	v_cvt_pk_bf16_f32 v77, v88, v89
	global_store_dwordx4 v[82:83], v[74:77], off
	v_lshlrev_b32_e32 v82, 16, v162
	v_and_b32_e32 v83, 0xffff0000, v162
	v_pk_add_f32 v[70:71], v[70:71], v[82:83]
	v_lshlrev_b32_e32 v82, 16, v163
	v_and_b32_e32 v83, 0xffff0000, v163
	v_pk_add_f32 v[72:73], v[72:73], v[82:83]
	v_lshlrev_b32_e32 v82, 16, v164
	v_and_b32_e32 v83, 0xffff0000, v164
	v_pk_add_f32 v[82:83], v[66:67], v[82:83]
	v_lshlrev_b32_e32 v66, 16, v165
	v_and_b32_e32 v67, 0xffff0000, v165
	v_pk_mul_f32 v[74:75], v[78:79], v[78:79]
	v_pk_mul_f32 v[78:79], v[86:87], v[86:87]
	v_pk_add_f32 v[86:87], v[68:69], v[66:67]
	v_cvt_pk_bf16_f32 v66, v70, v71
	v_pk_mul_f32 v[68:69], v[70:71], v[70:71]
	v_pk_mul_f32 v[70:71], v[72:73], v[72:73]
	v_pk_mul_f32 v[76:77], v[80:81], v[80:81]
	v_pk_mul_f32 v[80:81], v[88:89], v[88:89]
	v_pk_mul_f32 v[88:89], v[82:83], v[82:83]
	v_add_f32_e32 v70, v70, v71
	v_add_f32_e32 v68, v68, v69
	v_add_f32_e32 v68, v68, v70
	v_add_f32_e32 v69, v88, v89
	v_pk_mul_f32 v[90:91], v[86:87], v[86:87]
	v_add_f32_e32 v68, v69, v68
	v_add_f32_e32 v69, v76, v77
	v_add_f32_e32 v70, v74, v75
	v_add_f32_e32 v67, v90, v91
	v_add_f32_e32 v69, v70, v69
	v_add_f32_e32 v70, v78, v79
	v_add_f32_e32 v67, v67, v68
	v_add_f32_e32 v68, v80, v81
	v_add_f32_e32 v69, v70, v69
	v_add_f32_e32 v68, v68, v69
	v_add_f32_e32 v70, v68, v67
	v_mov_b32_e32 v71, v70
	s_nop 1
	v_permlane16_swap_b32_e32 v71, v70
	s_mov_b64 s[40:41], 0x30100
	v_lshl_add_u64 v[84:85], v[214:215], 0, s[40:41]
	v_cvt_pk_bf16_f32 v67, v72, v73
	v_cvt_pk_bf16_f32 v68, v82, v83
	v_cvt_pk_bf16_f32 v69, v86, v87
	global_store_dwordx4 v[84:85], v[66:69], off
	s_waitcnt lgkmcnt(0)
	s_nop 0
	v_add_f32_e32 v66, v70, v71
	v_mov_b32_e32 v67, v66
	s_nop 1
	v_permlane32_swap_b32_e32 v66, v67
	s_and_saveexec_b64 s[40:41], s[36:37]
	s_cbranch_execz .LBB0_535
	v_or_b32_e32 v68, 48, v216
	v_ashrrev_i32_e32 v69, 31, v68
	v_add_f32_e32 v70, v66, v67
	v_lshlrev_b64 v[66:67], 7, v[68:69]
	v_lshl_add_u64 v[66:67], s[8:9], 0, v[66:67]
	v_lshl_add_u64 v[66:67], s[20:21], 2, v[66:67]
	s_lshl_b32 s26, s69, 2
	v_lshl_add_u64 v[66:67], v[66:67], 0, s[26:27]
	global_store_dword v[66:67], v70, off
.LBB0_535:
	s_or_b64 exec, exec, s[40:41]
	s_waitcnt vmcnt(15)
	v_lshlrev_b32_e32 v70, 16, v158
	v_and_b32_e32 v71, 0xffff0000, v158
	v_pk_add_f32 v[62:63], v[62:63], v[70:71]
	v_lshlrev_b32_e32 v70, 16, v159
	v_and_b32_e32 v71, 0xffff0000, v159
	v_pk_add_f32 v[64:65], v[64:65], v[70:71]
	v_lshlrev_b32_e32 v70, 16, v160
	v_and_b32_e32 v71, 0xffff0000, v160
	v_pk_add_f32 v[70:71], v[58:59], v[70:71]
	v_lshlrev_b32_e32 v58, 16, v161
	v_and_b32_e32 v59, 0xffff0000, v161
	s_mov_b64 s[40:41], 0x80000
	v_pk_add_f32 v[72:73], v[60:61], v[58:59]
	v_lshl_add_u64 v[66:67], v[214:215], 0, s[40:41]
	v_cvt_pk_bf16_f32 v58, v62, v63
	v_cvt_pk_bf16_f32 v59, v64, v65
	v_cvt_pk_bf16_f32 v60, v70, v71
	v_cvt_pk_bf16_f32 v61, v72, v73
	global_store_dwordx4 v[66:67], v[58:61], off
	s_waitcnt vmcnt(15)
	v_lshlrev_b32_e32 v66, 16, v154
	v_and_b32_e32 v67, 0xffff0000, v154
	v_pk_add_f32 v[54:55], v[54:55], v[66:67]
	v_lshlrev_b32_e32 v66, 16, v155
	v_and_b32_e32 v67, 0xffff0000, v155
	v_pk_add_f32 v[56:57], v[56:57], v[66:67]
	v_lshlrev_b32_e32 v66, 16, v156
	v_and_b32_e32 v67, 0xffff0000, v156
	v_pk_add_f32 v[66:67], v[50:51], v[66:67]
	v_lshlrev_b32_e32 v50, 16, v157
	v_and_b32_e32 v51, 0xffff0000, v157
	v_pk_mul_f32 v[58:59], v[62:63], v[62:63]
	v_pk_mul_f32 v[62:63], v[70:71], v[70:71]
	v_pk_add_f32 v[70:71], v[52:53], v[50:51]
	v_cvt_pk_bf16_f32 v50, v54, v55
	v_pk_mul_f32 v[52:53], v[54:55], v[54:55]
	v_pk_mul_f32 v[54:55], v[56:57], v[56:57]
	v_pk_mul_f32 v[60:61], v[64:65], v[64:65]
	v_pk_mul_f32 v[64:65], v[72:73], v[72:73]
	v_pk_mul_f32 v[72:73], v[66:67], v[66:67]
	v_add_f32_e32 v54, v54, v55
	v_add_f32_e32 v52, v52, v53
	v_add_f32_e32 v52, v52, v54
	v_add_f32_e32 v53, v72, v73
	v_pk_mul_f32 v[74:75], v[70:71], v[70:71]
	v_add_f32_e32 v52, v53, v52
	v_add_f32_e32 v53, v60, v61
	v_add_f32_e32 v54, v58, v59
	v_add_f32_e32 v51, v74, v75
	v_add_f32_e32 v53, v54, v53
	v_add_f32_e32 v54, v62, v63
	v_add_f32_e32 v51, v51, v52
	v_add_f32_e32 v52, v64, v65
	v_add_f32_e32 v53, v54, v53
	v_add_f32_e32 v52, v52, v53
	v_add_f32_e32 v54, v52, v51
	v_mov_b32_e32 v55, v54
	s_nop 1
	v_permlane16_swap_b32_e32 v55, v54
	s_mov_b64 s[40:41], 0x80100
	v_lshl_add_u64 v[68:69], v[214:215], 0, s[40:41]
	v_cvt_pk_bf16_f32 v51, v56, v57
	v_cvt_pk_bf16_f32 v52, v66, v67
	v_cvt_pk_bf16_f32 v53, v70, v71
	global_store_dwordx4 v[68:69], v[50:53], off
	s_waitcnt lgkmcnt(0)
	s_nop 0
	v_add_f32_e32 v50, v54, v55
	v_mov_b32_e32 v51, v50
	s_nop 1
	v_permlane32_swap_b32_e32 v50, v51
	s_and_saveexec_b64 s[40:41], s[36:37]
	s_cbranch_execz .LBB0_537
	v_add_f32_e32 v52, v50, v51
	v_lshl_add_u64 v[50:51], s[20:21], 2, v[114:115]
	s_lshl_b32 s26, s69, 2
	v_lshl_add_u64 v[50:51], v[50:51], 0, s[26:27]
	v_add_co_u32_e32 v50, vcc, 0x4000, v50
	s_nop 1
	v_addc_co_u32_e32 v51, vcc, 0, v51, vcc
	global_store_dword v[50:51], v52, off
; __device__ __forceinline__ unsigned cvt_pk_bf16(float lo, float hi) { return __builtin_bit_cast(unsigned, __builtin_convertvector((f32x2_t){lo, hi}, bf16x2_t)); }
; __device__ __forceinline__ float bf_lo(unsigned w) { return __uint_as_float(w << 16); }
; __device__ __forceinline__ float bf_hi(unsigned w) { return __uint_as_float(w & 0xffff0000u); }
; __device__ __forceinline__ float sum_xor16(float v) { return v + swz_f<0x401F>(v); }
; __device__ __forceinline__ float sum_xor32(float v) { const auto r = __builtin_amdgcn_permlane32_swap(__float_as_uint(v), __float_as_uint(v), false, false); return __uint_as_float(r[0]) + __uint_as_float(r[1]); }
;     __device__ __forceinline__ void operator()(const f32x4 (&acc)[2][2][4][2], const Unit& u, int wr, int wc, int fr, int fq, PG8_LAS unsigned char*, int) const {
;     ...
;         for (int ai = 0; ai < 2; ++ai)
; #pragma unroll
;             for (int m = 0; m < 4; ++m) { const int row = row0 + ai * HALF + m * 16; float q = 0.f;
; #pragma unroll
;                 for (int bj = 0; bj < 2; ++bj) { const u32x4 o = old[ai][m][bj]; const f32x4 a0 = acc[ai][bj][m][0], a1 = acc[ai][bj][m][1];
;                     const float h0 = bf_lo(o.x) + a0[0], h1 = bf_hi(o.x) + a0[1], h2 = bf_lo(o.y) + a0[2], h3 = bf_hi(o.y) + a0[3], h4 = bf_lo(o.z) + a1[0], h5 = bf_hi(o.z) + a1[1], h6 = bf_lo(o.w) + a1[2], h7 = bf_hi(o.w) + a1[3];
;                     u32x4 w; w.x = cvt_pk_bf16(h0, h1); w.y = cvt_pk_bf16(h2, h3); w.z = cvt_pk_bf16(h4, h5); w.w = cvt_pk_bf16(h6, h7);
;                     *(u32x4*)(base + (size_t)(ai * HALF + m * 16) * 2048 + bj * HALF) = w;
;                     q += (h0 * h0 + h1 * h1) + (h2 * h2 + h3 * h3) + (h4 * h4 + h5 * h5) + (h6 * h6 + h7 * h7); }
;                 q = sum_xor32(sum_xor16(q));
;                 if (fq == 0) SSo[(size_t)row * 32 + u.pn * 4 + wc] = q; }
.LBB0_537:
	s_or_b64 exec, exec, s[40:41]
	s_waitcnt vmcnt(15)
	v_lshlrev_b32_e32 v54, 16, v150
	v_and_b32_e32 v55, 0xffff0000, v150
	v_pk_add_f32 v[46:47], v[46:47], v[54:55]
	v_lshlrev_b32_e32 v54, 16, v151
	v_and_b32_e32 v55, 0xffff0000, v151
	v_pk_add_f32 v[48:49], v[48:49], v[54:55]
	v_lshlrev_b32_e32 v54, 16, v152
	v_and_b32_e32 v55, 0xffff0000, v152
	v_pk_add_f32 v[54:55], v[42:43], v[54:55]
	v_lshlrev_b32_e32 v42, 16, v153
	v_and_b32_e32 v43, 0xffff0000, v153
	s_mov_b64 s[40:41], 0x90000
	v_pk_add_f32 v[56:57], v[44:45], v[42:43]
	v_lshl_add_u64 v[50:51], v[214:215], 0, s[40:41]
	v_cvt_pk_bf16_f32 v42, v46, v47
	v_cvt_pk_bf16_f32 v43, v48, v49
	v_cvt_pk_bf16_f32 v44, v54, v55
	v_cvt_pk_bf16_f32 v45, v56, v57
	global_store_dwordx4 v[50:51], v[42:45], off
	s_waitcnt vmcnt(15)
	v_lshlrev_b32_e32 v50, 16, v146
	v_and_b32_e32 v51, 0xffff0000, v146
	v_pk_add_f32 v[38:39], v[38:39], v[50:51]
	v_lshlrev_b32_e32 v50, 16, v147
	v_and_b32_e32 v51, 0xffff0000, v147
	v_pk_add_f32 v[40:41], v[40:41], v[50:51]
	v_lshlrev_b32_e32 v50, 16, v148
	v_and_b32_e32 v51, 0xffff0000, v148
	v_pk_add_f32 v[50:51], v[34:35], v[50:51]
	v_lshlrev_b32_e32 v34, 16, v149
	v_and_b32_e32 v35, 0xffff0000, v149
	v_pk_mul_f32 v[42:43], v[46:47], v[46:47]
	v_pk_mul_f32 v[46:47], v[54:55], v[54:55]
	v_pk_add_f32 v[54:55], v[36:37], v[34:35]
	v_cvt_pk_bf16_f32 v34, v38, v39
	v_pk_mul_f32 v[36:37], v[38:39], v[38:39]
	v_pk_mul_f32 v[38:39], v[40:41], v[40:41]
	v_pk_mul_f32 v[44:45], v[48:49], v[48:49]
	v_pk_mul_f32 v[48:49], v[56:57], v[56:57]
	v_pk_mul_f32 v[56:57], v[50:51], v[50:51]
	v_add_f32_e32 v38, v38, v39
	v_add_f32_e32 v36, v36, v37
	v_add_f32_e32 v36, v36, v38
	v_add_f32_e32 v37, v56, v57
	v_pk_mul_f32 v[58:59], v[54:55], v[54:55]
	v_add_f32_e32 v36, v37, v36
	v_add_f32_e32 v37, v44, v45
	v_add_f32_e32 v38, v42, v43
	v_add_f32_e32 v35, v58, v59
	v_add_f32_e32 v37, v38, v37
	v_add_f32_e32 v38, v46, v47
	v_add_f32_e32 v35, v35, v36
	v_add_f32_e32 v36, v48, v49
	v_add_f32_e32 v37, v38, v37
	v_add_f32_e32 v36, v36, v37
	v_add_f32_e32 v38, v36, v35
	v_mov_b32_e32 v39, v38
	s_nop 1
	v_permlane16_swap_b32_e32 v39, v38
	s_mov_b64 s[40:41], 0x90100
	v_lshl_add_u64 v[52:53], v[214:215], 0, s[40:41]
	v_cvt_pk_bf16_f32 v35, v40, v41
	v_cvt_pk_bf16_f32 v36, v50, v51
	v_cvt_pk_bf16_f32 v37, v54, v55
	global_store_dwordx4 v[52:53], v[34:37], off
	s_waitcnt lgkmcnt(0)
	s_nop 0
	v_add_f32_e32 v34, v38, v39
	v_mov_b32_e32 v35, v34
	s_nop 1
	v_permlane32_swap_b32_e32 v34, v35
	s_and_saveexec_b64 s[40:41], s[36:37]
	s_cbranch_execz .LBB0_539
	v_add_f32_e32 v36, v34, v35
	v_lshl_add_u64 v[34:35], s[20:21], 2, v[114:115]
	s_lshl_b32 s26, s69, 2
	v_lshl_add_u64 v[34:35], v[34:35], 0, s[26:27]
	v_add_co_u32_e32 v34, vcc, 0x4000, v34
	s_nop 1
	v_addc_co_u32_e32 v35, vcc, 0, v35, vcc
	global_store_dword v[34:35], v36, off offset:2048
; __device__ __forceinline__ unsigned cvt_pk_bf16(float lo, float hi) { return __builtin_bit_cast(unsigned, __builtin_convertvector((f32x2_t){lo, hi}, bf16x2_t)); }
; __device__ __forceinline__ float bf_lo(unsigned w) { return __uint_as_float(w << 16); }
; __device__ __forceinline__ float bf_hi(unsigned w) { return __uint_as_float(w & 0xffff0000u); }
; __device__ __forceinline__ float sum_xor16(float v) { return v + swz_f<0x401F>(v); }
; __device__ __forceinline__ float sum_xor32(float v) { const auto r = __builtin_amdgcn_permlane32_swap(__float_as_uint(v), __float_as_uint(v), false, false); return __uint_as_float(r[0]) + __uint_as_float(r[1]); }
;     __device__ __forceinline__ void operator()(const f32x4 (&acc)[2][2][4][2], const Unit& u, int wr, int wc, int fr, int fq, PG8_LAS unsigned char*, int) const {
;     ...
;         for (int ai = 0; ai < 2; ++ai)
; #pragma unroll
;             for (int m = 0; m < 4; ++m) { const int row = row0 + ai * HALF + m * 16; float q = 0.f;
; #pragma unroll
;                 for (int bj = 0; bj < 2; ++bj) { const u32x4 o = old[ai][m][bj]; const f32x4 a0 = acc[ai][bj][m][0], a1 = acc[ai][bj][m][1];
;                     const float h0 = bf_lo(o.x) + a0[0], h1 = bf_hi(o.x) + a0[1], h2 = bf_lo(o.y) + a0[2], h3 = bf_hi(o.y) + a0[3], h4 = bf_lo(o.z) + a1[0], h5 = bf_hi(o.z) + a1[1], h6 = bf_lo(o.w) + a1[2], h7 = bf_hi(o.w) + a1[3];
;                     u32x4 w; w.x = cvt_pk_bf16(h0, h1); w.y = cvt_pk_bf16(h2, h3); w.z = cvt_pk_bf16(h4, h5); w.w = cvt_pk_bf16(h6, h7);
;                     *(u32x4*)(base + (size_t)(ai * HALF + m * 16) * 2048 + bj * HALF) = w;
;                     q += (h0 * h0 + h1 * h1) + (h2 * h2 + h3 * h3) + (h4 * h4 + h5 * h5) + (h6 * h6 + h7 * h7); }
;                 q = sum_xor32(sum_xor16(q));
;                 if (fq == 0) SSo[(size_t)row * 32 + u.pn * 4 + wc] = q; }
.LBB0_539:
	s_or_b64 exec, exec, s[40:41]
	s_waitcnt vmcnt(15)
	v_lshlrev_b32_e32 v38, 16, v134
	v_and_b32_e32 v39, 0xffff0000, v134
	v_pk_add_f32 v[30:31], v[30:31], v[38:39]
	v_lshlrev_b32_e32 v38, 16, v135
	v_and_b32_e32 v39, 0xffff0000, v135
	v_pk_add_f32 v[32:33], v[32:33], v[38:39]
	v_lshlrev_b32_e32 v38, 16, v136
	v_and_b32_e32 v39, 0xffff0000, v136
	v_pk_add_f32 v[38:39], v[26:27], v[38:39]
	v_lshlrev_b32_e32 v26, 16, v137
	v_and_b32_e32 v27, 0xffff0000, v137
	s_mov_b64 s[40:41], 0xa0000
	v_pk_add_f32 v[40:41], v[28:29], v[26:27]
	v_lshl_add_u64 v[34:35], v[214:215], 0, s[40:41]
	v_cvt_pk_bf16_f32 v26, v30, v31
	v_cvt_pk_bf16_f32 v27, v32, v33
	v_cvt_pk_bf16_f32 v28, v38, v39
	v_cvt_pk_bf16_f32 v29, v40, v41
	global_store_dwordx4 v[34:35], v[26:29], off
	s_waitcnt vmcnt(15)
	v_lshlrev_b32_e32 v34, 16, v130
	v_and_b32_e32 v35, 0xffff0000, v130
	v_pk_add_f32 v[22:23], v[22:23], v[34:35]
	v_lshlrev_b32_e32 v34, 16, v131
	v_and_b32_e32 v35, 0xffff0000, v131
	v_pk_add_f32 v[24:25], v[24:25], v[34:35]
	v_lshlrev_b32_e32 v34, 16, v132
	v_and_b32_e32 v35, 0xffff0000, v132
	v_pk_add_f32 v[34:35], v[18:19], v[34:35]
	v_lshlrev_b32_e32 v18, 16, v133
	v_and_b32_e32 v19, 0xffff0000, v133
	v_pk_mul_f32 v[26:27], v[30:31], v[30:31]
	v_pk_mul_f32 v[30:31], v[38:39], v[38:39]
	v_pk_add_f32 v[38:39], v[20:21], v[18:19]
	v_cvt_pk_bf16_f32 v18, v22, v23
	v_pk_mul_f32 v[20:21], v[22:23], v[22:23]
	v_pk_mul_f32 v[22:23], v[24:25], v[24:25]
	v_pk_mul_f32 v[28:29], v[32:33], v[32:33]
	v_pk_mul_f32 v[32:33], v[40:41], v[40:41]
	v_pk_mul_f32 v[40:41], v[34:35], v[34:35]
	v_add_f32_e32 v22, v22, v23
	v_add_f32_e32 v20, v20, v21
	v_add_f32_e32 v20, v20, v22
	v_add_f32_e32 v21, v40, v41
	v_pk_mul_f32 v[42:43], v[38:39], v[38:39]
	v_add_f32_e32 v20, v21, v20
	v_add_f32_e32 v21, v28, v29
	v_add_f32_e32 v22, v26, v27
	v_add_f32_e32 v19, v42, v43
	v_add_f32_e32 v21, v22, v21
	v_add_f32_e32 v22, v30, v31
	v_add_f32_e32 v19, v19, v20
	v_add_f32_e32 v20, v32, v33
	v_add_f32_e32 v21, v22, v21
	v_add_f32_e32 v20, v20, v21
	v_add_f32_e32 v22, v20, v19
	v_mov_b32_e32 v23, v22
	s_nop 1
	v_permlane16_swap_b32_e32 v23, v22
	s_mov_b64 s[40:41], 0xa0100
	v_lshl_add_u64 v[36:37], v[214:215], 0, s[40:41]
	v_cvt_pk_bf16_f32 v19, v24, v25
	v_cvt_pk_bf16_f32 v20, v34, v35
	v_cvt_pk_bf16_f32 v21, v38, v39
	global_store_dwordx4 v[36:37], v[18:21], off
	s_waitcnt lgkmcnt(0)
	s_nop 0
	v_add_f32_e32 v18, v22, v23
	v_mov_b32_e32 v19, v18
	s_nop 1
	v_permlane32_swap_b32_e32 v18, v19
	s_and_saveexec_b64 s[40:41], s[36:37]
	s_cbranch_execz .LBB0_541
	v_add_f32_e32 v20, v18, v19
	v_lshl_add_u64 v[18:19], s[20:21], 2, v[114:115]
	s_lshl_b32 s26, s69, 2
	v_lshl_add_u64 v[18:19], v[18:19], 0, s[26:27]
	v_add_co_u32_e32 v18, vcc, 0x5000, v18
	s_nop 1
	v_addc_co_u32_e32 v19, vcc, 0, v19, vcc
	global_store_dword v[18:19], v20, off
.LBB0_541:
	s_or_b64 exec, exec, s[40:41]
	s_waitcnt vmcnt(15)
	v_lshlrev_b32_e32 v22, 16, v122
	v_and_b32_e32 v23, 0xffff0000, v122
	v_pk_add_f32 v[14:15], v[14:15], v[22:23]
	v_lshlrev_b32_e32 v22, 16, v123
	v_and_b32_e32 v23, 0xffff0000, v123
	v_pk_add_f32 v[16:17], v[16:17], v[22:23]
	v_lshlrev_b32_e32 v22, 16, v124
	v_and_b32_e32 v23, 0xffff0000, v124
	v_pk_add_f32 v[22:23], v[10:11], v[22:23]
	v_lshlrev_b32_e32 v10, 16, v125
	v_and_b32_e32 v11, 0xffff0000, v125
	s_mov_b64 s[40:41], 0xb0000
	v_pk_add_f32 v[24:25], v[12:13], v[10:11]
	v_lshl_add_u64 v[18:19], v[214:215], 0, s[40:41]
	v_cvt_pk_bf16_f32 v10, v14, v15
	v_cvt_pk_bf16_f32 v11, v16, v17
	v_cvt_pk_bf16_f32 v12, v22, v23
	v_cvt_pk_bf16_f32 v13, v24, v25
	global_store_dwordx4 v[18:19], v[10:13], off
	s_waitcnt vmcnt(15)
	v_lshlrev_b32_e32 v18, 16, v118
	v_and_b32_e32 v19, 0xffff0000, v118
	v_pk_add_f32 v[6:7], v[6:7], v[18:19]
	v_lshlrev_b32_e32 v18, 16, v119
	v_and_b32_e32 v19, 0xffff0000, v119
	v_pk_add_f32 v[8:9], v[8:9], v[18:19]
	v_lshlrev_b32_e32 v18, 16, v120
	v_and_b32_e32 v19, 0xffff0000, v120
	v_pk_add_f32 v[18:19], v[2:3], v[18:19]
	v_lshlrev_b32_e32 v2, 16, v121
	v_and_b32_e32 v3, 0xffff0000, v121
	v_pk_mul_f32 v[10:11], v[14:15], v[14:15]
	v_pk_mul_f32 v[14:15], v[22:23], v[22:23]
	v_pk_add_f32 v[22:23], v[4:5], v[2:3]
	v_cvt_pk_bf16_f32 v2, v6, v7
	v_pk_mul_f32 v[4:5], v[6:7], v[6:7]
	v_pk_mul_f32 v[6:7], v[8:9], v[8:9]
	v_pk_mul_f32 v[12:13], v[16:17], v[16:17]
	v_pk_mul_f32 v[16:17], v[24:25], v[24:25]
	v_pk_mul_f32 v[24:25], v[18:19], v[18:19]
	v_add_f32_e32 v6, v6, v7
	v_add_f32_e32 v4, v4, v5
	v_add_f32_e32 v4, v4, v6
	v_add_f32_e32 v5, v24, v25
	v_pk_mul_f32 v[26:27], v[22:23], v[22:23]
	v_add_f32_e32 v4, v5, v4
	v_add_f32_e32 v5, v12, v13
	v_add_f32_e32 v6, v10, v11
	v_add_f32_e32 v3, v26, v27
	v_add_f32_e32 v5, v6, v5
	v_add_f32_e32 v6, v14, v15
	v_add_f32_e32 v3, v3, v4
	v_add_f32_e32 v4, v16, v17
	v_add_f32_e32 v5, v6, v5
	v_add_f32_e32 v4, v4, v5
	v_add_f32_e32 v6, v4, v3
	v_mov_b32_e32 v7, v6
	s_nop 1
	v_permlane16_swap_b32_e32 v7, v6
	s_mov_b64 s[40:41], 0xb0100
	v_lshl_add_u64 v[20:21], v[214:215], 0, s[40:41]
	v_cvt_pk_bf16_f32 v3, v8, v9
	v_cvt_pk_bf16_f32 v4, v18, v19
	v_cvt_pk_bf16_f32 v5, v22, v23
	global_store_dwordx4 v[20:21], v[2:5], off
	s_waitcnt lgkmcnt(0)
	s_nop 0
	v_add_f32_e32 v2, v6, v7
	v_mov_b32_e32 v3, v2
	s_nop 1
	v_permlane32_swap_b32_e32 v2, v3
	s_and_saveexec_b64 s[40:41], s[36:37]
	s_cbranch_execz .LBB0_543
	v_add_f32_e32 v4, v2, v3
	v_lshl_add_u64 v[2:3], s[20:21], 2, v[114:115]
	s_lshl_b32 s26, s69, 2
	v_lshl_add_u64 v[2:3], v[2:3], 0, s[26:27]
	v_add_co_u32_e32 v2, vcc, 0x5000, v2
	s_nop 1
	v_addc_co_u32_e32 v3, vcc, 0, v3, vcc
	global_store_dword v[2:3], v4, off offset:2048

; #define PG8_LAS __attribute__((address_space(3)))
; __device__ __forceinline__ unsigned cvt_pk_bf16(float lo, float hi) { return __builtin_bit_cast(unsigned, __builtin_convertvector((f32x2_t){lo, hi}, bf16x2_t)); }
; __device__ __forceinline__ float bf_lo(unsigned w) { return __uint_as_float(w << 16); }
; __device__ __forceinline__ float bf_hi(unsigned w) { return __uint_as_float(w & 0xffff0000u); }
; __device__ __forceinline__ float sum_xor16(float v) { return v + swz_f<0x401F>(v); }
; __device__ __forceinline__ float sum_xor32(float v) { const auto r = __builtin_amdgcn_permlane32_swap(__float_as_uint(v), __float_as_uint(v), false, false); return __uint_as_float(r[0]) + __uint_as_float(r[1]); }
;     __device__ __forceinline__ void operator()(const f32x4 (&acc)[2][2][4][2], const Unit& u, int wr, int wc, int fr, int fq, PG8_LAS unsigned char*, int) const {
;         const int row0 = u.pm * BM + wr * 64 + fr, col0 = u.pn * BM + wc * 32 + 8 * fq;
;         bf16_t* const base = HB + (size_t)row0 * 2048 + col0;
;         u32x4 old[2][4][2];
; #pragma unroll
;         for (int ai = 0; ai < 2; ++ai)
; #pragma unroll
;             for (int m = 0; m < 4; ++m)
; #pragma unroll
;                 for (int bj = 0; bj < 2; ++bj) old[ai][m][bj] = *(const u32x4*)(base + (size_t)(ai * HALF + m * 16) * 2048 + bj * HALF);
; #pragma unroll
;         for (int ai = 0; ai < 2; ++ai)
; #pragma unroll
;             for (int m = 0; m < 4; ++m) { const int row = row0 + ai * HALF + m * 16; float q = 0.f;
; #pragma unroll
;                 for (int bj = 0; bj < 2; ++bj) { const u32x4 o = old[ai][m][bj]; const f32x4 a0 = acc[ai][bj][m][0], a1 = acc[ai][bj][m][1];
;                     const float h0 = bf_lo(o.x) + a0[0], h1 = bf_hi(o.x) + a0[1], h2 = bf_lo(o.y) + a0[2], h3 = bf_hi(o.y) + a0[3], h4 = bf_lo(o.z) + a1[0], h5 = bf_hi(o.z) + a1[1], h6 = bf_lo(o.w) + a1[2], h7 = bf_hi(o.w) + a1[3];
;                     u32x4 w; w.x = cvt_pk_bf16(h0, h1); w.y = cvt_pk_bf16(h2, h3); w.z = cvt_pk_bf16(h4, h5); w.w = cvt_pk_bf16(h6, h7);
;                     *(u32x4*)(base + (size_t)(ai * HALF + m * 16) * 2048 + bj * HALF) = w;
;                     q += (h0 * h0 + h1 * h1) + (h2 * h2 + h3 * h3) + (h4 * h4 + h5 * h5) + (h6 * h6 + h7 * h7); }
;                 q = sum_xor32(sum_xor16(q));
;                 if (fq == 0) SSo[(size_t)row * 32 + u.pn * 4 + wc] = q; }
.LBB0_762:
	v_lshl_add_u32 v216, s73, 8, v1
	v_ashrrev_i32_e32 v217, 31, v216
	v_lshl_add_u32 v118, s26, 8, v220
	v_lshlrev_b64 v[120:121], 12, v[216:217]
	v_lshl_add_u64 v[120:121], s[4:5], 0, v[120:121]
	v_ashrrev_i32_e32 v119, 31, v118
	v_lshl_add_u64 v[214:215], v[118:119], 1, v[120:121]
	global_load_dwordx4 v[226:229], v[214:215], off
	global_load_dwordx4 v[186:189], v[214:215], off offset:256
	v_add_co_u32_e32 v118, vcc, s23, v214
	s_mov_b32 s18, 0x80000
	s_nop 0
	v_addc_co_u32_e32 v119, vcc, 0, v215, vcc
	global_load_dwordx4 v[182:185], v[118:119], off
	global_load_dwordx4 v[178:181], v[118:119], off offset:256
	v_add_co_u32_e32 v118, vcc, s0, v214
	s_nop 1
	v_addc_co_u32_e32 v119, vcc, 0, v215, vcc
	global_load_dwordx4 v[174:177], v[118:119], off
	global_load_dwordx4 v[170:173], v[118:119], off offset:256
	v_add_co_u32_e32 v118, vcc, s1, v214
	s_nop 0
	s_nop 0
	v_addc_co_u32_e32 v119, vcc, 0, v215, vcc
	global_load_dwordx4 v[166:169], v[118:119], off
	global_load_dwordx4 v[162:165], v[118:119], off offset:256
	v_add_co_u32_e32 v118, vcc, s18, v214
	s_nop 0
	s_nop 0
	v_addc_co_u32_e32 v119, vcc, 0, v215, vcc
	global_load_dwordx4 v[158:161], v[118:119], off
	global_load_dwordx4 v[154:157], v[118:119], off offset:256
	v_add_co_u32_e32 v118, vcc, s50, v214
	s_nop 0
	s_nop 0
	v_addc_co_u32_e32 v119, vcc, 0, v215, vcc
	global_load_dwordx4 v[150:153], v[118:119], off
	global_load_dwordx4 v[146:149], v[118:119], off offset:256
	v_add_co_u32_e32 v118, vcc, s51, v214
	s_nop 0
	s_nop 0
	v_addc_co_u32_e32 v119, vcc, 0, v215, vcc
	global_load_dwordx4 v[134:137], v[118:119], off
	global_load_dwordx4 v[130:133], v[118:119], off offset:256
	v_add_co_u32_e32 v118, vcc, s82, v214
	s_nop 0
	s_nop 0
	v_addc_co_u32_e32 v119, vcc, 0, v215, vcc
	global_load_dwordx4 v[122:125], v[118:119], off
	s_nop 0
	global_load_dwordx4 v[118:121], v[118:119], off offset:256
	s_waitcnt vmcnt(0)
	v_lshlrev_b32_e32 v230, 16, v226
	v_and_b32_e32 v231, 0xffff0000, v226
	v_lshlrev_b32_e32 v226, 16, v227
	v_and_b32_e32 v227, 0xffff0000, v227
	v_pk_add_f32 v[144:145], v[144:145], v[226:227]
	v_lshlrev_b32_e32 v226, 16, v228
	v_and_b32_e32 v227, 0xffff0000, v228
	v_pk_add_f32 v[226:227], v[138:139], v[226:227]
	v_lshlrev_b32_e32 v138, 16, v229
	v_and_b32_e32 v139, 0xffff0000, v229
	v_pk_add_f32 v[142:143], v[142:143], v[230:231]
	v_pk_add_f32 v[228:229], v[140:141], v[138:139]
	v_cvt_pk_bf16_f32 v138, v142, v143
	v_cvt_pk_bf16_f32 v139, v144, v145
	v_cvt_pk_bf16_f32 v140, v226, v227
	v_cvt_pk_bf16_f32 v141, v228, v229
	global_store_dwordx4 v[214:215], v[138:141], off
	s_lshl_b32 s18, s26, 2
	s_ashr_i32 s19, s18, 31
	v_pk_mul_f32 v[138:139], v[142:143], v[142:143]
	v_pk_mul_f32 v[142:143], v[226:227], v[226:227]
	v_lshlrev_b32_e32 v226, 16, v186
	v_and_b32_e32 v227, 0xffff0000, v186
	v_lshlrev_b32_e32 v186, 16, v187
	v_and_b32_e32 v187, 0xffff0000, v187
	v_pk_add_f32 v[128:129], v[128:129], v[186:187]
	v_lshlrev_b32_e32 v186, 16, v188
	v_and_b32_e32 v187, 0xffff0000, v188
	v_pk_add_f32 v[186:187], v[114:115], v[186:187]
	v_lshlrev_b32_e32 v114, 16, v189
	v_and_b32_e32 v115, 0xffff0000, v189
	v_pk_add_f32 v[126:127], v[126:127], v[226:227]
	v_pk_add_f32 v[188:189], v[116:117], v[114:115]
	v_cvt_pk_bf16_f32 v114, v126, v127
	v_cvt_pk_bf16_f32 v115, v128, v129
	v_cvt_pk_bf16_f32 v116, v186, v187
	v_cvt_pk_bf16_f32 v117, v188, v189
	global_store_dwordx4 v[214:215], v[114:117], off offset:256
	v_pk_mul_f32 v[140:141], v[144:145], v[144:145]
	v_pk_mul_f32 v[144:145], v[228:229], v[228:229]
	v_pk_mul_f32 v[114:115], v[126:127], v[126:127]
	v_pk_mul_f32 v[116:117], v[128:129], v[128:129]
	v_add_f32_e32 v114, v114, v115
	v_add_f32_e32 v116, v116, v117
	v_pk_mul_f32 v[126:127], v[186:187], v[186:187]
	v_add_f32_e32 v114, v114, v116
	v_add_f32_e32 v116, v140, v141
	v_add_f32_e32 v117, v138, v139
	v_pk_mul_f32 v[128:129], v[188:189], v[188:189]
	v_add_f32_e32 v115, v126, v127
	v_add_f32_e32 v116, v117, v116
	v_add_f32_e32 v117, v142, v143
	v_add_f32_e32 v128, v128, v129
	v_add_f32_e32 v114, v115, v114
	v_add_f32_e32 v115, v144, v145
	v_add_f32_e32 v116, v117, v116
	v_add_f32_e32 v114, v128, v114
	v_add_f32_e32 v115, v115, v116
	v_add_f32_e32 v114, v115, v114
	v_mov_b32_e32 v115, v114
	s_nop 1
	v_permlane16_swap_b32_e32 v115, v114
	s_waitcnt lgkmcnt(0)
	v_add_f32_e32 v116, v114, v115
	v_mov_b32_e32 v117, v116
	v_lshlrev_b64 v[114:115], 7, v[216:217]
	s_nop 0
	v_permlane32_swap_b32_e32 v116, v117
	v_lshl_add_u64 v[114:115], s[8:9], 0, v[114:115]
	s_and_saveexec_b64 s[20:21], s[36:37]
	s_cbranch_execz .LBB0_764
	v_add_f32_e32 v126, v116, v117
	v_lshl_add_u64 v[116:117], s[18:19], 2, v[114:115]
	s_lshl_b32 s26, s65, 2
	v_lshl_add_u64 v[116:117], v[116:117], 0, s[26:27]
	global_store_dword v[116:117], v126, off
; __device__ __forceinline__ unsigned cvt_pk_bf16(float lo, float hi) { return __builtin_bit_cast(unsigned, __builtin_convertvector((f32x2_t){lo, hi}, bf16x2_t)); }
; __device__ __forceinline__ float bf_lo(unsigned w) { return __uint_as_float(w << 16); }
; __device__ __forceinline__ float bf_hi(unsigned w) { return __uint_as_float(w & 0xffff0000u); }
; __device__ __forceinline__ float sum_xor16(float v) { return v + swz_f<0x401F>(v); }
; __device__ __forceinline__ float sum_xor32(float v) { const auto r = __builtin_amdgcn_permlane32_swap(__float_as_uint(v), __float_as_uint(v), false, false); return __uint_as_float(r[0]) + __uint_as_float(r[1]); }
;     __device__ __forceinline__ void operator()(const f32x4 (&acc)[2][2][4][2], const Unit& u, int wr, int wc, int fr, int fq, PG8_LAS unsigned char*, int) const {
;     ...
;         for (int ai = 0; ai < 2; ++ai)
; #pragma unroll
;             for (int m = 0; m < 4; ++m) { const int row = row0 + ai * HALF + m * 16; float q = 0.f;
; #pragma unroll
;                 for (int bj = 0; bj < 2; ++bj) { const u32x4 o = old[ai][m][bj]; const f32x4 a0 = acc[ai][bj][m][0], a1 = acc[ai][bj][m][1];
;                     const float h0 = bf_lo(o.x) + a0[0], h1 = bf_hi(o.x) + a0[1], h2 = bf_lo(o.y) + a0[2], h3 = bf_hi(o.y) + a0[3], h4 = bf_lo(o.z) + a1[0], h5 = bf_hi(o.z) + a1[1], h6 = bf_lo(o.w) + a1[2], h7 = bf_hi(o.w) + a1[3];
;                     u32x4 w; w.x = cvt_pk_bf16(h0, h1); w.y = cvt_pk_bf16(h2, h3); w.z = cvt_pk_bf16(h4, h5); w.w = cvt_pk_bf16(h6, h7);
;                     *(u32x4*)(base + (size_t)(ai * HALF + m * 16) * 2048 + bj * HALF) = w;
;                     q += (h0 * h0 + h1 * h1) + (h2 * h2 + h3 * h3) + (h4 * h4 + h5 * h5) + (h6 * h6 + h7 * h7); }
;                 q = sum_xor32(sum_xor16(q));
;                 if (fq == 0) SSo[(size_t)row * 32 + u.pn * 4 + wc] = q; }
.LBB0_764:
	s_or_b64 exec, exec, s[20:21]
	v_lshlrev_b32_e32 v128, 16, v182
	v_and_b32_e32 v129, 0xffff0000, v182
	v_pk_add_f32 v[110:111], v[110:111], v[128:129]
	v_lshlrev_b32_e32 v128, 16, v183
	v_and_b32_e32 v129, 0xffff0000, v183
	v_pk_add_f32 v[112:113], v[112:113], v[128:129]
	v_lshlrev_b32_e32 v128, 16, v184
	v_and_b32_e32 v129, 0xffff0000, v184
	v_pk_add_f32 v[128:129], v[106:107], v[128:129]
	v_lshlrev_b32_e32 v106, 16, v185
	v_and_b32_e32 v107, 0xffff0000, v185
	s_mov_b64 s[20:21], 0x10000
	v_pk_add_f32 v[138:139], v[108:109], v[106:107]
	v_lshl_add_u64 v[116:117], v[214:215], 0, s[20:21]
	v_cvt_pk_bf16_f32 v106, v110, v111
	v_cvt_pk_bf16_f32 v107, v112, v113
	v_cvt_pk_bf16_f32 v108, v128, v129
	v_cvt_pk_bf16_f32 v109, v138, v139
	global_store_dwordx4 v[116:117], v[106:109], off
	v_lshlrev_b32_e32 v116, 16, v178
	v_and_b32_e32 v117, 0xffff0000, v178
	v_pk_add_f32 v[102:103], v[102:103], v[116:117]
	v_lshlrev_b32_e32 v116, 16, v179
	v_and_b32_e32 v117, 0xffff0000, v179
	v_pk_add_f32 v[104:105], v[104:105], v[116:117]
	v_lshlrev_b32_e32 v116, 16, v180
	v_and_b32_e32 v117, 0xffff0000, v180
	v_pk_add_f32 v[116:117], v[98:99], v[116:117]
	v_lshlrev_b32_e32 v98, 16, v181
	v_and_b32_e32 v99, 0xffff0000, v181
	v_pk_mul_f32 v[106:107], v[110:111], v[110:111]
	v_pk_mul_f32 v[110:111], v[128:129], v[128:129]
	v_pk_add_f32 v[128:129], v[100:101], v[98:99]
	v_cvt_pk_bf16_f32 v98, v102, v103
	v_pk_mul_f32 v[100:101], v[102:103], v[102:103]
	v_pk_mul_f32 v[102:103], v[104:105], v[104:105]
	v_pk_mul_f32 v[108:109], v[112:113], v[112:113]
	v_pk_mul_f32 v[112:113], v[138:139], v[138:139]
	v_pk_mul_f32 v[138:139], v[116:117], v[116:117]
	v_add_f32_e32 v102, v102, v103
	v_add_f32_e32 v100, v100, v101
	v_add_f32_e32 v100, v100, v102
	v_add_f32_e32 v101, v138, v139
	v_pk_mul_f32 v[140:141], v[128:129], v[128:129]
	v_add_f32_e32 v100, v101, v100
	v_add_f32_e32 v101, v108, v109
	v_add_f32_e32 v102, v106, v107
	v_add_f32_e32 v99, v140, v141
	v_add_f32_e32 v101, v102, v101
	v_add_f32_e32 v102, v110, v111
	v_add_f32_e32 v99, v99, v100
	v_add_f32_e32 v100, v112, v113
	v_add_f32_e32 v101, v102, v101
	v_add_f32_e32 v100, v100, v101
	v_add_f32_e32 v102, v100, v99
	v_mov_b32_e32 v103, v102
	s_nop 1
	v_permlane16_swap_b32_e32 v103, v102
	s_mov_b64 s[20:21], 0x10100
	v_lshl_add_u64 v[126:127], v[214:215], 0, s[20:21]
	v_cvt_pk_bf16_f32 v99, v104, v105
	v_cvt_pk_bf16_f32 v100, v116, v117
	v_cvt_pk_bf16_f32 v101, v128, v129
	global_store_dwordx4 v[126:127], v[98:101], off
	s_waitcnt lgkmcnt(0)
	s_nop 0
	v_add_f32_e32 v98, v102, v103
	v_mov_b32_e32 v99, v98
	s_nop 1
	v_permlane32_swap_b32_e32 v98, v99
	s_and_saveexec_b64 s[20:21], s[36:37]
	s_cbranch_execz .LBB0_766
	v_or_b32_e32 v100, 16, v216
	v_ashrrev_i32_e32 v101, 31, v100
	v_add_f32_e32 v102, v98, v99
	v_lshlrev_b64 v[98:99], 7, v[100:101]
	v_lshl_add_u64 v[98:99], s[8:9], 0, v[98:99]
	v_lshl_add_u64 v[98:99], s[18:19], 2, v[98:99]
	s_lshl_b32 s26, s65, 2
	v_lshl_add_u64 v[98:99], v[98:99], 0, s[26:27]
	global_store_dword v[98:99], v102, off
.LBB0_766:
	s_or_b64 exec, exec, s[20:21]
	s_waitcnt vmcnt(15)
	v_lshlrev_b32_e32 v102, 16, v174
	v_and_b32_e32 v103, 0xffff0000, v174
	v_pk_add_f32 v[94:95], v[94:95], v[102:103]
	v_lshlrev_b32_e32 v102, 16, v175
	v_and_b32_e32 v103, 0xffff0000, v175
	v_pk_add_f32 v[96:97], v[96:97], v[102:103]
	v_lshlrev_b32_e32 v102, 16, v176
	v_and_b32_e32 v103, 0xffff0000, v176
	v_pk_add_f32 v[102:103], v[90:91], v[102:103]
	v_lshlrev_b32_e32 v90, 16, v177
	v_and_b32_e32 v91, 0xffff0000, v177
	s_mov_b64 s[20:21], 0x20000
	v_pk_add_f32 v[104:105], v[92:93], v[90:91]
	v_lshl_add_u64 v[98:99], v[214:215], 0, s[20:21]
	v_cvt_pk_bf16_f32 v90, v94, v95
	v_cvt_pk_bf16_f32 v91, v96, v97
	v_cvt_pk_bf16_f32 v92, v102, v103
	v_cvt_pk_bf16_f32 v93, v104, v105
	global_store_dwordx4 v[98:99], v[90:93], off
	s_waitcnt vmcnt(15)
	v_lshlrev_b32_e32 v98, 16, v170
	v_and_b32_e32 v99, 0xffff0000, v170
	v_pk_add_f32 v[86:87], v[86:87], v[98:99]
	v_lshlrev_b32_e32 v98, 16, v171
	v_and_b32_e32 v99, 0xffff0000, v171
	v_pk_add_f32 v[88:89], v[88:89], v[98:99]
	v_lshlrev_b32_e32 v98, 16, v172
	v_and_b32_e32 v99, 0xffff0000, v172
	v_pk_add_f32 v[98:99], v[82:83], v[98:99]
	v_lshlrev_b32_e32 v82, 16, v173
	v_and_b32_e32 v83, 0xffff0000, v173
	v_pk_mul_f32 v[90:91], v[94:95], v[94:95]
	v_pk_mul_f32 v[94:95], v[102:103], v[102:103]
	v_pk_add_f32 v[102:103], v[84:85], v[82:83]
	v_cvt_pk_bf16_f32 v82, v86, v87
	v_pk_mul_f32 v[84:85], v[86:87], v[86:87]
	v_pk_mul_f32 v[86:87], v[88:89], v[88:89]
	v_pk_mul_f32 v[92:93], v[96:97], v[96:97]
	v_pk_mul_f32 v[96:97], v[104:105], v[104:105]
	v_pk_mul_f32 v[104:105], v[98:99], v[98:99]
	v_add_f32_e32 v86, v86, v87
	v_add_f32_e32 v84, v84, v85
	v_add_f32_e32 v84, v84, v86
	v_add_f32_e32 v85, v104, v105
	v_pk_mul_f32 v[106:107], v[102:103], v[102:103]
	v_add_f32_e32 v84, v85, v84
	v_add_f32_e32 v85, v92, v93
	v_add_f32_e32 v86, v90, v91
	v_add_f32_e32 v83, v106, v107
	v_add_f32_e32 v85, v86, v85
	v_add_f32_e32 v86, v94, v95
	v_add_f32_e32 v83, v83, v84
	v_add_f32_e32 v84, v96, v97
	v_add_f32_e32 v85, v86, v85
	v_add_f32_e32 v84, v84, v85
	v_add_f32_e32 v86, v84, v83
	v_mov_b32_e32 v87, v86
	s_nop 1
	v_permlane16_swap_b32_e32 v87, v86
	s_mov_b64 s[20:21], 0x20100
	v_lshl_add_u64 v[100:101], v[214:215], 0, s[20:21]
	v_cvt_pk_bf16_f32 v83, v88, v89
	v_cvt_pk_bf16_f32 v84, v98, v99
	v_cvt_pk_bf16_f32 v85, v102, v103
	global_store_dwordx4 v[100:101], v[82:85], off
	s_waitcnt lgkmcnt(0)
	s_nop 0
	v_add_f32_e32 v82, v86, v87
	v_mov_b32_e32 v83, v82
	s_nop 1
	v_permlane32_swap_b32_e32 v82, v83
	s_and_saveexec_b64 s[20:21], s[36:37]
	s_cbranch_execz .LBB0_768
	v_or_b32_e32 v84, 32, v216
	v_ashrrev_i32_e32 v85, 31, v84
	v_add_f32_e32 v86, v82, v83
	v_lshlrev_b64 v[82:83], 7, v[84:85]
	v_lshl_add_u64 v[82:83], s[8:9], 0, v[82:83]
	v_lshl_add_u64 v[82:83], s[18:19], 2, v[82:83]
	s_lshl_b32 s26, s65, 2
	v_lshl_add_u64 v[82:83], v[82:83], 0, s[26:27]
	global_store_dword v[82:83], v86, off
; __device__ __forceinline__ unsigned cvt_pk_bf16(float lo, float hi) { return __builtin_bit_cast(unsigned, __builtin_convertvector((f32x2_t){lo, hi}, bf16x2_t)); }
; __device__ __forceinline__ float bf_lo(unsigned w) { return __uint_as_float(w << 16); }
; __device__ __forceinline__ float bf_hi(unsigned w) { return __uint_as_float(w & 0xffff0000u); }
; __device__ __forceinline__ float sum_xor16(float v) { return v + swz_f<0x401F>(v); }
; __device__ __forceinline__ float sum_xor32(float v) { const auto r = __builtin_amdgcn_permlane32_swap(__float_as_uint(v), __float_as_uint(v), false, false); return __uint_as_float(r[0]) + __uint_as_float(r[1]); }
;     __device__ __forceinline__ void operator()(const f32x4 (&acc)[2][2][4][2], const Unit& u, int wr, int wc, int fr, int fq, PG8_LAS unsigned char*, int) const {
;     ...
;         for (int ai = 0; ai < 2; ++ai)
; #pragma unroll
;             for (int m = 0; m < 4; ++m) { const int row = row0 + ai * HALF + m * 16; float q = 0.f;
; #pragma unroll
;                 for (int bj = 0; bj < 2; ++bj) { const u32x4 o = old[ai][m][bj]; const f32x4 a0 = acc[ai][bj][m][0], a1 = acc[ai][bj][m][1];
;                     const float h0 = bf_lo(o.x) + a0[0], h1 = bf_hi(o.x) + a0[1], h2 = bf_lo(o.y) + a0[2], h3 = bf_hi(o.y) + a0[3], h4 = bf_lo(o.z) + a1[0], h5 = bf_hi(o.z) + a1[1], h6 = bf_lo(o.w) + a1[2], h7 = bf_hi(o.w) + a1[3];
;                     u32x4 w; w.x = cvt_pk_bf16(h0, h1); w.y = cvt_pk_bf16(h2, h3); w.z = cvt_pk_bf16(h4, h5); w.w = cvt_pk_bf16(h6, h7);
;                     *(u32x4*)(base + (size_t)(ai * HALF + m * 16) * 2048 + bj * HALF) = w;
;                     q += (h0 * h0 + h1 * h1) + (h2 * h2 + h3 * h3) + (h4 * h4 + h5 * h5) + (h6 * h6 + h7 * h7); }
;                 q = sum_xor32(sum_xor16(q));
;                 if (fq == 0) SSo[(size_t)row * 32 + u.pn * 4 + wc] = q; }
.LBB0_768:
	s_or_b64 exec, exec, s[20:21]
	s_waitcnt vmcnt(15)
	v_lshlrev_b32_e32 v86, 16, v166
	v_and_b32_e32 v87, 0xffff0000, v166
	v_pk_add_f32 v[78:79], v[78:79], v[86:87]
	v_lshlrev_b32_e32 v86, 16, v167
	v_and_b32_e32 v87, 0xffff0000, v167
	v_pk_add_f32 v[80:81], v[80:81], v[86:87]
	v_lshlrev_b32_e32 v86, 16, v168
	v_and_b32_e32 v87, 0xffff0000, v168
	v_pk_add_f32 v[86:87], v[74:75], v[86:87]
	v_lshlrev_b32_e32 v74, 16, v169
	v_and_b32_e32 v75, 0xffff0000, v169
	v_pk_add_f32 v[88:89], v[76:77], v[74:75]
	v_lshl_add_u64 v[82:83], v[214:215], 0, s[94:95]
	v_cvt_pk_bf16_f32 v74, v78, v79
	v_cvt_pk_bf16_f32 v75, v80, v81
	v_cvt_pk_bf16_f32 v76, v86, v87
	v_cvt_pk_bf16_f32 v77, v88, v89
	global_store_dwordx4 v[82:83], v[74:77], off
	s_waitcnt vmcnt(15)
	v_lshlrev_b32_e32 v82, 16, v162
	v_and_b32_e32 v83, 0xffff0000, v162
	v_pk_add_f32 v[70:71], v[70:71], v[82:83]
	v_lshlrev_b32_e32 v82, 16, v163
	v_and_b32_e32 v83, 0xffff0000, v163
	v_pk_add_f32 v[72:73], v[72:73], v[82:83]
	v_lshlrev_b32_e32 v82, 16, v164
	v_and_b32_e32 v83, 0xffff0000, v164
	v_pk_add_f32 v[82:83], v[66:67], v[82:83]
	v_lshlrev_b32_e32 v66, 16, v165
	v_and_b32_e32 v67, 0xffff0000, v165
	v_pk_mul_f32 v[74:75], v[78:79], v[78:79]
	v_pk_mul_f32 v[78:79], v[86:87], v[86:87]
	v_pk_add_f32 v[86:87], v[68:69], v[66:67]
	v_cvt_pk_bf16_f32 v66, v70, v71
	v_pk_mul_f32 v[68:69], v[70:71], v[70:71]
	v_pk_mul_f32 v[70:71], v[72:73], v[72:73]
	v_pk_mul_f32 v[76:77], v[80:81], v[80:81]
	v_pk_mul_f32 v[80:81], v[88:89], v[88:89]
	v_pk_mul_f32 v[88:89], v[82:83], v[82:83]
	v_add_f32_e32 v70, v70, v71
	v_add_f32_e32 v68, v68, v69
	v_add_f32_e32 v68, v68, v70
	v_add_f32_e32 v69, v88, v89
	v_pk_mul_f32 v[90:91], v[86:87], v[86:87]
	v_add_f32_e32 v68, v69, v68
	v_add_f32_e32 v69, v76, v77
	v_add_f32_e32 v70, v74, v75
	v_add_f32_e32 v67, v90, v91
	v_add_f32_e32 v69, v70, v69
	v_add_f32_e32 v70, v78, v79
	v_add_f32_e32 v67, v67, v68
	v_add_f32_e32 v68, v80, v81
	v_add_f32_e32 v69, v70, v69
	v_add_f32_e32 v68, v68, v69
	v_add_f32_e32 v70, v68, v67
	v_mov_b32_e32 v71, v70
	s_nop 1
	v_permlane16_swap_b32_e32 v71, v70
	s_mov_b64 s[20:21], 0x30100
	v_lshl_add_u64 v[84:85], v[214:215], 0, s[20:21]
	v_cvt_pk_bf16_f32 v67, v72, v73
	v_cvt_pk_bf16_f32 v68, v82, v83
	v_cvt_pk_bf16_f32 v69, v86, v87
	global_store_dwordx4 v[84:85], v[66:69], off
	s_waitcnt lgkmcnt(0)
	s_nop 0
	v_add_f32_e32 v66, v70, v71
	v_mov_b32_e32 v67, v66
	s_nop 1
	v_permlane32_swap_b32_e32 v66, v67
	s_and_saveexec_b64 s[20:21], s[36:37]
	s_cbranch_execz .LBB0_770
	v_or_b32_e32 v68, 48, v216
	v_ashrrev_i32_e32 v69, 31, v68
	v_add_f32_e32 v70, v66, v67
	v_lshlrev_b64 v[66:67], 7, v[68:69]
	v_lshl_add_u64 v[66:67], s[8:9], 0, v[66:67]
	v_lshl_add_u64 v[66:67], s[18:19], 2, v[66:67]
	s_lshl_b32 s26, s65, 2
	v_lshl_add_u64 v[66:67], v[66:67], 0, s[26:27]
	global_store_dword v[66:67], v70, off
.LBB0_770:
	s_or_b64 exec, exec, s[20:21]
	s_waitcnt vmcnt(15)
	v_lshlrev_b32_e32 v70, 16, v158
	v_and_b32_e32 v71, 0xffff0000, v158
	v_pk_add_f32 v[62:63], v[62:63], v[70:71]
	v_lshlrev_b32_e32 v70, 16, v159
	v_and_b32_e32 v71, 0xffff0000, v159
	v_pk_add_f32 v[64:65], v[64:65], v[70:71]
	v_lshlrev_b32_e32 v70, 16, v160
	v_and_b32_e32 v71, 0xffff0000, v160
	v_pk_add_f32 v[70:71], v[58:59], v[70:71]
	v_lshlrev_b32_e32 v58, 16, v161
	v_and_b32_e32 v59, 0xffff0000, v161
	s_mov_b64 s[20:21], 0x80000
	v_pk_add_f32 v[72:73], v[60:61], v[58:59]
	v_lshl_add_u64 v[66:67], v[214:215], 0, s[20:21]
	v_cvt_pk_bf16_f32 v58, v62, v63
	v_cvt_pk_bf16_f32 v59, v64, v65
	v_cvt_pk_bf16_f32 v60, v70, v71
	v_cvt_pk_bf16_f32 v61, v72, v73
	global_store_dwordx4 v[66:67], v[58:61], off
	s_waitcnt vmcnt(15)
	v_lshlrev_b32_e32 v66, 16, v154
	v_and_b32_e32 v67, 0xffff0000, v154
	v_pk_add_f32 v[54:55], v[54:55], v[66:67]
	v_lshlrev_b32_e32 v66, 16, v155
	v_and_b32_e32 v67, 0xffff0000, v155
	v_pk_add_f32 v[56:57], v[56:57], v[66:67]
	v_lshlrev_b32_e32 v66, 16, v156
	v_and_b32_e32 v67, 0xffff0000, v156
	v_pk_add_f32 v[66:67], v[50:51], v[66:67]
	v_lshlrev_b32_e32 v50, 16, v157
	v_and_b32_e32 v51, 0xffff0000, v157
	v_pk_mul_f32 v[58:59], v[62:63], v[62:63]
	v_pk_mul_f32 v[62:63], v[70:71], v[70:71]
	v_pk_add_f32 v[70:71], v[52:53], v[50:51]
	v_cvt_pk_bf16_f32 v50, v54, v55
	v_pk_mul_f32 v[52:53], v[54:55], v[54:55]
	v_pk_mul_f32 v[54:55], v[56:57], v[56:57]
	v_pk_mul_f32 v[60:61], v[64:65], v[64:65]
	v_pk_mul_f32 v[64:65], v[72:73], v[72:73]
	v_pk_mul_f32 v[72:73], v[66:67], v[66:67]
	v_add_f32_e32 v54, v54, v55
	v_add_f32_e32 v52, v52, v53
	v_add_f32_e32 v52, v52, v54
	v_add_f32_e32 v53, v72, v73
	v_pk_mul_f32 v[74:75], v[70:71], v[70:71]
	v_add_f32_e32 v52, v53, v52
	v_add_f32_e32 v53, v60, v61
	v_add_f32_e32 v54, v58, v59
	v_add_f32_e32 v51, v74, v75
	v_add_f32_e32 v53, v54, v53
	v_add_f32_e32 v54, v62, v63
	v_add_f32_e32 v51, v51, v52
	v_add_f32_e32 v52, v64, v65
	v_add_f32_e32 v53, v54, v53
	v_add_f32_e32 v52, v52, v53
	v_add_f32_e32 v54, v52, v51
	v_mov_b32_e32 v55, v54
	s_nop 1
	v_permlane16_swap_b32_e32 v55, v54
	s_mov_b64 s[20:21], 0x80100
	v_lshl_add_u64 v[68:69], v[214:215], 0, s[20:21]
	v_cvt_pk_bf16_f32 v51, v56, v57
	v_cvt_pk_bf16_f32 v52, v66, v67
	v_cvt_pk_bf16_f32 v53, v70, v71
	global_store_dwordx4 v[68:69], v[50:53], off
	s_waitcnt lgkmcnt(0)
	s_nop 0
	v_add_f32_e32 v50, v54, v55
	v_mov_b32_e32 v51, v50
	s_nop 1
	v_permlane32_swap_b32_e32 v50, v51
	s_and_saveexec_b64 s[20:21], s[36:37]
	s_cbranch_execz .LBB0_772
	v_add_f32_e32 v52, v50, v51
	v_lshl_add_u64 v[50:51], s[18:19], 2, v[114:115]
	s_lshl_b32 s26, s65, 2
	v_lshl_add_u64 v[50:51], v[50:51], 0, s[26:27]
	v_add_co_u32_e32 v50, vcc, 0x4000, v50
	s_nop 1
	v_addc_co_u32_e32 v51, vcc, 0, v51, vcc
	global_store_dword v[50:51], v52, off
; __device__ __forceinline__ unsigned cvt_pk_bf16(float lo, float hi) { return __builtin_bit_cast(unsigned, __builtin_convertvector((f32x2_t){lo, hi}, bf16x2_t)); }
; __device__ __forceinline__ float bf_lo(unsigned w) { return __uint_as_float(w << 16); }
; __device__ __forceinline__ float bf_hi(unsigned w) { return __uint_as_float(w & 0xffff0000u); }
; __device__ __forceinline__ float sum_xor16(float v) { return v + swz_f<0x401F>(v); }
; __device__ __forceinline__ float sum_xor32(float v) { const auto r = __builtin_amdgcn_permlane32_swap(__float_as_uint(v), __float_as_uint(v), false, false); return __uint_as_float(r[0]) + __uint_as_float(r[1]); }
;     __device__ __forceinline__ void operator()(const f32x4 (&acc)[2][2][4][2], const Unit& u, int wr, int wc, int fr, int fq, PG8_LAS unsigned char*, int) const {
;     ...
;         for (int ai = 0; ai < 2; ++ai)
; #pragma unroll
;             for (int m = 0; m < 4; ++m) { const int row = row0 + ai * HALF + m * 16; float q = 0.f;
; #pragma unroll
;                 for (int bj = 0; bj < 2; ++bj) { const u32x4 o = old[ai][m][bj]; const f32x4 a0 = acc[ai][bj][m][0], a1 = acc[ai][bj][m][1];
;                     const float h0 = bf_lo(o.x) + a0[0], h1 = bf_hi(o.x) + a0[1], h2 = bf_lo(o.y) + a0[2], h3 = bf_hi(o.y) + a0[3], h4 = bf_lo(o.z) + a1[0], h5 = bf_hi(o.z) + a1[1], h6 = bf_lo(o.w) + a1[2], h7 = bf_hi(o.w) + a1[3];
;                     u32x4 w; w.x = cvt_pk_bf16(h0, h1); w.y = cvt_pk_bf16(h2, h3); w.z = cvt_pk_bf16(h4, h5); w.w = cvt_pk_bf16(h6, h7);
;                     *(u32x4*)(base + (size_t)(ai * HALF + m * 16) * 2048 + bj * HALF) = w;
;                     q += (h0 * h0 + h1 * h1) + (h2 * h2 + h3 * h3) + (h4 * h4 + h5 * h5) + (h6 * h6 + h7 * h7); }
;                 q = sum_xor32(sum_xor16(q));
;                 if (fq == 0) SSo[(size_t)row * 32 + u.pn * 4 + wc] = q; }
.LBB0_772:
	s_or_b64 exec, exec, s[20:21]
	s_waitcnt vmcnt(15)
	v_lshlrev_b32_e32 v54, 16, v150
	v_and_b32_e32 v55, 0xffff0000, v150
	v_pk_add_f32 v[46:47], v[46:47], v[54:55]
	v_lshlrev_b32_e32 v54, 16, v151
	v_and_b32_e32 v55, 0xffff0000, v151
	v_pk_add_f32 v[48:49], v[48:49], v[54:55]
	v_lshlrev_b32_e32 v54, 16, v152
	v_and_b32_e32 v55, 0xffff0000, v152
	v_pk_add_f32 v[54:55], v[42:43], v[54:55]
	v_lshlrev_b32_e32 v42, 16, v153
	v_and_b32_e32 v43, 0xffff0000, v153
	s_mov_b64 s[20:21], 0x90000
	v_pk_add_f32 v[56:57], v[44:45], v[42:43]
	v_lshl_add_u64 v[50:51], v[214:215], 0, s[20:21]
	v_cvt_pk_bf16_f32 v42, v46, v47
	v_cvt_pk_bf16_f32 v43, v48, v49
	v_cvt_pk_bf16_f32 v44, v54, v55
	v_cvt_pk_bf16_f32 v45, v56, v57
	global_store_dwordx4 v[50:51], v[42:45], off
	s_waitcnt vmcnt(15)
	v_lshlrev_b32_e32 v50, 16, v146
	v_and_b32_e32 v51, 0xffff0000, v146
	v_pk_add_f32 v[38:39], v[38:39], v[50:51]
	v_lshlrev_b32_e32 v50, 16, v147
	v_and_b32_e32 v51, 0xffff0000, v147
	v_pk_add_f32 v[40:41], v[40:41], v[50:51]
	v_lshlrev_b32_e32 v50, 16, v148
	v_and_b32_e32 v51, 0xffff0000, v148
	v_pk_add_f32 v[50:51], v[34:35], v[50:51]
	v_lshlrev_b32_e32 v34, 16, v149
	v_and_b32_e32 v35, 0xffff0000, v149
	v_pk_mul_f32 v[42:43], v[46:47], v[46:47]
	v_pk_mul_f32 v[46:47], v[54:55], v[54:55]
	v_pk_add_f32 v[54:55], v[36:37], v[34:35]
	v_cvt_pk_bf16_f32 v34, v38, v39
	v_pk_mul_f32 v[36:37], v[38:39], v[38:39]
	v_pk_mul_f32 v[38:39], v[40:41], v[40:41]
	v_pk_mul_f32 v[44:45], v[48:49], v[48:49]
	v_pk_mul_f32 v[48:49], v[56:57], v[56:57]
	v_pk_mul_f32 v[56:57], v[50:51], v[50:51]
	v_add_f32_e32 v38, v38, v39
	v_add_f32_e32 v36, v36, v37
	v_add_f32_e32 v36, v36, v38
	v_add_f32_e32 v37, v56, v57
	v_pk_mul_f32 v[58:59], v[54:55], v[54:55]
	v_add_f32_e32 v36, v37, v36
	v_add_f32_e32 v37, v44, v45
	v_add_f32_e32 v38, v42, v43
	v_add_f32_e32 v35, v58, v59
	v_add_f32_e32 v37, v38, v37
	v_add_f32_e32 v38, v46, v47
	v_add_f32_e32 v35, v35, v36
	v_add_f32_e32 v36, v48, v49
	v_add_f32_e32 v37, v38, v37
	v_add_f32_e32 v36, v36, v37
	v_add_f32_e32 v38, v36, v35
	v_mov_b32_e32 v39, v38
	s_nop 1
	v_permlane16_swap_b32_e32 v39, v38
	s_mov_b64 s[20:21], 0x90100
	v_lshl_add_u64 v[52:53], v[214:215], 0, s[20:21]
	v_cvt_pk_bf16_f32 v35, v40, v41
	v_cvt_pk_bf16_f32 v36, v50, v51
	v_cvt_pk_bf16_f32 v37, v54, v55
	global_store_dwordx4 v[52:53], v[34:37], off
	s_waitcnt lgkmcnt(0)
	s_nop 0
	v_add_f32_e32 v34, v38, v39
	v_mov_b32_e32 v35, v34
	s_nop 1
	v_permlane32_swap_b32_e32 v34, v35
	s_and_saveexec_b64 s[20:21], s[36:37]
	s_cbranch_execz .LBB0_774
	v_add_f32_e32 v36, v34, v35
	v_lshl_add_u64 v[34:35], s[18:19], 2, v[114:115]
	s_lshl_b32 s26, s65, 2
	v_lshl_add_u64 v[34:35], v[34:35], 0, s[26:27]
	v_add_co_u32_e32 v34, vcc, 0x4000, v34
	s_nop 1
	v_addc_co_u32_e32 v35, vcc, 0, v35, vcc
	global_store_dword v[34:35], v36, off offset:2048
; __device__ __forceinline__ unsigned cvt_pk_bf16(float lo, float hi) { return __builtin_bit_cast(unsigned, __builtin_convertvector((f32x2_t){lo, hi}, bf16x2_t)); }
; __device__ __forceinline__ float bf_lo(unsigned w) { return __uint_as_float(w << 16); }
; __device__ __forceinline__ float bf_hi(unsigned w) { return __uint_as_float(w & 0xffff0000u); }
; __device__ __forceinline__ float sum_xor16(float v) { return v + swz_f<0x401F>(v); }
; __device__ __forceinline__ float sum_xor32(float v) { const auto r = __builtin_amdgcn_permlane32_swap(__float_as_uint(v), __float_as_uint(v), false, false); return __uint_as_float(r[0]) + __uint_as_float(r[1]); }
;     __device__ __forceinline__ void operator()(const f32x4 (&acc)[2][2][4][2], const Unit& u, int wr, int wc, int fr, int fq, PG8_LAS unsigned char*, int) const {
;     ...
;         for (int ai = 0; ai < 2; ++ai)
; #pragma unroll
;             for (int m = 0; m < 4; ++m) { const int row = row0 + ai * HALF + m * 16; float q = 0.f;
; #pragma unroll
;                 for (int bj = 0; bj < 2; ++bj) { const u32x4 o = old[ai][m][bj]; const f32x4 a0 = acc[ai][bj][m][0], a1 = acc[ai][bj][m][1];
;                     const float h0 = bf_lo(o.x) + a0[0], h1 = bf_hi(o.x) + a0[1], h2 = bf_lo(o.y) + a0[2], h3 = bf_hi(o.y) + a0[3], h4 = bf_lo(o.z) + a1[0], h5 = bf_hi(o.z) + a1[1], h6 = bf_lo(o.w) + a1[2], h7 = bf_hi(o.w) + a1[3];
;                     u32x4 w; w.x = cvt_pk_bf16(h0, h1); w.y = cvt_pk_bf16(h2, h3); w.z = cvt_pk_bf16(h4, h5); w.w = cvt_pk_bf16(h6, h7);
;                     *(u32x4*)(base + (size_t)(ai * HALF + m * 16) * 2048 + bj * HALF) = w;
;                     q += (h0 * h0 + h1 * h1) + (h2 * h2 + h3 * h3) + (h4 * h4 + h5 * h5) + (h6 * h6 + h7 * h7); }
;                 q = sum_xor32(sum_xor16(q));
;                 if (fq == 0) SSo[(size_t)row * 32 + u.pn * 4 + wc] = q; }
.LBB0_774:
	s_or_b64 exec, exec, s[20:21]
	s_waitcnt vmcnt(15)
	v_lshlrev_b32_e32 v38, 16, v134
	v_and_b32_e32 v39, 0xffff0000, v134
	v_pk_add_f32 v[30:31], v[30:31], v[38:39]
	v_lshlrev_b32_e32 v38, 16, v135
	v_and_b32_e32 v39, 0xffff0000, v135
	v_pk_add_f32 v[32:33], v[32:33], v[38:39]
	v_lshlrev_b32_e32 v38, 16, v136
	v_and_b32_e32 v39, 0xffff0000, v136
	v_pk_add_f32 v[38:39], v[26:27], v[38:39]
	v_lshlrev_b32_e32 v26, 16, v137
	v_and_b32_e32 v27, 0xffff0000, v137
	s_mov_b64 s[20:21], 0xa0000
	v_pk_add_f32 v[40:41], v[28:29], v[26:27]
	v_lshl_add_u64 v[34:35], v[214:215], 0, s[20:21]
	v_cvt_pk_bf16_f32 v26, v30, v31
	v_cvt_pk_bf16_f32 v27, v32, v33
	v_cvt_pk_bf16_f32 v28, v38, v39
	v_cvt_pk_bf16_f32 v29, v40, v41
	global_store_dwordx4 v[34:35], v[26:29], off
	s_waitcnt vmcnt(15)
	v_lshlrev_b32_e32 v34, 16, v130
	v_and_b32_e32 v35, 0xffff0000, v130
	v_pk_add_f32 v[22:23], v[22:23], v[34:35]
	v_lshlrev_b32_e32 v34, 16, v131
	v_and_b32_e32 v35, 0xffff0000, v131
	v_pk_add_f32 v[24:25], v[24:25], v[34:35]
	v_lshlrev_b32_e32 v34, 16, v132
	v_and_b32_e32 v35, 0xffff0000, v132
	v_pk_add_f32 v[34:35], v[18:19], v[34:35]
	v_lshlrev_b32_e32 v18, 16, v133
	v_and_b32_e32 v19, 0xffff0000, v133
	v_pk_mul_f32 v[26:27], v[30:31], v[30:31]
	v_pk_mul_f32 v[30:31], v[38:39], v[38:39]
	v_pk_add_f32 v[38:39], v[20:21], v[18:19]
	v_cvt_pk_bf16_f32 v18, v22, v23
	v_pk_mul_f32 v[20:21], v[22:23], v[22:23]
	v_pk_mul_f32 v[22:23], v[24:25], v[24:25]
	v_pk_mul_f32 v[28:29], v[32:33], v[32:33]
	v_pk_mul_f32 v[32:33], v[40:41], v[40:41]
	v_pk_mul_f32 v[40:41], v[34:35], v[34:35]
	v_add_f32_e32 v22, v22, v23
	v_add_f32_e32 v20, v20, v21
	v_add_f32_e32 v20, v20, v22
	v_add_f32_e32 v21, v40, v41
	v_pk_mul_f32 v[42:43], v[38:39], v[38:39]
	v_add_f32_e32 v20, v21, v20
	v_add_f32_e32 v21, v28, v29
	v_add_f32_e32 v22, v26, v27
	v_add_f32_e32 v19, v42, v43
	v_add_f32_e32 v21, v22, v21
	v_add_f32_e32 v22, v30, v31
	v_add_f32_e32 v19, v19, v20
	v_add_f32_e32 v20, v32, v33
	v_add_f32_e32 v21, v22, v21
	v_add_f32_e32 v20, v20, v21
	v_add_f32_e32 v22, v20, v19
	v_mov_b32_e32 v23, v22
	s_nop 1
	v_permlane16_swap_b32_e32 v23, v22
	s_mov_b64 s[20:21], 0xa0100
	v_lshl_add_u64 v[36:37], v[214:215], 0, s[20:21]
	v_cvt_pk_bf16_f32 v19, v24, v25
	v_cvt_pk_bf16_f32 v20, v34, v35
	v_cvt_pk_bf16_f32 v21, v38, v39
	global_store_dwordx4 v[36:37], v[18:21], off
	s_waitcnt lgkmcnt(0)
	s_nop 0
	v_add_f32_e32 v18, v22, v23
	v_mov_b32_e32 v19, v18
	s_nop 1
	v_permlane32_swap_b32_e32 v18, v19
	s_and_saveexec_b64 s[20:21], s[36:37]
	s_cbranch_execz .LBB0_776
	v_add_f32_e32 v20, v18, v19
	v_lshl_add_u64 v[18:19], s[18:19], 2, v[114:115]
	s_lshl_b32 s26, s65, 2
	v_lshl_add_u64 v[18:19], v[18:19], 0, s[26:27]
	v_add_co_u32_e32 v18, vcc, 0x5000, v18
	s_nop 1
	v_addc_co_u32_e32 v19, vcc, 0, v19, vcc
	global_store_dword v[18:19], v20, off
.LBB0_776:
	s_or_b64 exec, exec, s[20:21]
	s_waitcnt vmcnt(15)
	v_lshlrev_b32_e32 v22, 16, v122
	v_and_b32_e32 v23, 0xffff0000, v122
	v_pk_add_f32 v[14:15], v[14:15], v[22:23]
	v_lshlrev_b32_e32 v22, 16, v123
	v_and_b32_e32 v23, 0xffff0000, v123
	v_pk_add_f32 v[16:17], v[16:17], v[22:23]
	v_lshlrev_b32_e32 v22, 16, v124
	v_and_b32_e32 v23, 0xffff0000, v124
	v_pk_add_f32 v[22:23], v[10:11], v[22:23]
	v_lshlrev_b32_e32 v10, 16, v125
	v_and_b32_e32 v11, 0xffff0000, v125
	s_mov_b64 s[20:21], 0xb0000
	v_pk_add_f32 v[24:25], v[12:13], v[10:11]
	v_lshl_add_u64 v[18:19], v[214:215], 0, s[20:21]
	v_cvt_pk_bf16_f32 v10, v14, v15
	v_cvt_pk_bf16_f32 v11, v16, v17
	v_cvt_pk_bf16_f32 v12, v22, v23
	v_cvt_pk_bf16_f32 v13, v24, v25
	global_store_dwordx4 v[18:19], v[10:13], off
	s_waitcnt vmcnt(15)
	v_lshlrev_b32_e32 v18, 16, v118
	v_and_b32_e32 v19, 0xffff0000, v118
	v_pk_add_f32 v[6:7], v[6:7], v[18:19]
	v_lshlrev_b32_e32 v18, 16, v119
	v_and_b32_e32 v19, 0xffff0000, v119
	v_pk_add_f32 v[8:9], v[8:9], v[18:19]
	v_lshlrev_b32_e32 v18, 16, v120
	v_and_b32_e32 v19, 0xffff0000, v120
	v_pk_add_f32 v[18:19], v[2:3], v[18:19]
	v_lshlrev_b32_e32 v2, 16, v121
	v_and_b32_e32 v3, 0xffff0000, v121
	v_pk_mul_f32 v[10:11], v[14:15], v[14:15]
	v_pk_mul_f32 v[14:15], v[22:23], v[22:23]
	v_pk_add_f32 v[22:23], v[4:5], v[2:3]
	v_cvt_pk_bf16_f32 v2, v6, v7
	v_pk_mul_f32 v[4:5], v[6:7], v[6:7]
	v_pk_mul_f32 v[6:7], v[8:9], v[8:9]
	v_pk_mul_f32 v[12:13], v[16:17], v[16:17]
	v_pk_mul_f32 v[16:17], v[24:25], v[24:25]
	v_pk_mul_f32 v[24:25], v[18:19], v[18:19]
	v_add_f32_e32 v6, v6, v7
	v_add_f32_e32 v4, v4, v5
	v_add_f32_e32 v4, v4, v6
	v_add_f32_e32 v5, v24, v25
	v_pk_mul_f32 v[26:27], v[22:23], v[22:23]
	v_add_f32_e32 v4, v5, v4
	v_add_f32_e32 v5, v12, v13
	v_add_f32_e32 v6, v10, v11
	v_add_f32_e32 v3, v26, v27
	v_add_f32_e32 v5, v6, v5
	v_add_f32_e32 v6, v14, v15
	v_add_f32_e32 v3, v3, v4
	v_add_f32_e32 v4, v16, v17
	v_add_f32_e32 v5, v6, v5
	v_add_f32_e32 v4, v4, v5
	v_add_f32_e32 v6, v4, v3
	v_mov_b32_e32 v7, v6
	s_nop 1
	v_permlane16_swap_b32_e32 v7, v6
	s_mov_b64 s[20:21], 0xb0100
	v_lshl_add_u64 v[20:21], v[214:215], 0, s[20:21]
	v_cvt_pk_bf16_f32 v3, v8, v9
	v_cvt_pk_bf16_f32 v4, v18, v19
	v_cvt_pk_bf16_f32 v5, v22, v23
	global_store_dwordx4 v[20:21], v[2:5], off
	s_waitcnt lgkmcnt(0)
	s_nop 0
	v_add_f32_e32 v2, v6, v7
	v_mov_b32_e32 v3, v2
	s_nop 1
	v_permlane32_swap_b32_e32 v2, v3
	s_and_saveexec_b64 s[20:21], s[36:37]
	s_cbranch_execz .LBB0_778
	v_add_f32_e32 v4, v2, v3
	v_lshl_add_u64 v[2:3], s[18:19], 2, v[114:115]
	s_lshl_b32 s26, s65, 2
	v_lshl_add_u64 v[2:3], v[2:3], 0, s[26:27]
	v_add_co_u32_e32 v2, vcc, 0x5000, v2
	s_nop 1
	v_addc_co_u32_e32 v3, vcc, 0, v3, vcc
	global_store_dword v[2:3], v4, off offset:2048

; #define PG8_LAS __attribute__((address_space(3)))
; __device__ __forceinline__ float sigmoid_f(float x) { return __builtin_amdgcn_rcpf(1.0f + __builtin_amdgcn_exp2f(-1.4426950408889634f * x)); }
; __device__ __forceinline__ float bf_lo(unsigned w) { return __uint_as_float(w << 16); }
; __device__ __forceinline__ float bf_hi(unsigned w) { return __uint_as_float(w & 0xffff0000u); }
;     __device__ __forceinline__ void operator()(const f32x4 (&acc)[2][2][4][2], const Unit& u, int wr, int wc, int fr, int fq, PG8_LAS unsigned char* lds, int parity) const {
;         float rs[8]; rs_load(rs, lds, parity, wr, fr);
;         const int row0 = u.pm * BM + wr * 64 + fr, col0 = u.pn * BM + wc * 32 + 8 * fq;
;         const size_t off0 = (size_t)row0 * 2048 + col0;
; #pragma unroll
;         for (int ai = 0; ai < 2; ++ai) {
;             u32x4 old[4][2], ppv[4][2];
; #pragma unroll
;             for (int m = 0; m < 4; ++m)
; #pragma unroll
;                 for (int bj = 0; bj < 2; ++bj) { const size_t o = off0 + (size_t)(ai * HALF + m * 16) * 2048 + bj * HALF; old[m][bj] = *(const u32x4*)(HBi + o); ppv[m][bj] = *(const u32x4*)(PP + o); }
; #pragma unroll
;             for (int m = 0; m < 4; ++m) { const int row = row0 + ai * HALF + m * 16; const float s = rs[ai * 4 + m]; float q = 0.f;
; #pragma unroll
;                 for (int bj = 0; bj < 2; ++bj) { const u32x4 o = old[m][bj], pw = ppv[m][bj]; const f32x4 a0 = acc[ai][bj][m][0] * s, a1 = acc[ai][bj][m][1] * s;
;                     const float h0 = bf_lo(o.x) + sigmoid_f(a0[0]) * bf_lo(pw.x), h1 = bf_hi(o.x) + sigmoid_f(a0[1]) * bf_hi(pw.x), h2 = bf_lo(o.y) + sigmoid_f(a0[2]) * bf_lo(pw.y), h3 = bf_hi(o.y) + sigmoid_f(a0[3]) * bf_hi(pw.y);
;                     const float h4 = bf_lo(o.z) + sigmoid_f(a1[0]) * bf_lo(pw.z), h5 = bf_hi(o.z) + sigmoid_f(a1[1]) * bf_hi(pw.z), h6 = bf_lo(o.w) + sigmoid_f(a1[2]) * bf_lo(pw.w), h7 = bf_hi(o.w) + sigmoid_f(a1[3]) * bf_hi(pw.w);
.LBB0_911:
	v_lshl_add_u32 v114, v245, 10, v242
	v_lshl_add_u32 v230, s48, 8, v235
	ds_read_b32 v238, v114
	ds_read_b32 v236, v114 offset:64
	ds_read_b32 v234, v114 offset:128
	ds_read_b32 v232, v114 offset:192
	ds_read_b32 v224, v114 offset:512
	ds_read_b32 v222, v114 offset:576
	ds_read_b32 v220, v114 offset:640
	ds_read_b32 v218, v114 offset:704
	s_waitcnt lgkmcnt(0)
	v_lshl_add_u32 v114, s26, 8, v243
	v_ashrrev_i32_e32 v231, 31, v230
	v_lshlrev_b64 v[116:117], 11, v[230:231]
	v_ashrrev_i32_e32 v115, 31, v114
	v_lshl_add_u64 v[114:115], v[116:117], 0, v[114:115]
	v_lshlrev_b64 v[240:241], 1, v[114:115]
	v_lshl_add_u64 v[228:229], s[8:9], 0, v[240:241]
	global_load_dwordx4 v[190:193], v[228:229], off
	v_lshl_add_u64 v[226:227], s[2:3], 0, v[240:241]
	global_load_dwordx4 v[186:189], v[226:227], off
	global_load_dwordx4 v[182:185], v[228:229], off offset:256
	global_load_dwordx4 v[178:181], v[226:227], off offset:256
	v_add_co_u32_e32 v114, vcc, s23, v228
	s_mov_b32 s19, 0x20000
	s_nop 0
	v_addc_co_u32_e32 v115, vcc, 0, v229, vcc
	v_add_co_u32_e32 v116, vcc, s23, v226
	global_load_dwordx4 v[174:177], v[114:115], off
	s_nop 0
	v_addc_co_u32_e32 v117, vcc, 0, v227, vcc
	global_load_dwordx4 v[170:173], v[116:117], off
	global_load_dwordx4 v[166:169], v[114:115], off offset:256
	global_load_dwordx4 v[162:165], v[116:117], off offset:256
	v_add_co_u32_e32 v114, vcc, s19, v228
	v_pk_mul_f32 v[160:161], v[160:161], v[238:239] op_sel_hi:[1,0]
	s_nop 0
	v_addc_co_u32_e32 v115, vcc, 0, v229, vcc
	v_add_co_u32_e32 v116, vcc, s19, v226
	s_mov_b32 s19, 0x30000
	s_nop 0
	v_addc_co_u32_e32 v117, vcc, 0, v227, vcc
	global_load_dwordx4 v[146:149], v[114:115], off
	global_load_dwordx4 v[150:153], v[116:117], off
	global_load_dwordx4 v[142:145], v[114:115], off offset:256
	global_load_dwordx4 v[138:141], v[116:117], off offset:256
	v_add_co_u32_e32 v114, vcc, s19, v228
	v_pk_mul_f32 v[154:155], v[154:155], v[238:239] op_sel_hi:[1,0]
	s_nop 0
	v_addc_co_u32_e32 v115, vcc, 0, v229, vcc
	v_add_co_u32_e32 v116, vcc, s19, v226
	global_load_dwordx4 v[130:133], v[114:115], off
	s_nop 0
	v_addc_co_u32_e32 v117, vcc, 0, v227, vcc
	global_load_dwordx4 v[134:137], v[116:117], off
	global_load_dwordx4 v[118:121], v[114:115], off offset:256
	s_nop 0
	global_load_dwordx4 v[114:117], v[116:117], off offset:256
	v_mul_f32_e32 v160, 0xbfb8aa3b, v160
	v_mul_f32_e32 v161, 0xbfb8aa3b, v161
	v_exp_f32_e32 v160, v160
	v_exp_f32_e32 v161, v161
	v_mul_f32_e32 v154, 0xbfb8aa3b, v154
	v_mul_f32_e32 v155, 0xbfb8aa3b, v155
	v_exp_f32_e32 v154, v154
	v_exp_f32_e32 v155, v155
	v_add_f32_e32 v160, 1.0, v160
	v_add_f32_e32 v161, 1.0, v161
	v_rcp_f32_e32 v160, v160
	v_rcp_f32_e32 v161, v161
	v_add_f32_e32 v154, 1.0, v154
	v_add_f32_e32 v155, 1.0, v155
	v_rcp_f32_e32 v154, v154
	v_rcp_f32_e32 v155, v155
	v_pk_mul_f32 v[158:159], v[158:159], v[238:239] op_sel_hi:[1,0]
	v_pk_mul_f32 v[156:157], v[156:157], v[238:239] op_sel_hi:[1,0]
	v_mul_f32_e32 v158, 0xbfb8aa3b, v158
	v_mul_f32_e32 v159, 0xbfb8aa3b, v159
	v_exp_f32_e32 v158, v158
	v_exp_f32_e32 v159, v159
	v_pk_mul_f32 v[128:129], v[128:129], v[238:239] op_sel_hi:[1,0]
	v_pk_mul_f32 v[122:123], v[122:123], v[238:239] op_sel_hi:[1,0]
	v_mul_f32_e32 v128, 0xbfb8aa3b, v128
	v_mul_f32_e32 v129, 0xbfb8aa3b, v129
	v_exp_f32_e32 v128, v128
	v_exp_f32_e32 v129, v129
	v_mul_f32_e32 v122, 0xbfb8aa3b, v122
	v_mul_f32_e32 v123, 0xbfb8aa3b, v123
	v_add_f32_e32 v158, 1.0, v158
	v_add_f32_e32 v159, 1.0, v159
	v_exp_f32_e32 v122, v122
	v_exp_f32_e32 v123, v123
	v_rcp_f32_e32 v158, v158
	v_rcp_f32_e32 v159, v159
	v_add_f32_e32 v128, 1.0, v128
	v_add_f32_e32 v129, 1.0, v129
	v_rcp_f32_e32 v128, v128
	v_rcp_f32_e32 v129, v129
	v_add_f32_e32 v122, 1.0, v122
	v_add_f32_e32 v123, 1.0, v123
	v_rcp_f32_e32 v122, v122
	s_waitcnt vmcnt(0)
	v_lshlrev_b32_e32 v246, 16, v190
	v_and_b32_e32 v247, 0xffff0000, v190
	v_lshlrev_b32_e32 v248, 16, v186
	v_and_b32_e32 v249, 0xffff0000, v186
	v_lshlrev_b32_e32 v190, 16, v191
	v_and_b32_e32 v191, 0xffff0000, v191
	v_lshlrev_b32_e32 v186, 16, v187
	v_and_b32_e32 v187, 0xffff0000, v187
	v_pk_fma_f32 v[160:161], v[160:161], v[186:187], v[190:191]
	v_lshlrev_b32_e32 v186, 16, v192
	v_and_b32_e32 v187, 0xffff0000, v192
	v_lshlrev_b32_e32 v190, 16, v188
	v_and_b32_e32 v191, 0xffff0000, v188
	v_pk_fma_f32 v[190:191], v[154:155], v[190:191], v[186:187]
	v_mul_f32_e32 v154, 0xbfb8aa3b, v156
	v_mul_f32_e32 v155, 0xbfb8aa3b, v157
	v_exp_f32_e32 v154, v154
	v_exp_f32_e32 v155, v155
	v_lshlrev_b32_e32 v156, 16, v193
	v_and_b32_e32 v157, 0xffff0000, v193
	v_add_f32_e32 v154, 1.0, v154
	v_add_f32_e32 v155, 1.0, v155
	v_rcp_f32_e32 v154, v154
	v_rcp_f32_e32 v155, v155
	v_lshlrev_b32_e32 v186, 16, v189
	v_and_b32_e32 v187, 0xffff0000, v189
	v_pk_fma_f32 v[158:159], v[158:159], v[248:249], v[246:247]
	v_pk_fma_f32 v[156:157], v[154:155], v[186:187], v[156:157]
	v_rcp_f32_e32 v123, v123
	v_cvt_pk_bf16_f32 v186, v158, v159
	v_cvt_pk_bf16_f32 v187, v160, v161
	v_cvt_pk_bf16_f32 v188, v190, v191
	v_cvt_pk_bf16_f32 v189, v156, v157
	v_lshl_add_u64 v[154:155], s[12:13], 0, v[240:241]
	global_store_dwordx4 v[154:155], v[186:189], off
	v_pk_mul_f32 v[126:127], v[126:127], v[238:239] op_sel_hi:[1,0]
	v_pk_mul_f32 v[124:125], v[124:125], v[238:239] op_sel_hi:[1,0]
	v_pk_mul_f32 v[186:187], v[190:191], v[190:191]
	v_lshlrev_b32_e32 v188, 16, v182
	v_and_b32_e32 v189, 0xffff0000, v182
	v_lshlrev_b32_e32 v190, 16, v178
	v_and_b32_e32 v191, 0xffff0000, v178
	v_lshlrev_b32_e32 v182, 16, v183
	v_and_b32_e32 v183, 0xffff0000, v183
	v_lshlrev_b32_e32 v178, 16, v179
	v_and_b32_e32 v179, 0xffff0000, v179
	v_pk_fma_f32 v[128:129], v[128:129], v[178:179], v[182:183]
; __device__ __forceinline__ unsigned cvt_pk_bf16(float lo, float hi) { return __builtin_bit_cast(unsigned, __builtin_convertvector((f32x2_t){lo, hi}, bf16x2_t)); }
; __device__ __forceinline__ float sigmoid_f(float x) { return __builtin_amdgcn_rcpf(1.0f + __builtin_amdgcn_exp2f(-1.4426950408889634f * x)); }
; __device__ __forceinline__ float bf_lo(unsigned w) { return __uint_as_float(w << 16); }
; __device__ __forceinline__ float bf_hi(unsigned w) { return __uint_as_float(w & 0xffff0000u); }
; __device__ __forceinline__ float sum_xor16(float v) { return v + swz_f<0x401F>(v); }
; __device__ __forceinline__ float sum_xor32(float v) { const auto r = __builtin_amdgcn_permlane32_swap(__float_as_uint(v), __float_as_uint(v), false, false); return __uint_as_float(r[0]) + __uint_as_float(r[1]); }
;     __device__ __forceinline__ void operator()(const f32x4 (&acc)[2][2][4][2], const Unit& u, int wr, int wc, int fr, int fq, PG8_LAS unsigned char* lds, int parity) const {
;     ...
;             for (int m = 0; m < 4; ++m) { const int row = row0 + ai * HALF + m * 16; const float s = rs[ai * 4 + m]; float q = 0.f;
; #pragma unroll
;                 for (int bj = 0; bj < 2; ++bj) { const u32x4 o = old[m][bj], pw = ppv[m][bj]; const f32x4 a0 = acc[ai][bj][m][0] * s, a1 = acc[ai][bj][m][1] * s;
;                     const float h0 = bf_lo(o.x) + sigmoid_f(a0[0]) * bf_lo(pw.x), h1 = bf_hi(o.x) + sigmoid_f(a0[1]) * bf_hi(pw.x), h2 = bf_lo(o.y) + sigmoid_f(a0[2]) * bf_lo(pw.y), h3 = bf_hi(o.y) + sigmoid_f(a0[3]) * bf_hi(pw.y);
;                     const float h4 = bf_lo(o.z) + sigmoid_f(a1[0]) * bf_lo(pw.z), h5 = bf_hi(o.z) + sigmoid_f(a1[1]) * bf_hi(pw.z), h6 = bf_lo(o.w) + sigmoid_f(a1[2]) * bf_lo(pw.w), h7 = bf_hi(o.w) + sigmoid_f(a1[3]) * bf_hi(pw.w);
;                     u32x4 w; w.x = cvt_pk_bf16(h0, h1); w.y = cvt_pk_bf16(h2, h3); w.z = cvt_pk_bf16(h4, h5); w.w = cvt_pk_bf16(h6, h7);
;                     *(u32x4*)(HBo + off0 + (size_t)(ai * HALF + m * 16) * 2048 + bj * HALF) = w;
;                     q += (h0 * h0 + h1 * h1) + (h2 * h2 + h3 * h3) + (h4 * h4 + h5 * h5) + (h6 * h6 + h7 * h7); }
;                 q = sum_xor32(sum_xor16(q));
;                 if (fq == 0) SSo[(size_t)row * 32 + u.pn * 4 + wc] = q; }
	v_lshlrev_b32_e32 v178, 16, v184
	v_and_b32_e32 v179, 0xffff0000, v184
	v_lshlrev_b32_e32 v182, 16, v180
	v_and_b32_e32 v183, 0xffff0000, v180
	v_mul_f32_e32 v126, 0xbfb8aa3b, v126
	v_mul_f32_e32 v127, 0xbfb8aa3b, v127
	v_pk_fma_f32 v[178:179], v[122:123], v[182:183], v[178:179]
	v_mul_f32_e32 v122, 0xbfb8aa3b, v124
	v_mul_f32_e32 v123, 0xbfb8aa3b, v125
	v_exp_f32_e32 v126, v126
	v_exp_f32_e32 v127, v127
	v_exp_f32_e32 v122, v122
	v_exp_f32_e32 v123, v123
	v_add_f32_e32 v126, 1.0, v126
	v_add_f32_e32 v127, 1.0, v127
	v_add_f32_e32 v122, 1.0, v122
	v_add_f32_e32 v123, 1.0, v123
	v_rcp_f32_e32 v126, v126
	v_rcp_f32_e32 v127, v127
	v_rcp_f32_e32 v122, v122
	v_rcp_f32_e32 v123, v123
	v_lshlrev_b32_e32 v124, 16, v185
	v_and_b32_e32 v125, 0xffff0000, v185
	v_lshlrev_b32_e32 v180, 16, v181
	v_and_b32_e32 v181, 0xffff0000, v181
	v_pk_fma_f32 v[126:127], v[126:127], v[190:191], v[188:189]
	v_pk_fma_f32 v[180:181], v[122:123], v[180:181], v[124:125]
	v_cvt_pk_bf16_f32 v122, v126, v127
	v_cvt_pk_bf16_f32 v123, v128, v129
	v_cvt_pk_bf16_f32 v124, v178, v179
	v_cvt_pk_bf16_f32 v125, v180, v181
	global_store_dwordx4 v[154:155], v[122:125], off offset:256
	v_pk_mul_f32 v[158:159], v[158:159], v[158:159]
	v_pk_mul_f32 v[160:161], v[160:161], v[160:161]
	v_pk_mul_f32 v[122:123], v[126:127], v[126:127]
	v_pk_mul_f32 v[124:125], v[128:129], v[128:129]
	v_add_f32_e32 v122, v122, v123
	v_add_f32_e32 v124, v124, v125
	v_pk_mul_f32 v[126:127], v[178:179], v[178:179]
	v_add_f32_e32 v122, v122, v124
	v_add_f32_e32 v124, v160, v161
	v_add_f32_e32 v125, v158, v159
	v_pk_mul_f32 v[156:157], v[156:157], v[156:157]
	v_pk_mul_f32 v[128:129], v[180:181], v[180:181]
	v_add_f32_e32 v123, v126, v127
	v_add_f32_e32 v124, v125, v124
	v_add_f32_e32 v125, v186, v187
	v_add_f32_e32 v128, v128, v129
	v_add_f32_e32 v122, v123, v122
	v_add_f32_e32 v123, v156, v157
	v_add_f32_e32 v124, v125, v124
	v_add_f32_e32 v122, v128, v122
	v_add_f32_e32 v123, v123, v124
	v_add_f32_e32 v122, v123, v122
	v_mov_b32_e32 v123, v122
	s_nop 1
	v_permlane16_swap_b32_e32 v123, v122
	s_lshl_b32 s48, s26, 2
	v_lshlrev_b64 v[124:125], 7, v[230:231]
	s_ashr_i32 s49, s48, 31
	s_mov_b32 s0, 0x20000
	s_waitcnt lgkmcnt(0)
	v_add_f32_e32 v122, v122, v123
	v_mov_b32_e32 v123, v122
	s_mov_b32 s1, 0x30000
	s_nop 0
	v_permlane32_swap_b32_e32 v122, v123
	v_lshl_add_u64 v[156:157], s[14:15], 0, v[124:125]
	s_and_saveexec_b64 s[52:53], s[38:39]
	s_cbranch_execz .LBB0_913
	v_lshl_add_u64 v[124:125], s[48:49], 2, v[156:157]
	s_lshl_b32 s26, s75, 2
	v_lshl_add_u64 v[124:125], v[124:125], 0, s[26:27]
	v_add_f32_e32 v122, v122, v123
	global_store_dword v[124:125], v122, off
.LBB0_913:
	s_or_b64 exec, exec, s[52:53]
	v_pk_mul_f32 v[110:111], v[110:111], v[236:237] op_sel_hi:[1,0]
	v_pk_mul_f32 v[112:113], v[112:113], v[236:237] op_sel_hi:[1,0]
	v_mul_f32_e32 v110, 0xbfb8aa3b, v110
	v_mul_f32_e32 v111, 0xbfb8aa3b, v111
	v_exp_f32_e32 v110, v110
	v_exp_f32_e32 v111, v111
	v_pk_mul_f32 v[106:107], v[106:107], v[236:237] op_sel_hi:[1,0]
	v_mul_f32_e32 v112, 0xbfb8aa3b, v112
	v_mul_f32_e32 v113, 0xbfb8aa3b, v113
	v_exp_f32_e32 v112, v112
	v_exp_f32_e32 v113, v113
	v_mul_f32_e32 v106, 0xbfb8aa3b, v106
	v_mul_f32_e32 v107, 0xbfb8aa3b, v107
	v_exp_f32_e32 v106, v106
	v_exp_f32_e32 v107, v107
	v_add_f32_e32 v110, 1.0, v110
	v_add_f32_e32 v111, 1.0, v111
	v_pk_mul_f32 v[108:109], v[108:109], v[236:237] op_sel_hi:[1,0]
	v_rcp_f32_e32 v110, v110
	v_rcp_f32_e32 v111, v111
	v_add_f32_e32 v112, 1.0, v112
	v_add_f32_e32 v113, 1.0, v113
	v_rcp_f32_e32 v112, v112
	v_rcp_f32_e32 v113, v113
	v_add_f32_e32 v106, 1.0, v106
	v_add_f32_e32 v107, 1.0, v107
	v_mul_f32_e32 v108, 0xbfb8aa3b, v108
	v_mul_f32_e32 v109, 0xbfb8aa3b, v109
	v_rcp_f32_e32 v106, v106
	v_rcp_f32_e32 v107, v107
	v_exp_f32_e32 v108, v108
	v_exp_f32_e32 v109, v109
	v_lshlrev_b32_e32 v122, 16, v174
	v_and_b32_e32 v123, 0xffff0000, v174
	v_lshlrev_b32_e32 v124, 16, v170
	v_and_b32_e32 v125, 0xffff0000, v170
	v_pk_mul_f32 v[102:103], v[102:103], v[236:237] op_sel_hi:[1,0]
	v_pk_fma_f32 v[110:111], v[110:111], v[124:125], v[122:123]
	v_lshlrev_b32_e32 v122, 16, v175
	v_and_b32_e32 v123, 0xffff0000, v175
	v_lshlrev_b32_e32 v124, 16, v171
	v_and_b32_e32 v125, 0xffff0000, v171
	v_pk_mul_f32 v[104:105], v[104:105], v[236:237] op_sel_hi:[1,0]
	v_mul_f32_e32 v102, 0xbfb8aa3b, v102
	v_mul_f32_e32 v103, 0xbfb8aa3b, v103
	v_pk_fma_f32 v[112:113], v[112:113], v[124:125], v[122:123]
	v_lshlrev_b32_e32 v122, 16, v176
	v_and_b32_e32 v123, 0xffff0000, v176
	v_lshlrev_b32_e32 v124, 16, v172
	v_and_b32_e32 v125, 0xffff0000, v172
	v_exp_f32_e32 v102, v102
	v_exp_f32_e32 v103, v103
	v_pk_mul_f32 v[98:99], v[98:99], v[236:237] op_sel_hi:[1,0]
	v_mul_f32_e32 v104, 0xbfb8aa3b, v104
	v_mul_f32_e32 v105, 0xbfb8aa3b, v105
	v_pk_fma_f32 v[122:123], v[106:107], v[124:125], v[122:123]
	v_add_f32_e32 v106, 1.0, v108
	v_add_f32_e32 v107, 1.0, v109
	v_exp_f32_e32 v104, v104
	v_exp_f32_e32 v105, v105
	v_mul_f32_e32 v98, 0xbfb8aa3b, v98
	v_mul_f32_e32 v99, 0xbfb8aa3b, v99
	v_rcp_f32_e32 v106, v106
	v_rcp_f32_e32 v107, v107
	v_exp_f32_e32 v98, v98
	v_exp_f32_e32 v99, v99
	v_pk_mul_f32 v[100:101], v[100:101], v[236:237] op_sel_hi:[1,0]
	v_add_f32_e32 v102, 1.0, v102
	v_add_f32_e32 v103, 1.0, v103
	v_lshlrev_b32_e32 v108, 16, v177
	v_and_b32_e32 v109, 0xffff0000, v177
	v_lshlrev_b32_e32 v124, 16, v173
	v_and_b32_e32 v125, 0xffff0000, v173
	v_rcp_f32_e32 v102, v102
	v_rcp_f32_e32 v103, v103
	v_add_f32_e32 v104, 1.0, v104
	v_add_f32_e32 v105, 1.0, v105
	v_mul_f32_e32 v100, 0xbfb8aa3b, v100
	v_pk_fma_f32 v[124:125], v[106:107], v[124:125], v[108:109]
	v_add_co_u32_e32 v126, vcc, s23, v154
	v_rcp_f32_e32 v104, v104
; __device__ __forceinline__ unsigned cvt_pk_bf16(float lo, float hi) { return __builtin_bit_cast(unsigned, __builtin_convertvector((f32x2_t){lo, hi}, bf16x2_t)); }
; __device__ __forceinline__ float sigmoid_f(float x) { return __builtin_amdgcn_rcpf(1.0f + __builtin_amdgcn_exp2f(-1.4426950408889634f * x)); }
; __device__ __forceinline__ float bf_lo(unsigned w) { return __uint_as_float(w << 16); }
; __device__ __forceinline__ float bf_hi(unsigned w) { return __uint_as_float(w & 0xffff0000u); }
; __device__ __forceinline__ float sum_xor16(float v) { return v + swz_f<0x401F>(v); }
; __device__ __forceinline__ float sum_xor32(float v) { const auto r = __builtin_amdgcn_permlane32_swap(__float_as_uint(v), __float_as_uint(v), false, false); return __uint_as_float(r[0]) + __uint_as_float(r[1]); }
;     __device__ __forceinline__ void operator()(const f32x4 (&acc)[2][2][4][2], const Unit& u, int wr, int wc, int fr, int fq, PG8_LAS unsigned char* lds, int parity) const {
;     ...
;             for (int m = 0; m < 4; ++m) { const int row = row0 + ai * HALF + m * 16; const float s = rs[ai * 4 + m]; float q = 0.f;
; #pragma unroll
;                 for (int bj = 0; bj < 2; ++bj) { const u32x4 o = old[m][bj], pw = ppv[m][bj]; const f32x4 a0 = acc[ai][bj][m][0] * s, a1 = acc[ai][bj][m][1] * s;
;                     const float h0 = bf_lo(o.x) + sigmoid_f(a0[0]) * bf_lo(pw.x), h1 = bf_hi(o.x) + sigmoid_f(a0[1]) * bf_hi(pw.x), h2 = bf_lo(o.y) + sigmoid_f(a0[2]) * bf_lo(pw.y), h3 = bf_hi(o.y) + sigmoid_f(a0[3]) * bf_hi(pw.y);
;                     const float h4 = bf_lo(o.z) + sigmoid_f(a1[0]) * bf_lo(pw.z), h5 = bf_hi(o.z) + sigmoid_f(a1[1]) * bf_hi(pw.z), h6 = bf_lo(o.w) + sigmoid_f(a1[2]) * bf_lo(pw.w), h7 = bf_hi(o.w) + sigmoid_f(a1[3]) * bf_hi(pw.w);
;                     u32x4 w; w.x = cvt_pk_bf16(h0, h1); w.y = cvt_pk_bf16(h2, h3); w.z = cvt_pk_bf16(h4, h5); w.w = cvt_pk_bf16(h6, h7);
;                     *(u32x4*)(HBo + off0 + (size_t)(ai * HALF + m * 16) * 2048 + bj * HALF) = w;
;                     q += (h0 * h0 + h1 * h1) + (h2 * h2 + h3 * h3) + (h4 * h4 + h5 * h5) + (h6 * h6 + h7 * h7); }
;                 q = sum_xor32(sum_xor16(q));
;                 if (fq == 0) SSo[(size_t)row * 32 + u.pn * 4 + wc] = q; }
	v_rcp_f32_e32 v105, v105
	v_add_f32_e32 v98, 1.0, v98
	v_add_f32_e32 v99, 1.0, v99
	v_exp_f32_e32 v128, v100
	v_mul_f32_e32 v100, 0xbfb8aa3b, v101
	v_cvt_pk_bf16_f32 v106, v110, v111
	v_cvt_pk_bf16_f32 v107, v112, v113
	v_cvt_pk_bf16_f32 v108, v122, v123
	v_cvt_pk_bf16_f32 v109, v124, v125
	v_addc_co_u32_e32 v127, vcc, 0, v155, vcc
	v_rcp_f32_e32 v98, v98
	v_rcp_f32_e32 v99, v99
	v_exp_f32_e32 v129, v100
	global_store_dwordx4 v[126:127], v[106:109], off
	s_nop 1
	v_pk_mul_f32 v[106:107], v[110:111], v[110:111]
	v_pk_mul_f32 v[108:109], v[112:113], v[112:113]
	v_pk_mul_f32 v[110:111], v[122:123], v[122:123]
	v_pk_mul_f32 v[112:113], v[124:125], v[124:125]
	v_lshlrev_b32_e32 v122, 16, v166
	v_and_b32_e32 v123, 0xffff0000, v166
	v_lshlrev_b32_e32 v124, 16, v162
	v_and_b32_e32 v125, 0xffff0000, v162
	v_pk_fma_f32 v[102:103], v[102:103], v[124:125], v[122:123]
	v_lshlrev_b32_e32 v122, 16, v167
	v_and_b32_e32 v123, 0xffff0000, v167
	v_lshlrev_b32_e32 v124, 16, v163
	v_and_b32_e32 v125, 0xffff0000, v163
	v_pk_fma_f32 v[104:105], v[104:105], v[124:125], v[122:123]
	v_lshlrev_b32_e32 v122, 16, v168
	v_and_b32_e32 v123, 0xffff0000, v168
	v_lshlrev_b32_e32 v124, 16, v164
	v_and_b32_e32 v125, 0xffff0000, v164
	v_pk_fma_f32 v[100:101], v[98:99], v[124:125], v[122:123]
	v_add_f32_e32 v98, 1.0, v128
	v_add_f32_e32 v99, 1.0, v129
	v_rcp_f32_e32 v98, v98
	v_rcp_f32_e32 v99, v99
	v_lshlrev_b32_e32 v122, 16, v169
	v_and_b32_e32 v123, 0xffff0000, v169
	v_lshlrev_b32_e32 v124, 16, v165
	v_and_b32_e32 v125, 0xffff0000, v165
	v_pk_fma_f32 v[122:123], v[98:99], v[124:125], v[122:123]
	v_cvt_pk_bf16_f32 v98, v102, v103
	v_pk_mul_f32 v[102:103], v[102:103], v[102:103]
	v_pk_mul_f32 v[124:125], v[104:105], v[104:105]
	v_pk_mul_f32 v[128:129], v[100:101], v[100:101]
	v_add_f32_e32 v124, v124, v125
	v_add_f32_e32 v102, v102, v103
	v_add_f32_e32 v102, v102, v124
	v_add_f32_e32 v103, v128, v129
	v_pk_mul_f32 v[158:159], v[122:123], v[122:123]
	v_add_f32_e32 v102, v103, v102
	v_add_f32_e32 v103, v108, v109
	v_add_f32_e32 v106, v106, v107
	v_add_f32_e32 v99, v158, v159
	v_add_f32_e32 v103, v106, v103
	v_add_f32_e32 v106, v110, v111
	v_add_f32_e32 v99, v99, v102
	v_add_f32_e32 v102, v112, v113
	v_add_f32_e32 v103, v106, v103
	v_add_f32_e32 v102, v102, v103
	v_add_f32_e32 v102, v102, v99
	v_mov_b32_e32 v103, v102
	s_nop 1
	v_permlane16_swap_b32_e32 v103, v102
	v_cvt_pk_bf16_f32 v99, v104, v105
	v_cvt_pk_bf16_f32 v100, v100, v101
	v_cvt_pk_bf16_f32 v101, v122, v123
	global_store_dwordx4 v[126:127], v[98:101], off offset:256
	s_waitcnt lgkmcnt(0)
	s_nop 0
	v_add_f32_e32 v98, v102, v103
	v_mov_b32_e32 v99, v98
	s_nop 1
	v_permlane32_swap_b32_e32 v98, v99
	s_and_saveexec_b64 s[52:53], s[38:39]
	s_cbranch_execz .LBB0_915
	v_or_b32_e32 v100, 16, v230
	v_ashrrev_i32_e32 v101, 31, v100
	v_add_f32_e32 v102, v98, v99
	v_lshlrev_b64 v[98:99], 7, v[100:101]
	v_lshl_add_u64 v[98:99], s[14:15], 0, v[98:99]
	v_lshl_add_u64 v[98:99], s[48:49], 2, v[98:99]
	s_lshl_b32 s26, s75, 2
	v_lshl_add_u64 v[98:99], v[98:99], 0, s[26:27]
	global_store_dword v[98:99], v102, off
.LBB0_915:
	s_or_b64 exec, exec, s[52:53]
	v_pk_mul_f32 v[94:95], v[94:95], v[234:235] op_sel_hi:[1,0]
	v_pk_mul_f32 v[96:97], v[96:97], v[234:235] op_sel_hi:[1,0]
	v_mul_f32_e32 v94, 0xbfb8aa3b, v94
	v_mul_f32_e32 v95, 0xbfb8aa3b, v95
	v_exp_f32_e32 v94, v94
	v_exp_f32_e32 v95, v95
	v_pk_mul_f32 v[90:91], v[90:91], v[234:235] op_sel_hi:[1,0]
	v_mul_f32_e32 v96, 0xbfb8aa3b, v96
	v_mul_f32_e32 v97, 0xbfb8aa3b, v97
	v_exp_f32_e32 v96, v96
	v_exp_f32_e32 v97, v97
	v_mul_f32_e32 v90, 0xbfb8aa3b, v90
	v_mul_f32_e32 v91, 0xbfb8aa3b, v91
	v_exp_f32_e32 v90, v90
	v_exp_f32_e32 v91, v91
	v_add_f32_e32 v94, 1.0, v94
	v_add_f32_e32 v95, 1.0, v95
	v_pk_mul_f32 v[92:93], v[92:93], v[234:235] op_sel_hi:[1,0]
	v_rcp_f32_e32 v94, v94
	v_rcp_f32_e32 v95, v95
	v_add_f32_e32 v96, 1.0, v96
	v_add_f32_e32 v97, 1.0, v97
	v_rcp_f32_e32 v96, v96
	v_rcp_f32_e32 v97, v97
	v_add_f32_e32 v90, 1.0, v90
	v_add_f32_e32 v91, 1.0, v91
	v_mul_f32_e32 v92, 0xbfb8aa3b, v92
	v_mul_f32_e32 v93, 0xbfb8aa3b, v93
	v_rcp_f32_e32 v90, v90
	v_rcp_f32_e32 v91, v91
	v_exp_f32_e32 v92, v92
	v_exp_f32_e32 v93, v93
	v_lshlrev_b32_e32 v98, 16, v146
	v_and_b32_e32 v99, 0xffff0000, v146
	v_lshlrev_b32_e32 v100, 16, v150
	v_and_b32_e32 v101, 0xffff0000, v150
	v_pk_mul_f32 v[86:87], v[86:87], v[234:235] op_sel_hi:[1,0]
	v_pk_fma_f32 v[94:95], v[94:95], v[100:101], v[98:99]
	v_lshlrev_b32_e32 v98, 16, v147
	v_and_b32_e32 v99, 0xffff0000, v147
	v_lshlrev_b32_e32 v100, 16, v151
	v_and_b32_e32 v101, 0xffff0000, v151
	v_pk_mul_f32 v[88:89], v[88:89], v[234:235] op_sel_hi:[1,0]
	v_mul_f32_e32 v86, 0xbfb8aa3b, v86
	v_mul_f32_e32 v87, 0xbfb8aa3b, v87
	v_pk_fma_f32 v[96:97], v[96:97], v[100:101], v[98:99]
	v_lshlrev_b32_e32 v98, 16, v148
	v_and_b32_e32 v99, 0xffff0000, v148
	v_lshlrev_b32_e32 v100, 16, v152
	v_and_b32_e32 v101, 0xffff0000, v152
	v_exp_f32_e32 v86, v86
	v_exp_f32_e32 v87, v87
	v_pk_mul_f32 v[82:83], v[82:83], v[234:235] op_sel_hi:[1,0]
	v_mul_f32_e32 v88, 0xbfb8aa3b, v88
	v_mul_f32_e32 v89, 0xbfb8aa3b, v89
	v_pk_fma_f32 v[98:99], v[90:91], v[100:101], v[98:99]
	v_add_f32_e32 v90, 1.0, v92
	v_add_f32_e32 v91, 1.0, v93
	v_exp_f32_e32 v88, v88
	v_exp_f32_e32 v89, v89
	v_mul_f32_e32 v82, 0xbfb8aa3b, v82
	v_mul_f32_e32 v83, 0xbfb8aa3b, v83
	v_rcp_f32_e32 v90, v90
	v_rcp_f32_e32 v91, v91
	v_exp_f32_e32 v82, v82
	v_exp_f32_e32 v83, v83
	v_pk_mul_f32 v[84:85], v[84:85], v[234:235] op_sel_hi:[1,0]
	v_add_f32_e32 v86, 1.0, v86
	v_add_f32_e32 v87, 1.0, v87
	v_lshlrev_b32_e32 v92, 16, v149
	v_and_b32_e32 v93, 0xffff0000, v149
	v_lshlrev_b32_e32 v100, 16, v153
	v_and_b32_e32 v101, 0xffff0000, v153
; __device__ __forceinline__ unsigned cvt_pk_bf16(float lo, float hi) { return __builtin_bit_cast(unsigned, __builtin_convertvector((f32x2_t){lo, hi}, bf16x2_t)); }
; __device__ __forceinline__ float sigmoid_f(float x) { return __builtin_amdgcn_rcpf(1.0f + __builtin_amdgcn_exp2f(-1.4426950408889634f * x)); }
; __device__ __forceinline__ float bf_lo(unsigned w) { return __uint_as_float(w << 16); }
; __device__ __forceinline__ float bf_hi(unsigned w) { return __uint_as_float(w & 0xffff0000u); }
; __device__ __forceinline__ float sum_xor16(float v) { return v + swz_f<0x401F>(v); }
; __device__ __forceinline__ float sum_xor32(float v) { const auto r = __builtin_amdgcn_permlane32_swap(__float_as_uint(v), __float_as_uint(v), false, false); return __uint_as_float(r[0]) + __uint_as_float(r[1]); }
;     __device__ __forceinline__ void operator()(const f32x4 (&acc)[2][2][4][2], const Unit& u, int wr, int wc, int fr, int fq, PG8_LAS unsigned char* lds, int parity) const {
;     ...
;             for (int m = 0; m < 4; ++m) { const int row = row0 + ai * HALF + m * 16; const float s = rs[ai * 4 + m]; float q = 0.f;
; #pragma unroll
;                 for (int bj = 0; bj < 2; ++bj) { const u32x4 o = old[m][bj], pw = ppv[m][bj]; const f32x4 a0 = acc[ai][bj][m][0] * s, a1 = acc[ai][bj][m][1] * s;
;                     const float h0 = bf_lo(o.x) + sigmoid_f(a0[0]) * bf_lo(pw.x), h1 = bf_hi(o.x) + sigmoid_f(a0[1]) * bf_hi(pw.x), h2 = bf_lo(o.y) + sigmoid_f(a0[2]) * bf_lo(pw.y), h3 = bf_hi(o.y) + sigmoid_f(a0[3]) * bf_hi(pw.y);
;                     const float h4 = bf_lo(o.z) + sigmoid_f(a1[0]) * bf_lo(pw.z), h5 = bf_hi(o.z) + sigmoid_f(a1[1]) * bf_hi(pw.z), h6 = bf_lo(o.w) + sigmoid_f(a1[2]) * bf_lo(pw.w), h7 = bf_hi(o.w) + sigmoid_f(a1[3]) * bf_hi(pw.w);
;                     u32x4 w; w.x = cvt_pk_bf16(h0, h1); w.y = cvt_pk_bf16(h2, h3); w.z = cvt_pk_bf16(h4, h5); w.w = cvt_pk_bf16(h6, h7);
;                     *(u32x4*)(HBo + off0 + (size_t)(ai * HALF + m * 16) * 2048 + bj * HALF) = w;
;                     q += (h0 * h0 + h1 * h1) + (h2 * h2 + h3 * h3) + (h4 * h4 + h5 * h5) + (h6 * h6 + h7 * h7); }
;                 q = sum_xor32(sum_xor16(q));
;                 if (fq == 0) SSo[(size_t)row * 32 + u.pn * 4 + wc] = q; }
	v_rcp_f32_e32 v86, v86
	v_rcp_f32_e32 v87, v87
	v_add_f32_e32 v88, 1.0, v88
	v_add_f32_e32 v89, 1.0, v89
	v_mul_f32_e32 v84, 0xbfb8aa3b, v84
	v_pk_fma_f32 v[100:101], v[90:91], v[100:101], v[92:93]
	v_add_co_u32_e32 v102, vcc, s0, v154
	v_rcp_f32_e32 v88, v88
	v_rcp_f32_e32 v89, v89
	v_add_f32_e32 v82, 1.0, v82
	v_add_f32_e32 v83, 1.0, v83
	v_exp_f32_e32 v104, v84
	v_mul_f32_e32 v84, 0xbfb8aa3b, v85
	v_cvt_pk_bf16_f32 v90, v94, v95
	v_cvt_pk_bf16_f32 v91, v96, v97
	v_cvt_pk_bf16_f32 v92, v98, v99
	v_cvt_pk_bf16_f32 v93, v100, v101
	v_addc_co_u32_e32 v103, vcc, 0, v155, vcc
	v_rcp_f32_e32 v82, v82
	v_rcp_f32_e32 v83, v83
	v_exp_f32_e32 v105, v84
	global_store_dwordx4 v[102:103], v[90:93], off
	s_nop 1
	v_pk_mul_f32 v[90:91], v[94:95], v[94:95]
	v_pk_mul_f32 v[92:93], v[96:97], v[96:97]
	v_pk_mul_f32 v[94:95], v[98:99], v[98:99]
	v_pk_mul_f32 v[96:97], v[100:101], v[100:101]
	v_lshlrev_b32_e32 v98, 16, v142
	v_and_b32_e32 v99, 0xffff0000, v142
	v_lshlrev_b32_e32 v100, 16, v138
	v_and_b32_e32 v101, 0xffff0000, v138
	v_pk_fma_f32 v[86:87], v[86:87], v[100:101], v[98:99]
	v_lshlrev_b32_e32 v98, 16, v143
	v_and_b32_e32 v99, 0xffff0000, v143
	v_lshlrev_b32_e32 v100, 16, v139
	v_and_b32_e32 v101, 0xffff0000, v139
	v_pk_fma_f32 v[88:89], v[88:89], v[100:101], v[98:99]
	v_lshlrev_b32_e32 v98, 16, v144
	v_and_b32_e32 v99, 0xffff0000, v144
	v_lshlrev_b32_e32 v100, 16, v140
	v_and_b32_e32 v101, 0xffff0000, v140
	v_pk_fma_f32 v[84:85], v[82:83], v[100:101], v[98:99]
	v_add_f32_e32 v82, 1.0, v104
	v_add_f32_e32 v83, 1.0, v105
	v_rcp_f32_e32 v82, v82
	v_rcp_f32_e32 v83, v83
	v_lshlrev_b32_e32 v98, 16, v145
	v_and_b32_e32 v99, 0xffff0000, v145
	v_lshlrev_b32_e32 v100, 16, v141
	v_and_b32_e32 v101, 0xffff0000, v141
	v_pk_fma_f32 v[98:99], v[82:83], v[100:101], v[98:99]
	v_cvt_pk_bf16_f32 v82, v86, v87
	v_pk_mul_f32 v[86:87], v[86:87], v[86:87]
	v_pk_mul_f32 v[100:101], v[88:89], v[88:89]
	v_pk_mul_f32 v[104:105], v[84:85], v[84:85]
	v_add_f32_e32 v100, v100, v101
	v_add_f32_e32 v86, v86, v87
	v_add_f32_e32 v86, v86, v100
	v_add_f32_e32 v87, v104, v105
	v_pk_mul_f32 v[106:107], v[98:99], v[98:99]
	v_add_f32_e32 v86, v87, v86
	v_add_f32_e32 v87, v92, v93
	v_add_f32_e32 v90, v90, v91
	v_add_f32_e32 v83, v106, v107
	v_add_f32_e32 v87, v90, v87
	v_add_f32_e32 v90, v94, v95
	v_add_f32_e32 v83, v83, v86
	v_add_f32_e32 v86, v96, v97
	v_add_f32_e32 v87, v90, v87
	v_add_f32_e32 v86, v86, v87
	v_add_f32_e32 v86, v86, v83
	v_mov_b32_e32 v87, v86
	s_nop 1
	v_permlane16_swap_b32_e32 v87, v86
	v_cvt_pk_bf16_f32 v83, v88, v89
	v_cvt_pk_bf16_f32 v84, v84, v85
	v_cvt_pk_bf16_f32 v85, v98, v99
	global_store_dwordx4 v[102:103], v[82:85], off offset:256
	s_waitcnt lgkmcnt(0)
	s_nop 0
	v_add_f32_e32 v82, v86, v87
	v_mov_b32_e32 v83, v82
	s_nop 1
	v_permlane32_swap_b32_e32 v82, v83
	s_and_saveexec_b64 s[52:53], s[38:39]
	s_cbranch_execz .LBB0_917
	v_or_b32_e32 v84, 32, v230
	v_ashrrev_i32_e32 v85, 31, v84
	v_add_f32_e32 v86, v82, v83
	v_lshlrev_b64 v[82:83], 7, v[84:85]
	v_lshl_add_u64 v[82:83], s[14:15], 0, v[82:83]
	v_lshl_add_u64 v[82:83], s[48:49], 2, v[82:83]
	s_lshl_b32 s26, s75, 2
	v_lshl_add_u64 v[82:83], v[82:83], 0, s[26:27]
	global_store_dword v[82:83], v86, off
.LBB0_917:
	s_or_b64 exec, exec, s[52:53]
	v_pk_mul_f32 v[78:79], v[78:79], v[232:233] op_sel_hi:[1,0]
	v_pk_mul_f32 v[80:81], v[80:81], v[232:233] op_sel_hi:[1,0]
	v_mul_f32_e32 v78, 0xbfb8aa3b, v78
	v_mul_f32_e32 v79, 0xbfb8aa3b, v79
	v_exp_f32_e32 v78, v78
	v_exp_f32_e32 v79, v79
	v_pk_mul_f32 v[74:75], v[74:75], v[232:233] op_sel_hi:[1,0]
	v_mul_f32_e32 v80, 0xbfb8aa3b, v80
	v_mul_f32_e32 v81, 0xbfb8aa3b, v81
	v_exp_f32_e32 v80, v80
	v_exp_f32_e32 v81, v81
	v_mul_f32_e32 v74, 0xbfb8aa3b, v74
	v_mul_f32_e32 v75, 0xbfb8aa3b, v75
	v_exp_f32_e32 v74, v74
	v_exp_f32_e32 v75, v75
	v_add_f32_e32 v78, 1.0, v78
	v_add_f32_e32 v79, 1.0, v79
	v_pk_mul_f32 v[76:77], v[76:77], v[232:233] op_sel_hi:[1,0]
	v_rcp_f32_e32 v78, v78
	v_rcp_f32_e32 v79, v79
	v_add_f32_e32 v80, 1.0, v80
	v_add_f32_e32 v81, 1.0, v81
	v_rcp_f32_e32 v80, v80
	v_rcp_f32_e32 v81, v81
	v_add_f32_e32 v74, 1.0, v74
	v_add_f32_e32 v75, 1.0, v75
	v_mul_f32_e32 v76, 0xbfb8aa3b, v76
	v_mul_f32_e32 v77, 0xbfb8aa3b, v77
	v_rcp_f32_e32 v74, v74
	v_rcp_f32_e32 v75, v75
	v_exp_f32_e32 v76, v76
	v_exp_f32_e32 v77, v77
	v_lshlrev_b32_e32 v82, 16, v130
	v_and_b32_e32 v83, 0xffff0000, v130
	v_lshlrev_b32_e32 v84, 16, v134
	v_and_b32_e32 v85, 0xffff0000, v134
	v_pk_mul_f32 v[70:71], v[70:71], v[232:233] op_sel_hi:[1,0]
	v_pk_fma_f32 v[78:79], v[78:79], v[84:85], v[82:83]
	v_lshlrev_b32_e32 v82, 16, v131
	v_and_b32_e32 v83, 0xffff0000, v131
	v_lshlrev_b32_e32 v84, 16, v135
	v_and_b32_e32 v85, 0xffff0000, v135
	v_pk_mul_f32 v[72:73], v[72:73], v[232:233] op_sel_hi:[1,0]
	v_mul_f32_e32 v70, 0xbfb8aa3b, v70
	v_mul_f32_e32 v71, 0xbfb8aa3b, v71
	v_pk_fma_f32 v[80:81], v[80:81], v[84:85], v[82:83]
	v_lshlrev_b32_e32 v82, 16, v132
	v_and_b32_e32 v83, 0xffff0000, v132
	v_lshlrev_b32_e32 v84, 16, v136
	v_and_b32_e32 v85, 0xffff0000, v136
	v_exp_f32_e32 v70, v70
	v_exp_f32_e32 v71, v71
	v_pk_mul_f32 v[66:67], v[66:67], v[232:233] op_sel_hi:[1,0]
	v_mul_f32_e32 v72, 0xbfb8aa3b, v72
	v_mul_f32_e32 v73, 0xbfb8aa3b, v73
	v_pk_fma_f32 v[82:83], v[74:75], v[84:85], v[82:83]
	v_add_f32_e32 v74, 1.0, v76
	v_add_f32_e32 v75, 1.0, v77
	v_exp_f32_e32 v72, v72
	v_exp_f32_e32 v73, v73
	v_mul_f32_e32 v66, 0xbfb8aa3b, v66
	v_mul_f32_e32 v67, 0xbfb8aa3b, v67
	v_rcp_f32_e32 v74, v74
	v_rcp_f32_e32 v75, v75
	v_exp_f32_e32 v66, v66
	v_exp_f32_e32 v67, v67
	v_pk_mul_f32 v[68:69], v[68:69], v[232:233] op_sel_hi:[1,0]
	v_add_f32_e32 v70, 1.0, v70
	v_add_f32_e32 v71, 1.0, v71
	v_lshlrev_b32_e32 v76, 16, v133
; __device__ __forceinline__ unsigned cvt_pk_bf16(float lo, float hi) { return __builtin_bit_cast(unsigned, __builtin_convertvector((f32x2_t){lo, hi}, bf16x2_t)); }
; __device__ __forceinline__ float sigmoid_f(float x) { return __builtin_amdgcn_rcpf(1.0f + __builtin_amdgcn_exp2f(-1.4426950408889634f * x)); }
; __device__ __forceinline__ float bf_lo(unsigned w) { return __uint_as_float(w << 16); }
; __device__ __forceinline__ float bf_hi(unsigned w) { return __uint_as_float(w & 0xffff0000u); }
; __device__ __forceinline__ float sum_xor16(float v) { return v + swz_f<0x401F>(v); }
;     __device__ __forceinline__ void operator()(const f32x4 (&acc)[2][2][4][2], const Unit& u, int wr, int wc, int fr, int fq, PG8_LAS unsigned char* lds, int parity) const {
;     ...
;             u32x4 old[4][2], ppv[4][2];
; #pragma unroll
;             for (int m = 0; m < 4; ++m)
; #pragma unroll
;                 for (int bj = 0; bj < 2; ++bj) { const size_t o = off0 + (size_t)(ai * HALF + m * 16) * 2048 + bj * HALF; old[m][bj] = *(const u32x4*)(HBi + o); ppv[m][bj] = *(const u32x4*)(PP + o); }
;     ...
;             for (int m = 0; m < 4; ++m) { const int row = row0 + ai * HALF + m * 16; const float s = rs[ai * 4 + m]; float q = 0.f;
; #pragma unroll
;                 for (int bj = 0; bj < 2; ++bj) { const u32x4 o = old[m][bj], pw = ppv[m][bj]; const f32x4 a0 = acc[ai][bj][m][0] * s, a1 = acc[ai][bj][m][1] * s;
;                     const float h0 = bf_lo(o.x) + sigmoid_f(a0[0]) * bf_lo(pw.x), h1 = bf_hi(o.x) + sigmoid_f(a0[1]) * bf_hi(pw.x), h2 = bf_lo(o.y) + sigmoid_f(a0[2]) * bf_lo(pw.y), h3 = bf_hi(o.y) + sigmoid_f(a0[3]) * bf_hi(pw.y);
;                     const float h4 = bf_lo(o.z) + sigmoid_f(a1[0]) * bf_lo(pw.z), h5 = bf_hi(o.z) + sigmoid_f(a1[1]) * bf_hi(pw.z), h6 = bf_lo(o.w) + sigmoid_f(a1[2]) * bf_lo(pw.w), h7 = bf_hi(o.w) + sigmoid_f(a1[3]) * bf_hi(pw.w);
;                     u32x4 w; w.x = cvt_pk_bf16(h0, h1); w.y = cvt_pk_bf16(h2, h3); w.z = cvt_pk_bf16(h4, h5); w.w = cvt_pk_bf16(h6, h7);
;                     *(u32x4*)(HBo + off0 + (size_t)(ai * HALF + m * 16) * 2048 + bj * HALF) = w;
;                     q += (h0 * h0 + h1 * h1) + (h2 * h2 + h3 * h3) + (h4 * h4 + h5 * h5) + (h6 * h6 + h7 * h7); }
;                 q = sum_xor32(sum_xor16(q));
;                 if (fq == 0) SSo[(size_t)row * 32 + u.pn * 4 + wc] = q; }
	v_and_b32_e32 v77, 0xffff0000, v133
	v_lshlrev_b32_e32 v84, 16, v137
	v_and_b32_e32 v85, 0xffff0000, v137
	v_rcp_f32_e32 v70, v70
	v_rcp_f32_e32 v71, v71
	v_add_f32_e32 v72, 1.0, v72
	v_add_f32_e32 v73, 1.0, v73
	v_mul_f32_e32 v68, 0xbfb8aa3b, v68
	v_pk_fma_f32 v[84:85], v[74:75], v[84:85], v[76:77]
	v_add_co_u32_e32 v86, vcc, s1, v154
	v_rcp_f32_e32 v72, v72
	v_rcp_f32_e32 v73, v73
	v_add_f32_e32 v66, 1.0, v66
	v_add_f32_e32 v67, 1.0, v67
	v_exp_f32_e32 v88, v68
	v_mul_f32_e32 v68, 0xbfb8aa3b, v69
	v_cvt_pk_bf16_f32 v74, v78, v79
	v_cvt_pk_bf16_f32 v75, v80, v81
	v_cvt_pk_bf16_f32 v76, v82, v83
	v_cvt_pk_bf16_f32 v77, v84, v85
	v_addc_co_u32_e32 v87, vcc, 0, v155, vcc
	v_rcp_f32_e32 v66, v66
	v_rcp_f32_e32 v67, v67
	v_exp_f32_e32 v89, v68
	global_store_dwordx4 v[86:87], v[74:77], off
	s_nop 1
	v_pk_mul_f32 v[74:75], v[78:79], v[78:79]
	v_pk_mul_f32 v[76:77], v[80:81], v[80:81]
	v_pk_mul_f32 v[78:79], v[82:83], v[82:83]
	v_pk_mul_f32 v[80:81], v[84:85], v[84:85]
	v_lshlrev_b32_e32 v82, 16, v118
	v_and_b32_e32 v83, 0xffff0000, v118
	v_lshlrev_b32_e32 v84, 16, v114
	v_and_b32_e32 v85, 0xffff0000, v114
	v_pk_fma_f32 v[70:71], v[70:71], v[84:85], v[82:83]
	v_lshlrev_b32_e32 v82, 16, v119
	v_and_b32_e32 v83, 0xffff0000, v119
	v_lshlrev_b32_e32 v84, 16, v115
	v_and_b32_e32 v85, 0xffff0000, v115
	v_pk_fma_f32 v[72:73], v[72:73], v[84:85], v[82:83]
	v_lshlrev_b32_e32 v82, 16, v120
	v_and_b32_e32 v83, 0xffff0000, v120
	v_lshlrev_b32_e32 v84, 16, v116
	v_and_b32_e32 v85, 0xffff0000, v116
	v_pk_fma_f32 v[68:69], v[66:67], v[84:85], v[82:83]
	v_add_f32_e32 v66, 1.0, v88
	v_add_f32_e32 v67, 1.0, v89
	v_rcp_f32_e32 v66, v66
	v_rcp_f32_e32 v67, v67
	v_lshlrev_b32_e32 v82, 16, v121
	v_and_b32_e32 v83, 0xffff0000, v121
	v_lshlrev_b32_e32 v84, 16, v117
	v_and_b32_e32 v85, 0xffff0000, v117
	v_pk_fma_f32 v[82:83], v[66:67], v[84:85], v[82:83]
	v_cvt_pk_bf16_f32 v66, v70, v71
	v_pk_mul_f32 v[70:71], v[70:71], v[70:71]
	v_pk_mul_f32 v[84:85], v[72:73], v[72:73]
	v_pk_mul_f32 v[88:89], v[68:69], v[68:69]
	v_add_f32_e32 v84, v84, v85
	v_add_f32_e32 v70, v70, v71
	v_add_f32_e32 v70, v70, v84
	v_add_f32_e32 v71, v88, v89
	v_pk_mul_f32 v[90:91], v[82:83], v[82:83]
	v_add_f32_e32 v70, v71, v70
	v_add_f32_e32 v71, v76, v77
	v_add_f32_e32 v74, v74, v75
	v_add_f32_e32 v67, v90, v91
	v_add_f32_e32 v71, v74, v71
	v_add_f32_e32 v74, v78, v79
	v_add_f32_e32 v67, v67, v70
	v_add_f32_e32 v70, v80, v81
	v_add_f32_e32 v71, v74, v71
	v_add_f32_e32 v70, v70, v71
	v_add_f32_e32 v70, v70, v67
	v_mov_b32_e32 v71, v70
	s_nop 1
	v_permlane16_swap_b32_e32 v71, v70
	v_cvt_pk_bf16_f32 v67, v72, v73
	v_cvt_pk_bf16_f32 v68, v68, v69
	v_cvt_pk_bf16_f32 v69, v82, v83
	global_store_dwordx4 v[86:87], v[66:69], off offset:256
	s_waitcnt lgkmcnt(0)
	s_nop 0
	v_add_f32_e32 v66, v70, v71
	v_mov_b32_e32 v67, v66
	s_nop 1
	v_permlane32_swap_b32_e32 v66, v67
	s_and_saveexec_b64 s[52:53], s[38:39]
	s_cbranch_execz .LBB0_919
	v_or_b32_e32 v68, 48, v230
	v_ashrrev_i32_e32 v69, 31, v68
	v_add_f32_e32 v70, v66, v67
	v_lshlrev_b64 v[66:67], 7, v[68:69]
	v_lshl_add_u64 v[66:67], s[14:15], 0, v[66:67]
	v_lshl_add_u64 v[66:67], s[48:49], 2, v[66:67]
	s_lshl_b32 s26, s75, 2
	v_lshl_add_u64 v[66:67], v[66:67], 0, s[26:27]
	global_store_dword v[66:67], v70, off
.LBB0_919:
	s_or_b64 exec, exec, s[52:53]
	v_add_co_u32_e32 v66, vcc, 0x80000, v228
	v_pk_mul_f32 v[64:65], v[64:65], v[224:225] op_sel_hi:[1,0]
	s_nop 0
	v_addc_co_u32_e32 v67, vcc, 0, v229, vcc
	global_load_dwordx4 v[122:125], v[66:67], off
	v_add_co_u32_e32 v68, vcc, 0x80000, v226
	v_pk_mul_f32 v[130:131], v[62:63], v[224:225] op_sel_hi:[1,0]
	s_nop 0
	v_addc_co_u32_e32 v69, vcc, 0, v227, vcc
	global_load_dwordx4 v[126:129], v[68:69], off
	global_load_dwordx4 v[118:121], v[66:67], off offset:256
	global_load_dwordx4 v[114:117], v[68:69], off offset:256
	v_add_co_u32_e32 v66, vcc, s50, v228
	v_pk_mul_f32 v[62:63], v[58:59], v[224:225] op_sel_hi:[1,0]
	s_nop 0
	v_addc_co_u32_e32 v67, vcc, 0, v229, vcc
	v_add_co_u32_e32 v68, vcc, s50, v226
	global_load_dwordx4 v[106:109], v[66:67], off
	s_nop 0
	v_addc_co_u32_e32 v69, vcc, 0, v227, vcc
	global_load_dwordx4 v[110:113], v[68:69], off
	global_load_dwordx4 v[102:105], v[66:67], off offset:256
	global_load_dwordx4 v[98:101], v[68:69], off offset:256
	v_add_co_u32_e32 v66, vcc, s51, v228
	v_mul_f32_e32 v64, 0xbfb8aa3b, v64
	s_nop 0
	v_addc_co_u32_e32 v67, vcc, 0, v229, vcc
	v_add_co_u32_e32 v68, vcc, s51, v226
	global_load_dwordx4 v[90:93], v[66:67], off
	s_nop 0
	v_addc_co_u32_e32 v69, vcc, 0, v227, vcc
	global_load_dwordx4 v[94:97], v[68:69], off
	global_load_dwordx4 v[86:89], v[66:67], off offset:256
	global_load_dwordx4 v[82:85], v[68:69], off offset:256
	v_add_co_u32_e32 v66, vcc, s82, v228
	v_mul_f32_e32 v65, 0xbfb8aa3b, v65
	s_nop 0
	v_addc_co_u32_e32 v67, vcc, 0, v229, vcc
	v_add_co_u32_e32 v68, vcc, s82, v226
	global_load_dwordx4 v[74:77], v[66:67], off
	s_nop 0
	v_addc_co_u32_e32 v69, vcc, 0, v227, vcc
	global_load_dwordx4 v[78:81], v[68:69], off
	global_load_dwordx4 v[70:73], v[66:67], off offset:256
	s_nop 0
	global_load_dwordx4 v[66:69], v[68:69], off offset:256
	v_pk_mul_f32 v[60:61], v[60:61], v[224:225] op_sel_hi:[1,0]
	v_exp_f32_e32 v64, v64
	v_exp_f32_e32 v65, v65
	v_mul_f32_e32 v62, 0xbfb8aa3b, v62
	v_mul_f32_e32 v63, 0xbfb8aa3b, v63
	v_mul_f32_e32 v58, 0xbfb8aa3b, v130
	v_mul_f32_e32 v59, 0xbfb8aa3b, v131
	v_exp_f32_e32 v62, v62
	v_exp_f32_e32 v63, v63
	v_mul_f32_e32 v60, 0xbfb8aa3b, v60
	v_mul_f32_e32 v61, 0xbfb8aa3b, v61
	v_exp_f32_e32 v58, v58
	v_exp_f32_e32 v59, v59
	v_exp_f32_e32 v60, v60
	v_exp_f32_e32 v61, v61
	v_pk_mul_f32 v[56:57], v[56:57], v[224:225] op_sel_hi:[1,0]
	v_add_f32_e32 v64, 1.0, v64
	v_add_f32_e32 v65, 1.0, v65
	v_pk_mul_f32 v[50:51], v[50:51], v[224:225] op_sel_hi:[1,0]
	v_mul_f32_e32 v56, 0xbfb8aa3b, v56
	v_mul_f32_e32 v57, 0xbfb8aa3b, v57
	v_rcp_f32_e32 v64, v64
	v_rcp_f32_e32 v65, v65
	v_add_f32_e32 v62, 1.0, v62
	v_add_f32_e32 v63, 1.0, v63
	v_exp_f32_e32 v56, v56
	v_exp_f32_e32 v57, v57
	v_mul_f32_e32 v50, 0xbfb8aa3b, v50
	v_mul_f32_e32 v51, 0xbfb8aa3b, v51
	v_add_f32_e32 v58, 1.0, v58
	v_add_f32_e32 v59, 1.0, v59
	v_rcp_f32_e32 v62, v62
	v_rcp_f32_e32 v63, v63
	v_add_f32_e32 v60, 1.0, v60
	v_add_f32_e32 v61, 1.0, v61
	v_exp_f32_e32 v50, v50
	v_exp_f32_e32 v51, v51
	v_rcp_f32_e32 v58, v58
	v_rcp_f32_e32 v59, v59
	v_rcp_f32_e32 v60, v60
	v_rcp_f32_e32 v61, v61
	s_waitcnt vmcnt(15)
; __device__ __forceinline__ unsigned cvt_pk_bf16(float lo, float hi) { return __builtin_bit_cast(unsigned, __builtin_convertvector((f32x2_t){lo, hi}, bf16x2_t)); }
; __device__ __forceinline__ float sigmoid_f(float x) { return __builtin_amdgcn_rcpf(1.0f + __builtin_amdgcn_exp2f(-1.4426950408889634f * x)); }
; __device__ __forceinline__ float bf_lo(unsigned w) { return __uint_as_float(w << 16); }
; __device__ __forceinline__ float bf_hi(unsigned w) { return __uint_as_float(w & 0xffff0000u); }
; __device__ __forceinline__ float sum_xor16(float v) { return v + swz_f<0x401F>(v); }
; __device__ __forceinline__ float sum_xor32(float v) { const auto r = __builtin_amdgcn_permlane32_swap(__float_as_uint(v), __float_as_uint(v), false, false); return __uint_as_float(r[0]) + __uint_as_float(r[1]); }
;     __device__ __forceinline__ void operator()(const f32x4 (&acc)[2][2][4][2], const Unit& u, int wr, int wc, int fr, int fq, PG8_LAS unsigned char* lds, int parity) const {
;     ...
;             for (int m = 0; m < 4; ++m) { const int row = row0 + ai * HALF + m * 16; const float s = rs[ai * 4 + m]; float q = 0.f;
; #pragma unroll
;                 for (int bj = 0; bj < 2; ++bj) { const u32x4 o = old[m][bj], pw = ppv[m][bj]; const f32x4 a0 = acc[ai][bj][m][0] * s, a1 = acc[ai][bj][m][1] * s;
;                     const float h0 = bf_lo(o.x) + sigmoid_f(a0[0]) * bf_lo(pw.x), h1 = bf_hi(o.x) + sigmoid_f(a0[1]) * bf_hi(pw.x), h2 = bf_lo(o.y) + sigmoid_f(a0[2]) * bf_lo(pw.y), h3 = bf_hi(o.y) + sigmoid_f(a0[3]) * bf_hi(pw.y);
;                     const float h4 = bf_lo(o.z) + sigmoid_f(a1[0]) * bf_lo(pw.z), h5 = bf_hi(o.z) + sigmoid_f(a1[1]) * bf_hi(pw.z), h6 = bf_lo(o.w) + sigmoid_f(a1[2]) * bf_lo(pw.w), h7 = bf_hi(o.w) + sigmoid_f(a1[3]) * bf_hi(pw.w);
;                     u32x4 w; w.x = cvt_pk_bf16(h0, h1); w.y = cvt_pk_bf16(h2, h3); w.z = cvt_pk_bf16(h4, h5); w.w = cvt_pk_bf16(h6, h7);
;                     *(u32x4*)(HBo + off0 + (size_t)(ai * HALF + m * 16) * 2048 + bj * HALF) = w;
;                     q += (h0 * h0 + h1 * h1) + (h2 * h2 + h3 * h3) + (h4 * h4 + h5 * h5) + (h6 * h6 + h7 * h7); }
;                 q = sum_xor32(sum_xor16(q));
;                 if (fq == 0) SSo[(size_t)row * 32 + u.pn * 4 + wc] = q; }
	v_lshlrev_b32_e32 v130, 16, v122
	v_and_b32_e32 v131, 0xffff0000, v122
	v_lshlrev_b32_e32 v122, 16, v123
	s_waitcnt vmcnt(14)
	v_lshlrev_b32_e32 v132, 16, v126
	v_and_b32_e32 v133, 0xffff0000, v126
	v_and_b32_e32 v123, 0xffff0000, v123
	v_lshlrev_b32_e32 v126, 16, v127
	v_and_b32_e32 v127, 0xffff0000, v127
	v_pk_fma_f32 v[64:65], v[64:65], v[126:127], v[122:123]
	v_lshlrev_b32_e32 v122, 16, v124
	v_and_b32_e32 v123, 0xffff0000, v124
	v_lshlrev_b32_e32 v126, 16, v128
	v_and_b32_e32 v127, 0xffff0000, v128
	v_add_f32_e32 v56, 1.0, v56
	v_add_f32_e32 v57, 1.0, v57
	v_pk_fma_f32 v[122:123], v[62:63], v[126:127], v[122:123]
	v_lshlrev_b32_e32 v62, 16, v125
	v_and_b32_e32 v63, 0xffff0000, v125
	v_lshlrev_b32_e32 v124, 16, v129
	v_and_b32_e32 v125, 0xffff0000, v129
	s_mov_b32 s19, 0x80000
	v_rcp_f32_e32 v56, v56
	v_rcp_f32_e32 v57, v57
	v_add_f32_e32 v50, 1.0, v50
	v_add_f32_e32 v51, 1.0, v51
	v_pk_fma_f32 v[58:59], v[58:59], v[132:133], v[130:131]
	v_pk_fma_f32 v[124:125], v[60:61], v[124:125], v[62:63]
	v_add_co_u32_e32 v126, vcc, s19, v154
	v_rcp_f32_e32 v50, v50
	v_rcp_f32_e32 v51, v51
	v_cvt_pk_bf16_f32 v60, v58, v59
	v_cvt_pk_bf16_f32 v61, v64, v65
	v_cvt_pk_bf16_f32 v62, v122, v123
	v_cvt_pk_bf16_f32 v63, v124, v125
	v_addc_co_u32_e32 v127, vcc, 0, v155, vcc
	global_store_dwordx4 v[126:127], v[60:63], off
	v_pk_mul_f32 v[54:55], v[54:55], v[224:225] op_sel_hi:[1,0]
	v_pk_mul_f32 v[52:53], v[52:53], v[224:225] op_sel_hi:[1,0]
	v_pk_mul_f32 v[60:61], v[64:65], v[64:65]
	v_pk_mul_f32 v[62:63], v[122:123], v[122:123]
	v_pk_mul_f32 v[64:65], v[124:125], v[124:125]
	s_waitcnt vmcnt(14)
	v_lshlrev_b32_e32 v122, 16, v118
	v_and_b32_e32 v123, 0xffff0000, v118
	s_waitcnt vmcnt(13)
	v_lshlrev_b32_e32 v124, 16, v114
	v_and_b32_e32 v125, 0xffff0000, v114
	v_lshlrev_b32_e32 v118, 16, v119
	v_and_b32_e32 v119, 0xffff0000, v119
	v_lshlrev_b32_e32 v114, 16, v115
	v_and_b32_e32 v115, 0xffff0000, v115
	v_pk_fma_f32 v[56:57], v[56:57], v[114:115], v[118:119]
	v_lshlrev_b32_e32 v114, 16, v120
	v_and_b32_e32 v115, 0xffff0000, v120
	v_lshlrev_b32_e32 v118, 16, v116
	v_and_b32_e32 v119, 0xffff0000, v116
	v_mul_f32_e32 v54, 0xbfb8aa3b, v54
	v_mul_f32_e32 v55, 0xbfb8aa3b, v55
	v_pk_fma_f32 v[114:115], v[50:51], v[118:119], v[114:115]
	v_mul_f32_e32 v50, 0xbfb8aa3b, v52
	v_mul_f32_e32 v51, 0xbfb8aa3b, v53
	v_exp_f32_e32 v54, v54
	v_exp_f32_e32 v55, v55
	v_exp_f32_e32 v50, v50
	v_exp_f32_e32 v51, v51
	v_add_f32_e32 v54, 1.0, v54
	v_add_f32_e32 v55, 1.0, v55
	v_add_f32_e32 v50, 1.0, v50
	v_add_f32_e32 v51, 1.0, v51
	v_rcp_f32_e32 v54, v54
	v_rcp_f32_e32 v55, v55
	v_rcp_f32_e32 v50, v50
	v_rcp_f32_e32 v51, v51
	v_lshlrev_b32_e32 v52, 16, v121
	v_and_b32_e32 v53, 0xffff0000, v121
	v_lshlrev_b32_e32 v116, 16, v117
	v_and_b32_e32 v117, 0xffff0000, v117
	v_pk_fma_f32 v[54:55], v[54:55], v[124:125], v[122:123]
	v_pk_fma_f32 v[116:117], v[50:51], v[116:117], v[52:53]
	v_cvt_pk_bf16_f32 v50, v54, v55
	v_cvt_pk_bf16_f32 v51, v56, v57
	v_cvt_pk_bf16_f32 v52, v114, v115
	v_cvt_pk_bf16_f32 v53, v116, v117
	global_store_dwordx4 v[126:127], v[50:53], off offset:256
	v_pk_mul_f32 v[58:59], v[58:59], v[58:59]
	s_nop 0
	v_pk_mul_f32 v[50:51], v[54:55], v[54:55]
	v_pk_mul_f32 v[52:53], v[56:57], v[56:57]
	v_add_f32_e32 v50, v50, v51
	v_add_f32_e32 v52, v52, v53
	v_pk_mul_f32 v[54:55], v[114:115], v[114:115]
	v_add_f32_e32 v50, v50, v52
	v_add_f32_e32 v52, v60, v61
	v_add_f32_e32 v53, v58, v59
	v_pk_mul_f32 v[56:57], v[116:117], v[116:117]
	v_add_f32_e32 v51, v54, v55
	v_add_f32_e32 v52, v53, v52
	v_add_f32_e32 v53, v62, v63
	v_add_f32_e32 v56, v56, v57
	v_add_f32_e32 v50, v51, v50
	v_add_f32_e32 v51, v64, v65
	v_add_f32_e32 v52, v53, v52
	v_add_f32_e32 v50, v56, v50
	v_add_f32_e32 v51, v51, v52
	v_add_f32_e32 v50, v51, v50
	v_mov_b32_e32 v51, v50
	s_nop 1
	v_permlane16_swap_b32_e32 v51, v50
	s_waitcnt lgkmcnt(0)
	v_add_f32_e32 v50, v50, v51
	v_mov_b32_e32 v51, v50
	s_nop 1
	v_permlane32_swap_b32_e32 v50, v51
	s_and_saveexec_b64 s[52:53], s[38:39]
	s_cbranch_execz .LBB0_921
	v_add_f32_e32 v52, v50, v51
	v_lshl_add_u64 v[50:51], s[48:49], 2, v[156:157]
	s_lshl_b32 s26, s75, 2
	v_lshl_add_u64 v[50:51], v[50:51], 0, s[26:27]
	v_add_co_u32_e32 v50, vcc, 0x4000, v50
	s_nop 1
	v_addc_co_u32_e32 v51, vcc, 0, v51, vcc
	global_store_dword v[50:51], v52, off
; __device__ __forceinline__ unsigned cvt_pk_bf16(float lo, float hi) { return __builtin_bit_cast(unsigned, __builtin_convertvector((f32x2_t){lo, hi}, bf16x2_t)); }
; __device__ __forceinline__ float sigmoid_f(float x) { return __builtin_amdgcn_rcpf(1.0f + __builtin_amdgcn_exp2f(-1.4426950408889634f * x)); }
; __device__ __forceinline__ float bf_lo(unsigned w) { return __uint_as_float(w << 16); }
; __device__ __forceinline__ float bf_hi(unsigned w) { return __uint_as_float(w & 0xffff0000u); }
; __device__ __forceinline__ float sum_xor16(float v) { return v + swz_f<0x401F>(v); }
; __device__ __forceinline__ float sum_xor32(float v) { const auto r = __builtin_amdgcn_permlane32_swap(__float_as_uint(v), __float_as_uint(v), false, false); return __uint_as_float(r[0]) + __uint_as_float(r[1]); }
;     __device__ __forceinline__ void operator()(const f32x4 (&acc)[2][2][4][2], const Unit& u, int wr, int wc, int fr, int fq, PG8_LAS unsigned char* lds, int parity) const {
;     ...
;             for (int m = 0; m < 4; ++m) { const int row = row0 + ai * HALF + m * 16; const float s = rs[ai * 4 + m]; float q = 0.f;
; #pragma unroll
;                 for (int bj = 0; bj < 2; ++bj) { const u32x4 o = old[m][bj], pw = ppv[m][bj]; const f32x4 a0 = acc[ai][bj][m][0] * s, a1 = acc[ai][bj][m][1] * s;
;                     const float h0 = bf_lo(o.x) + sigmoid_f(a0[0]) * bf_lo(pw.x), h1 = bf_hi(o.x) + sigmoid_f(a0[1]) * bf_hi(pw.x), h2 = bf_lo(o.y) + sigmoid_f(a0[2]) * bf_lo(pw.y), h3 = bf_hi(o.y) + sigmoid_f(a0[3]) * bf_hi(pw.y);
;                     const float h4 = bf_lo(o.z) + sigmoid_f(a1[0]) * bf_lo(pw.z), h5 = bf_hi(o.z) + sigmoid_f(a1[1]) * bf_hi(pw.z), h6 = bf_lo(o.w) + sigmoid_f(a1[2]) * bf_lo(pw.w), h7 = bf_hi(o.w) + sigmoid_f(a1[3]) * bf_hi(pw.w);
;                     u32x4 w; w.x = cvt_pk_bf16(h0, h1); w.y = cvt_pk_bf16(h2, h3); w.z = cvt_pk_bf16(h4, h5); w.w = cvt_pk_bf16(h6, h7);
;                     *(u32x4*)(HBo + off0 + (size_t)(ai * HALF + m * 16) * 2048 + bj * HALF) = w;
;                     q += (h0 * h0 + h1 * h1) + (h2 * h2 + h3 * h3) + (h4 * h4 + h5 * h5) + (h6 * h6 + h7 * h7); }
;                 q = sum_xor32(sum_xor16(q));
;                 if (fq == 0) SSo[(size_t)row * 32 + u.pn * 4 + wc] = q; }
.LBB0_921:
	s_or_b64 exec, exec, s[52:53]
	v_pk_mul_f32 v[46:47], v[46:47], v[222:223] op_sel_hi:[1,0]
	v_pk_mul_f32 v[48:49], v[48:49], v[222:223] op_sel_hi:[1,0]
	v_mul_f32_e32 v46, 0xbfb8aa3b, v46
	v_mul_f32_e32 v47, 0xbfb8aa3b, v47
	v_exp_f32_e32 v46, v46
	v_exp_f32_e32 v47, v47
	v_pk_mul_f32 v[42:43], v[42:43], v[222:223] op_sel_hi:[1,0]
	v_mul_f32_e32 v48, 0xbfb8aa3b, v48
	v_mul_f32_e32 v49, 0xbfb8aa3b, v49
	v_exp_f32_e32 v48, v48
	v_exp_f32_e32 v49, v49
	v_mul_f32_e32 v42, 0xbfb8aa3b, v42
	v_mul_f32_e32 v43, 0xbfb8aa3b, v43
	v_exp_f32_e32 v42, v42
	v_exp_f32_e32 v43, v43
	v_add_f32_e32 v46, 1.0, v46
	v_add_f32_e32 v47, 1.0, v47
	v_pk_mul_f32 v[44:45], v[44:45], v[222:223] op_sel_hi:[1,0]
	v_rcp_f32_e32 v46, v46
	v_rcp_f32_e32 v47, v47
	v_add_f32_e32 v48, 1.0, v48
	v_add_f32_e32 v49, 1.0, v49
	v_rcp_f32_e32 v48, v48
	v_rcp_f32_e32 v49, v49
	v_add_f32_e32 v42, 1.0, v42
	v_add_f32_e32 v43, 1.0, v43
	v_mul_f32_e32 v44, 0xbfb8aa3b, v44
	v_mul_f32_e32 v45, 0xbfb8aa3b, v45
	v_rcp_f32_e32 v42, v42
	v_rcp_f32_e32 v43, v43
	v_exp_f32_e32 v44, v44
	v_exp_f32_e32 v45, v45
	s_waitcnt vmcnt(13)
	v_lshlrev_b32_e32 v50, 16, v106
	v_and_b32_e32 v51, 0xffff0000, v106
	s_waitcnt vmcnt(12)
	v_lshlrev_b32_e32 v52, 16, v110
	v_and_b32_e32 v53, 0xffff0000, v110
	v_pk_mul_f32 v[38:39], v[38:39], v[222:223] op_sel_hi:[1,0]
	v_pk_fma_f32 v[46:47], v[46:47], v[52:53], v[50:51]
	v_lshlrev_b32_e32 v50, 16, v107
	v_and_b32_e32 v51, 0xffff0000, v107
	v_lshlrev_b32_e32 v52, 16, v111
	v_and_b32_e32 v53, 0xffff0000, v111
	v_pk_mul_f32 v[40:41], v[40:41], v[222:223] op_sel_hi:[1,0]
	v_mul_f32_e32 v38, 0xbfb8aa3b, v38
	v_mul_f32_e32 v39, 0xbfb8aa3b, v39
	v_pk_fma_f32 v[48:49], v[48:49], v[52:53], v[50:51]
	v_lshlrev_b32_e32 v50, 16, v108
	v_and_b32_e32 v51, 0xffff0000, v108
	v_lshlrev_b32_e32 v52, 16, v112
	v_and_b32_e32 v53, 0xffff0000, v112
	v_exp_f32_e32 v38, v38
	v_exp_f32_e32 v39, v39
	v_pk_mul_f32 v[34:35], v[34:35], v[222:223] op_sel_hi:[1,0]
	v_mul_f32_e32 v40, 0xbfb8aa3b, v40
	v_mul_f32_e32 v41, 0xbfb8aa3b, v41
	v_pk_fma_f32 v[50:51], v[42:43], v[52:53], v[50:51]
	v_add_f32_e32 v42, 1.0, v44
	v_add_f32_e32 v43, 1.0, v45
	v_exp_f32_e32 v40, v40
	v_exp_f32_e32 v41, v41
	v_mul_f32_e32 v34, 0xbfb8aa3b, v34
	v_mul_f32_e32 v35, 0xbfb8aa3b, v35
	v_rcp_f32_e32 v42, v42
	v_rcp_f32_e32 v43, v43
	v_exp_f32_e32 v34, v34
	v_exp_f32_e32 v35, v35
	v_pk_mul_f32 v[36:37], v[36:37], v[222:223] op_sel_hi:[1,0]
	v_add_f32_e32 v38, 1.0, v38
	v_add_f32_e32 v39, 1.0, v39
	v_lshlrev_b32_e32 v44, 16, v109
	v_and_b32_e32 v45, 0xffff0000, v109
	v_lshlrev_b32_e32 v52, 16, v113
	v_and_b32_e32 v53, 0xffff0000, v113
	v_rcp_f32_e32 v38, v38
	v_rcp_f32_e32 v39, v39
	v_add_f32_e32 v40, 1.0, v40
	v_add_f32_e32 v41, 1.0, v41
	v_mul_f32_e32 v36, 0xbfb8aa3b, v36
	v_pk_fma_f32 v[52:53], v[42:43], v[52:53], v[44:45]
	v_add_co_u32_e32 v54, vcc, s50, v154
	v_rcp_f32_e32 v40, v40
	v_rcp_f32_e32 v41, v41
	v_add_f32_e32 v34, 1.0, v34
	v_add_f32_e32 v35, 1.0, v35
	v_exp_f32_e32 v56, v36
	v_mul_f32_e32 v36, 0xbfb8aa3b, v37
	v_cvt_pk_bf16_f32 v42, v46, v47
	v_cvt_pk_bf16_f32 v43, v48, v49
	v_cvt_pk_bf16_f32 v44, v50, v51
	v_cvt_pk_bf16_f32 v45, v52, v53
	v_addc_co_u32_e32 v55, vcc, 0, v155, vcc
	v_rcp_f32_e32 v34, v34
	v_rcp_f32_e32 v35, v35
	v_exp_f32_e32 v57, v36
	global_store_dwordx4 v[54:55], v[42:45], off
	s_nop 1
	v_pk_mul_f32 v[42:43], v[46:47], v[46:47]
	v_pk_mul_f32 v[44:45], v[48:49], v[48:49]
	v_pk_mul_f32 v[46:47], v[50:51], v[50:51]
	v_pk_mul_f32 v[48:49], v[52:53], v[52:53]
	s_waitcnt vmcnt(12)
	v_lshlrev_b32_e32 v50, 16, v102
	v_and_b32_e32 v51, 0xffff0000, v102
	s_waitcnt vmcnt(11)
	v_lshlrev_b32_e32 v52, 16, v98
	v_and_b32_e32 v53, 0xffff0000, v98
	v_pk_fma_f32 v[38:39], v[38:39], v[52:53], v[50:51]
	v_lshlrev_b32_e32 v50, 16, v103
	v_and_b32_e32 v51, 0xffff0000, v103
	v_lshlrev_b32_e32 v52, 16, v99
	v_and_b32_e32 v53, 0xffff0000, v99
	v_pk_fma_f32 v[40:41], v[40:41], v[52:53], v[50:51]
	v_lshlrev_b32_e32 v50, 16, v104
	v_and_b32_e32 v51, 0xffff0000, v104
	v_lshlrev_b32_e32 v52, 16, v100
	v_and_b32_e32 v53, 0xffff0000, v100
	v_pk_fma_f32 v[36:37], v[34:35], v[52:53], v[50:51]
	v_add_f32_e32 v34, 1.0, v56
	v_add_f32_e32 v35, 1.0, v57
	v_rcp_f32_e32 v34, v34
	v_rcp_f32_e32 v35, v35
	v_lshlrev_b32_e32 v50, 16, v105
	v_and_b32_e32 v51, 0xffff0000, v105
	v_lshlrev_b32_e32 v52, 16, v101
	v_and_b32_e32 v53, 0xffff0000, v101
	v_pk_fma_f32 v[50:51], v[34:35], v[52:53], v[50:51]
	v_cvt_pk_bf16_f32 v34, v38, v39
	v_pk_mul_f32 v[38:39], v[38:39], v[38:39]
	v_pk_mul_f32 v[52:53], v[40:41], v[40:41]
	v_pk_mul_f32 v[56:57], v[36:37], v[36:37]
	v_add_f32_e32 v52, v52, v53
	v_add_f32_e32 v38, v38, v39
	v_add_f32_e32 v38, v38, v52
	v_add_f32_e32 v39, v56, v57
	v_pk_mul_f32 v[58:59], v[50:51], v[50:51]
	v_add_f32_e32 v38, v39, v38
	v_add_f32_e32 v39, v44, v45
	v_add_f32_e32 v42, v42, v43
	v_add_f32_e32 v35, v58, v59
	v_add_f32_e32 v39, v42, v39
	v_add_f32_e32 v42, v46, v47
	v_add_f32_e32 v35, v35, v38
	v_add_f32_e32 v38, v48, v49
	v_add_f32_e32 v39, v42, v39
	v_add_f32_e32 v38, v38, v39
	v_add_f32_e32 v38, v38, v35
	v_mov_b32_e32 v39, v38
	s_nop 1
	v_permlane16_swap_b32_e32 v39, v38
	v_cvt_pk_bf16_f32 v35, v40, v41
	v_cvt_pk_bf16_f32 v36, v36, v37
	v_cvt_pk_bf16_f32 v37, v50, v51
	global_store_dwordx4 v[54:55], v[34:37], off offset:256
	s_waitcnt lgkmcnt(0)
	s_nop 0
	v_add_f32_e32 v34, v38, v39
	v_mov_b32_e32 v35, v34
	s_nop 1
	v_permlane32_swap_b32_e32 v34, v35
	s_and_saveexec_b64 s[52:53], s[38:39]
	s_cbranch_execz .LBB0_923
	v_add_f32_e32 v36, v34, v35
	v_lshl_add_u64 v[34:35], s[48:49], 2, v[156:157]
	s_lshl_b32 s26, s75, 2
	v_lshl_add_u64 v[34:35], v[34:35], 0, s[26:27]
	v_add_co_u32_e32 v34, vcc, 0x4000, v34
	s_nop 1
	v_addc_co_u32_e32 v35, vcc, 0, v35, vcc
	global_store_dword v[34:35], v36, off offset:2048
; __device__ __forceinline__ unsigned cvt_pk_bf16(float lo, float hi) { return __builtin_bit_cast(unsigned, __builtin_convertvector((f32x2_t){lo, hi}, bf16x2_t)); }
; __device__ __forceinline__ float sigmoid_f(float x) { return __builtin_amdgcn_rcpf(1.0f + __builtin_amdgcn_exp2f(-1.4426950408889634f * x)); }
; __device__ __forceinline__ float bf_lo(unsigned w) { return __uint_as_float(w << 16); }
; __device__ __forceinline__ float bf_hi(unsigned w) { return __uint_as_float(w & 0xffff0000u); }
; __device__ __forceinline__ float sum_xor16(float v) { return v + swz_f<0x401F>(v); }
; __device__ __forceinline__ float sum_xor32(float v) { const auto r = __builtin_amdgcn_permlane32_swap(__float_as_uint(v), __float_as_uint(v), false, false); return __uint_as_float(r[0]) + __uint_as_float(r[1]); }
;     __device__ __forceinline__ void operator()(const f32x4 (&acc)[2][2][4][2], const Unit& u, int wr, int wc, int fr, int fq, PG8_LAS unsigned char* lds, int parity) const {
;     ...
;             for (int m = 0; m < 4; ++m) { const int row = row0 + ai * HALF + m * 16; const float s = rs[ai * 4 + m]; float q = 0.f;
; #pragma unroll
;                 for (int bj = 0; bj < 2; ++bj) { const u32x4 o = old[m][bj], pw = ppv[m][bj]; const f32x4 a0 = acc[ai][bj][m][0] * s, a1 = acc[ai][bj][m][1] * s;
;                     const float h0 = bf_lo(o.x) + sigmoid_f(a0[0]) * bf_lo(pw.x), h1 = bf_hi(o.x) + sigmoid_f(a0[1]) * bf_hi(pw.x), h2 = bf_lo(o.y) + sigmoid_f(a0[2]) * bf_lo(pw.y), h3 = bf_hi(o.y) + sigmoid_f(a0[3]) * bf_hi(pw.y);
;                     const float h4 = bf_lo(o.z) + sigmoid_f(a1[0]) * bf_lo(pw.z), h5 = bf_hi(o.z) + sigmoid_f(a1[1]) * bf_hi(pw.z), h6 = bf_lo(o.w) + sigmoid_f(a1[2]) * bf_lo(pw.w), h7 = bf_hi(o.w) + sigmoid_f(a1[3]) * bf_hi(pw.w);
;                     u32x4 w; w.x = cvt_pk_bf16(h0, h1); w.y = cvt_pk_bf16(h2, h3); w.z = cvt_pk_bf16(h4, h5); w.w = cvt_pk_bf16(h6, h7);
;                     *(u32x4*)(HBo + off0 + (size_t)(ai * HALF + m * 16) * 2048 + bj * HALF) = w;
;                     q += (h0 * h0 + h1 * h1) + (h2 * h2 + h3 * h3) + (h4 * h4 + h5 * h5) + (h6 * h6 + h7 * h7); }
;                 q = sum_xor32(sum_xor16(q));
;                 if (fq == 0) SSo[(size_t)row * 32 + u.pn * 4 + wc] = q; }
.LBB0_923:
	s_or_b64 exec, exec, s[52:53]
	v_pk_mul_f32 v[30:31], v[30:31], v[220:221] op_sel_hi:[1,0]
	v_pk_mul_f32 v[32:33], v[32:33], v[220:221] op_sel_hi:[1,0]
	v_mul_f32_e32 v30, 0xbfb8aa3b, v30
	v_mul_f32_e32 v31, 0xbfb8aa3b, v31
	v_exp_f32_e32 v30, v30
	v_exp_f32_e32 v31, v31
	v_pk_mul_f32 v[26:27], v[26:27], v[220:221] op_sel_hi:[1,0]
	v_mul_f32_e32 v32, 0xbfb8aa3b, v32
	v_mul_f32_e32 v33, 0xbfb8aa3b, v33
	v_exp_f32_e32 v32, v32
	v_exp_f32_e32 v33, v33
	v_mul_f32_e32 v26, 0xbfb8aa3b, v26
	v_mul_f32_e32 v27, 0xbfb8aa3b, v27
	v_exp_f32_e32 v26, v26
	v_exp_f32_e32 v27, v27
	v_add_f32_e32 v30, 1.0, v30
	v_add_f32_e32 v31, 1.0, v31
	v_pk_mul_f32 v[28:29], v[28:29], v[220:221] op_sel_hi:[1,0]
	v_rcp_f32_e32 v30, v30
	v_rcp_f32_e32 v31, v31
	v_add_f32_e32 v32, 1.0, v32
	v_add_f32_e32 v33, 1.0, v33
	v_rcp_f32_e32 v32, v32
	v_rcp_f32_e32 v33, v33
	v_add_f32_e32 v26, 1.0, v26
	v_add_f32_e32 v27, 1.0, v27
	v_mul_f32_e32 v28, 0xbfb8aa3b, v28
	v_mul_f32_e32 v29, 0xbfb8aa3b, v29
	v_rcp_f32_e32 v26, v26
	v_rcp_f32_e32 v27, v27
	v_exp_f32_e32 v28, v28
	v_exp_f32_e32 v29, v29
	s_waitcnt vmcnt(11)
	v_lshlrev_b32_e32 v34, 16, v90
	v_and_b32_e32 v35, 0xffff0000, v90
	s_waitcnt vmcnt(10)
	v_lshlrev_b32_e32 v36, 16, v94
	v_and_b32_e32 v37, 0xffff0000, v94
	v_pk_mul_f32 v[22:23], v[22:23], v[220:221] op_sel_hi:[1,0]
	v_pk_fma_f32 v[30:31], v[30:31], v[36:37], v[34:35]
	v_lshlrev_b32_e32 v34, 16, v91
	v_and_b32_e32 v35, 0xffff0000, v91
	v_lshlrev_b32_e32 v36, 16, v95
	v_and_b32_e32 v37, 0xffff0000, v95
	v_pk_mul_f32 v[24:25], v[24:25], v[220:221] op_sel_hi:[1,0]
	v_mul_f32_e32 v22, 0xbfb8aa3b, v22
	v_mul_f32_e32 v23, 0xbfb8aa3b, v23
	v_pk_fma_f32 v[32:33], v[32:33], v[36:37], v[34:35]
	v_lshlrev_b32_e32 v34, 16, v92
	v_and_b32_e32 v35, 0xffff0000, v92
	v_lshlrev_b32_e32 v36, 16, v96
	v_and_b32_e32 v37, 0xffff0000, v96
	v_exp_f32_e32 v22, v22
	v_exp_f32_e32 v23, v23
	v_pk_mul_f32 v[18:19], v[18:19], v[220:221] op_sel_hi:[1,0]
	v_mul_f32_e32 v24, 0xbfb8aa3b, v24
	v_mul_f32_e32 v25, 0xbfb8aa3b, v25
	v_pk_fma_f32 v[34:35], v[26:27], v[36:37], v[34:35]
	v_add_f32_e32 v26, 1.0, v28
	v_add_f32_e32 v27, 1.0, v29
	v_exp_f32_e32 v24, v24
	v_exp_f32_e32 v25, v25
	v_mul_f32_e32 v18, 0xbfb8aa3b, v18
	v_mul_f32_e32 v19, 0xbfb8aa3b, v19
	v_rcp_f32_e32 v26, v26
	v_rcp_f32_e32 v27, v27
	v_exp_f32_e32 v18, v18
	v_exp_f32_e32 v19, v19
	v_pk_mul_f32 v[20:21], v[20:21], v[220:221] op_sel_hi:[1,0]
	v_add_f32_e32 v22, 1.0, v22
	v_add_f32_e32 v23, 1.0, v23
	v_lshlrev_b32_e32 v28, 16, v93
	v_and_b32_e32 v29, 0xffff0000, v93
	v_lshlrev_b32_e32 v36, 16, v97
	v_and_b32_e32 v37, 0xffff0000, v97
	v_rcp_f32_e32 v22, v22
	v_rcp_f32_e32 v23, v23
	v_add_f32_e32 v24, 1.0, v24
	v_add_f32_e32 v25, 1.0, v25
	v_mul_f32_e32 v20, 0xbfb8aa3b, v20
	v_pk_fma_f32 v[36:37], v[26:27], v[36:37], v[28:29]
	v_add_co_u32_e32 v38, vcc, s51, v154
	v_rcp_f32_e32 v24, v24
	v_rcp_f32_e32 v25, v25
	v_add_f32_e32 v18, 1.0, v18
	v_add_f32_e32 v19, 1.0, v19
	v_exp_f32_e32 v40, v20
	v_mul_f32_e32 v20, 0xbfb8aa3b, v21
	v_cvt_pk_bf16_f32 v26, v30, v31
	v_cvt_pk_bf16_f32 v27, v32, v33
	v_cvt_pk_bf16_f32 v28, v34, v35
	v_cvt_pk_bf16_f32 v29, v36, v37
	v_addc_co_u32_e32 v39, vcc, 0, v155, vcc
	v_rcp_f32_e32 v18, v18
	v_rcp_f32_e32 v19, v19
	v_exp_f32_e32 v41, v20
	global_store_dwordx4 v[38:39], v[26:29], off
	s_nop 1
	v_pk_mul_f32 v[26:27], v[30:31], v[30:31]
	v_pk_mul_f32 v[28:29], v[32:33], v[32:33]
	v_pk_mul_f32 v[30:31], v[34:35], v[34:35]
	v_pk_mul_f32 v[32:33], v[36:37], v[36:37]
	s_waitcnt vmcnt(10)
	v_lshlrev_b32_e32 v34, 16, v86
	v_and_b32_e32 v35, 0xffff0000, v86
	s_waitcnt vmcnt(9)
	v_lshlrev_b32_e32 v36, 16, v82
	v_and_b32_e32 v37, 0xffff0000, v82
	v_pk_fma_f32 v[22:23], v[22:23], v[36:37], v[34:35]
	v_lshlrev_b32_e32 v34, 16, v87
	v_and_b32_e32 v35, 0xffff0000, v87
	v_lshlrev_b32_e32 v36, 16, v83
	v_and_b32_e32 v37, 0xffff0000, v83
	v_pk_fma_f32 v[24:25], v[24:25], v[36:37], v[34:35]
	v_lshlrev_b32_e32 v34, 16, v88
	v_and_b32_e32 v35, 0xffff0000, v88
	v_lshlrev_b32_e32 v36, 16, v84
	v_and_b32_e32 v37, 0xffff0000, v84
	v_pk_fma_f32 v[20:21], v[18:19], v[36:37], v[34:35]
	v_add_f32_e32 v18, 1.0, v40
	v_add_f32_e32 v19, 1.0, v41
	v_rcp_f32_e32 v18, v18
	v_rcp_f32_e32 v19, v19
	v_lshlrev_b32_e32 v34, 16, v89
	v_and_b32_e32 v35, 0xffff0000, v89
	v_lshlrev_b32_e32 v36, 16, v85
	v_and_b32_e32 v37, 0xffff0000, v85
	v_pk_fma_f32 v[34:35], v[18:19], v[36:37], v[34:35]
	v_cvt_pk_bf16_f32 v18, v22, v23
	v_pk_mul_f32 v[22:23], v[22:23], v[22:23]
	v_pk_mul_f32 v[36:37], v[24:25], v[24:25]
	v_pk_mul_f32 v[40:41], v[20:21], v[20:21]
	v_add_f32_e32 v36, v36, v37
	v_add_f32_e32 v22, v22, v23
	v_add_f32_e32 v22, v22, v36
	v_add_f32_e32 v23, v40, v41
	v_pk_mul_f32 v[42:43], v[34:35], v[34:35]
	v_add_f32_e32 v22, v23, v22
	v_add_f32_e32 v23, v28, v29
	v_add_f32_e32 v26, v26, v27
	v_add_f32_e32 v19, v42, v43
	v_add_f32_e32 v23, v26, v23
	v_add_f32_e32 v26, v30, v31
	v_add_f32_e32 v19, v19, v22
	v_add_f32_e32 v22, v32, v33
	v_add_f32_e32 v23, v26, v23
	v_add_f32_e32 v22, v22, v23
	v_add_f32_e32 v22, v22, v19
	v_mov_b32_e32 v23, v22
	s_nop 1
	v_permlane16_swap_b32_e32 v23, v22
	v_cvt_pk_bf16_f32 v19, v24, v25
	v_cvt_pk_bf16_f32 v20, v20, v21
	v_cvt_pk_bf16_f32 v21, v34, v35
	global_store_dwordx4 v[38:39], v[18:21], off offset:256
	s_waitcnt lgkmcnt(0)
	s_nop 0
	v_add_f32_e32 v18, v22, v23
	v_mov_b32_e32 v19, v18
	s_nop 1
	v_permlane32_swap_b32_e32 v18, v19
	s_and_saveexec_b64 s[52:53], s[38:39]
	s_cbranch_execz .LBB0_925
	v_add_f32_e32 v20, v18, v19
	v_lshl_add_u64 v[18:19], s[48:49], 2, v[156:157]
	s_lshl_b32 s26, s75, 2
	v_lshl_add_u64 v[18:19], v[18:19], 0, s[26:27]
	v_add_co_u32_e32 v18, vcc, 0x5000, v18
	s_nop 1
	v_addc_co_u32_e32 v19, vcc, 0, v19, vcc
	global_store_dword v[18:19], v20, off
; __device__ __forceinline__ unsigned cvt_pk_bf16(float lo, float hi) { return __builtin_bit_cast(unsigned, __builtin_convertvector((f32x2_t){lo, hi}, bf16x2_t)); }
; __device__ __forceinline__ float sigmoid_f(float x) { return __builtin_amdgcn_rcpf(1.0f + __builtin_amdgcn_exp2f(-1.4426950408889634f * x)); }
; __device__ __forceinline__ float bf_lo(unsigned w) { return __uint_as_float(w << 16); }
; __device__ __forceinline__ float bf_hi(unsigned w) { return __uint_as_float(w & 0xffff0000u); }
; __device__ __forceinline__ float sum_xor16(float v) { return v + swz_f<0x401F>(v); }
; __device__ __forceinline__ float sum_xor32(float v) { const auto r = __builtin_amdgcn_permlane32_swap(__float_as_uint(v), __float_as_uint(v), false, false); return __uint_as_float(r[0]) + __uint_as_float(r[1]); }
;     __device__ __forceinline__ void operator()(const f32x4 (&acc)[2][2][4][2], const Unit& u, int wr, int wc, int fr, int fq, PG8_LAS unsigned char* lds, int parity) const {
;     ...
;             for (int m = 0; m < 4; ++m) { const int row = row0 + ai * HALF + m * 16; const float s = rs[ai * 4 + m]; float q = 0.f;
; #pragma unroll
;                 for (int bj = 0; bj < 2; ++bj) { const u32x4 o = old[m][bj], pw = ppv[m][bj]; const f32x4 a0 = acc[ai][bj][m][0] * s, a1 = acc[ai][bj][m][1] * s;
;                     const float h0 = bf_lo(o.x) + sigmoid_f(a0[0]) * bf_lo(pw.x), h1 = bf_hi(o.x) + sigmoid_f(a0[1]) * bf_hi(pw.x), h2 = bf_lo(o.y) + sigmoid_f(a0[2]) * bf_lo(pw.y), h3 = bf_hi(o.y) + sigmoid_f(a0[3]) * bf_hi(pw.y);
;                     const float h4 = bf_lo(o.z) + sigmoid_f(a1[0]) * bf_lo(pw.z), h5 = bf_hi(o.z) + sigmoid_f(a1[1]) * bf_hi(pw.z), h6 = bf_lo(o.w) + sigmoid_f(a1[2]) * bf_lo(pw.w), h7 = bf_hi(o.w) + sigmoid_f(a1[3]) * bf_hi(pw.w);
;                     u32x4 w; w.x = cvt_pk_bf16(h0, h1); w.y = cvt_pk_bf16(h2, h3); w.z = cvt_pk_bf16(h4, h5); w.w = cvt_pk_bf16(h6, h7);
;                     *(u32x4*)(HBo + off0 + (size_t)(ai * HALF + m * 16) * 2048 + bj * HALF) = w;
;                     q += (h0 * h0 + h1 * h1) + (h2 * h2 + h3 * h3) + (h4 * h4 + h5 * h5) + (h6 * h6 + h7 * h7); }
;                 q = sum_xor32(sum_xor16(q));
;                 if (fq == 0) SSo[(size_t)row * 32 + u.pn * 4 + wc] = q; }
.LBB0_925:
	s_or_b64 exec, exec, s[52:53]
	v_pk_mul_f32 v[14:15], v[14:15], v[218:219] op_sel_hi:[1,0]
	v_pk_mul_f32 v[16:17], v[16:17], v[218:219] op_sel_hi:[1,0]
	v_mul_f32_e32 v14, 0xbfb8aa3b, v14
	v_mul_f32_e32 v15, 0xbfb8aa3b, v15
	v_exp_f32_e32 v14, v14
	v_exp_f32_e32 v15, v15
	v_pk_mul_f32 v[10:11], v[10:11], v[218:219] op_sel_hi:[1,0]
	v_mul_f32_e32 v16, 0xbfb8aa3b, v16
	v_mul_f32_e32 v17, 0xbfb8aa3b, v17
	v_exp_f32_e32 v16, v16
	v_exp_f32_e32 v17, v17
	v_mul_f32_e32 v10, 0xbfb8aa3b, v10
	v_mul_f32_e32 v11, 0xbfb8aa3b, v11
	v_exp_f32_e32 v10, v10
	v_exp_f32_e32 v11, v11
	v_add_f32_e32 v14, 1.0, v14
	v_add_f32_e32 v15, 1.0, v15
	v_pk_mul_f32 v[12:13], v[12:13], v[218:219] op_sel_hi:[1,0]
	v_rcp_f32_e32 v14, v14
	v_rcp_f32_e32 v15, v15
	v_add_f32_e32 v16, 1.0, v16
	v_add_f32_e32 v17, 1.0, v17
	v_rcp_f32_e32 v16, v16
	v_rcp_f32_e32 v17, v17
	v_add_f32_e32 v10, 1.0, v10
	v_add_f32_e32 v11, 1.0, v11
	v_mul_f32_e32 v12, 0xbfb8aa3b, v12
	v_mul_f32_e32 v13, 0xbfb8aa3b, v13
	v_rcp_f32_e32 v10, v10
	v_rcp_f32_e32 v11, v11
	v_exp_f32_e32 v12, v12
	v_exp_f32_e32 v13, v13
	s_waitcnt vmcnt(9)
	v_lshlrev_b32_e32 v18, 16, v74
	v_and_b32_e32 v19, 0xffff0000, v74
	s_waitcnt vmcnt(8)
	v_lshlrev_b32_e32 v20, 16, v78
	v_and_b32_e32 v21, 0xffff0000, v78
	v_pk_mul_f32 v[6:7], v[6:7], v[218:219] op_sel_hi:[1,0]
	v_pk_fma_f32 v[14:15], v[14:15], v[20:21], v[18:19]
	v_lshlrev_b32_e32 v18, 16, v75
	v_and_b32_e32 v19, 0xffff0000, v75
	v_lshlrev_b32_e32 v20, 16, v79
	v_and_b32_e32 v21, 0xffff0000, v79
	v_pk_mul_f32 v[8:9], v[8:9], v[218:219] op_sel_hi:[1,0]
	v_mul_f32_e32 v6, 0xbfb8aa3b, v6
	v_mul_f32_e32 v7, 0xbfb8aa3b, v7
	v_pk_fma_f32 v[16:17], v[16:17], v[20:21], v[18:19]
	v_lshlrev_b32_e32 v18, 16, v76
	v_and_b32_e32 v19, 0xffff0000, v76
	v_lshlrev_b32_e32 v20, 16, v80
	v_and_b32_e32 v21, 0xffff0000, v80
	v_exp_f32_e32 v6, v6
	v_exp_f32_e32 v7, v7
	v_pk_mul_f32 v[2:3], v[2:3], v[218:219] op_sel_hi:[1,0]
	v_mul_f32_e32 v8, 0xbfb8aa3b, v8
	v_mul_f32_e32 v9, 0xbfb8aa3b, v9
	v_pk_fma_f32 v[18:19], v[10:11], v[20:21], v[18:19]
	v_add_f32_e32 v10, 1.0, v12
	v_add_f32_e32 v11, 1.0, v13
	v_exp_f32_e32 v8, v8
	v_exp_f32_e32 v9, v9
	v_mul_f32_e32 v2, 0xbfb8aa3b, v2
	v_mul_f32_e32 v3, 0xbfb8aa3b, v3
	v_rcp_f32_e32 v10, v10
	v_rcp_f32_e32 v11, v11
	v_exp_f32_e32 v2, v2
	v_exp_f32_e32 v3, v3
	v_pk_mul_f32 v[4:5], v[4:5], v[218:219] op_sel_hi:[1,0]
	v_add_f32_e32 v6, 1.0, v6
	v_add_f32_e32 v7, 1.0, v7
	v_lshlrev_b32_e32 v12, 16, v77
	v_and_b32_e32 v13, 0xffff0000, v77
	v_lshlrev_b32_e32 v20, 16, v81
	v_and_b32_e32 v21, 0xffff0000, v81
	v_rcp_f32_e32 v6, v6
	v_rcp_f32_e32 v7, v7
	v_add_f32_e32 v8, 1.0, v8
	v_add_f32_e32 v9, 1.0, v9
	v_mul_f32_e32 v4, 0xbfb8aa3b, v4
	v_pk_fma_f32 v[20:21], v[10:11], v[20:21], v[12:13]
	v_add_co_u32_e32 v22, vcc, s82, v154
	v_rcp_f32_e32 v8, v8
	v_rcp_f32_e32 v9, v9
	v_add_f32_e32 v2, 1.0, v2
	v_add_f32_e32 v3, 1.0, v3
	v_exp_f32_e32 v24, v4
	v_mul_f32_e32 v4, 0xbfb8aa3b, v5
	v_cvt_pk_bf16_f32 v10, v14, v15
	v_cvt_pk_bf16_f32 v11, v16, v17
	v_cvt_pk_bf16_f32 v12, v18, v19
	v_cvt_pk_bf16_f32 v13, v20, v21
	v_addc_co_u32_e32 v23, vcc, 0, v155, vcc
	v_rcp_f32_e32 v2, v2
	v_rcp_f32_e32 v3, v3
	v_exp_f32_e32 v25, v4
	global_store_dwordx4 v[22:23], v[10:13], off
	s_nop 1
	v_pk_mul_f32 v[10:11], v[14:15], v[14:15]
	v_pk_mul_f32 v[12:13], v[16:17], v[16:17]
	v_pk_mul_f32 v[14:15], v[18:19], v[18:19]
	v_pk_mul_f32 v[16:17], v[20:21], v[20:21]
	s_waitcnt vmcnt(8)
	v_lshlrev_b32_e32 v18, 16, v70
	v_and_b32_e32 v19, 0xffff0000, v70
	s_waitcnt vmcnt(7)
	v_lshlrev_b32_e32 v20, 16, v66
	v_and_b32_e32 v21, 0xffff0000, v66
	v_pk_fma_f32 v[6:7], v[6:7], v[20:21], v[18:19]
	v_lshlrev_b32_e32 v18, 16, v71
	v_and_b32_e32 v19, 0xffff0000, v71
	v_lshlrev_b32_e32 v20, 16, v67
	v_and_b32_e32 v21, 0xffff0000, v67
	v_pk_fma_f32 v[8:9], v[8:9], v[20:21], v[18:19]
	v_lshlrev_b32_e32 v18, 16, v72
	v_and_b32_e32 v19, 0xffff0000, v72
	v_lshlrev_b32_e32 v20, 16, v68
	v_and_b32_e32 v21, 0xffff0000, v68
	v_pk_fma_f32 v[4:5], v[2:3], v[20:21], v[18:19]
	v_add_f32_e32 v2, 1.0, v24
	v_add_f32_e32 v3, 1.0, v25
	v_rcp_f32_e32 v2, v2
	v_rcp_f32_e32 v3, v3
	v_lshlrev_b32_e32 v18, 16, v73
	v_and_b32_e32 v19, 0xffff0000, v73
	v_lshlrev_b32_e32 v20, 16, v69
	v_and_b32_e32 v21, 0xffff0000, v69
	v_pk_fma_f32 v[18:19], v[2:3], v[20:21], v[18:19]
	v_cvt_pk_bf16_f32 v2, v6, v7
	v_pk_mul_f32 v[6:7], v[6:7], v[6:7]
	v_pk_mul_f32 v[20:21], v[8:9], v[8:9]
	v_pk_mul_f32 v[24:25], v[4:5], v[4:5]
	v_add_f32_e32 v20, v20, v21
	v_add_f32_e32 v6, v6, v7
	v_add_f32_e32 v6, v6, v20
	v_add_f32_e32 v7, v24, v25
	v_pk_mul_f32 v[26:27], v[18:19], v[18:19]
	v_add_f32_e32 v6, v7, v6
	v_add_f32_e32 v7, v12, v13
	v_add_f32_e32 v10, v10, v11
	v_add_f32_e32 v3, v26, v27
	v_add_f32_e32 v7, v10, v7
	v_add_f32_e32 v10, v14, v15
	v_add_f32_e32 v3, v3, v6
	v_add_f32_e32 v6, v16, v17
	v_add_f32_e32 v7, v10, v7
	v_add_f32_e32 v6, v6, v7
	v_add_f32_e32 v6, v6, v3
	v_mov_b32_e32 v7, v6
	s_nop 1
	v_permlane16_swap_b32_e32 v7, v6
	v_cvt_pk_bf16_f32 v3, v8, v9
	v_cvt_pk_bf16_f32 v4, v4, v5
	v_cvt_pk_bf16_f32 v5, v18, v19
	global_store_dwordx4 v[22:23], v[2:5], off offset:256
	s_waitcnt lgkmcnt(0)
	s_nop 0
	v_add_f32_e32 v2, v6, v7
	v_mov_b32_e32 v3, v2
	s_nop 1
	v_permlane32_swap_b32_e32 v2, v3
	s_and_saveexec_b64 s[52:53], s[38:39]
	s_cbranch_execz .LBB0_927
	v_add_f32_e32 v4, v2, v3
	v_lshl_add_u64 v[2:3], s[48:49], 2, v[156:157]
	s_lshl_b32 s26, s75, 2
	v_lshl_add_u64 v[2:3], v[2:3], 0, s[26:27]
	v_add_co_u32_e32 v2, vcc, 0x5000, v2
	s_nop 1
	v_addc_co_u32_e32 v3, vcc, 0, v3, vcc
	global_store_dword v[2:3], v4, off offset:2048
